# P11 final output stores non-temporal (out is write-only now; keeps L2/MALL for the x / y0 / y1 reads)
# speedup vs baseline: 1.0032x; 1.0032x over previous
; __global__ void __launch_bounds__(NWAVES * 64, 2) mk_fwd(Args args) {
;     ...
;         const int per = (ML + F.NGW - 1) / F.NGW, per2 = (per + 1) & ~1, rbeg = F.gw * per2;
;         int rcur = -1; f32x4 PA[8];
;         for (int row0 = rbeg; row0 < rbeg + per2 && row0 < ML; row0 += 2) {
;             f32x4 v[2][8]; u32x2 yw[2][8];
; #pragma unroll
;             for (int q = 0; q < 2; ++q) { const int row = row0 + q; load_row_f32(args.out + (size_t)row * DM, F.lane, v[q]);
;                 const bf16_t* yr = Y + (size_t)row * DM;
; #pragma unroll
;                 for (int j = 0; j < 8; ++j) yw[q][j] = *(const u32x2*)(yr + 4 * F.lane + 256 * j); }
; #pragma unroll
;             for (int q = 0; q < 2; ++q) { const int row = row0 + q; const int r = row / SEQ;
;                 if (r != rcur) { const float* m1 = mod + (size_t)(9 + r) * 6144; rcur = r;
; #pragma unroll
;                     for (int j = 0; j < 8; ++j) { const int col = 4 * F.lane + 256 * j; PA[j] = *(const f32x4*)(m1 + 2 * DM + col) * *(const f32x4*)(post_norm + DM + col); } }
.LBB0_1288:
	s_cmp_gt_i32 s86, 11
	s_cselect_b64 s[2:3], -1, 0
	s_xor_b64 s[0:1], s[0:1], -1
	s_or_b64 s[0:1], s[2:3], s[0:1]
	s_and_b64 vcc, exec, s[0:1]
	s_cbranch_vccnz .LBB0_1296
	s_cmpk_lg_i32 s63, 0x100
	s_cbranch_scc1 .Lp11_generic
	v_and_b32_e32 v194, 63, v198
	v_lshlrev_b32_e32 v192, 4, v194
	v_add_u32_e32 v193, 0x1000, v192
	v_lshlrev_b32_e32 v194, 3, v194
	v_mov_b32_e32 v195, 0x358637bd
	s_lshr_b32 s0, s33, 8
	s_mul_i32 s1, s0, 0x6000
	s_add_u32 s8, s84, s1
	s_addc_u32 s9, s85, 0
	s_add_u32 s8, s8, 0x4000
	s_addc_u32 s9, s9, 0
	s_add_u32 s10, s8, 0x36000
	s_addc_u32 s11, s9, 0
	s_add_u32 s12, s82, 0x2000
	s_addc_u32 s13, s83, 0
	s_lshl_b32 s0, s33, 16
	s_add_u32 s14, s68, s0
	s_addc_u32 s15, s69, 0
	s_add_u32 s18, s94, s0
	s_addc_u32 s19, s95, 0
	s_lshl_b32 s0, s33, 15
	s_add_u32 s16, s84, s0
	s_addc_u32 s17, s85, 0
	s_add_u32 s22, s16, 0x8800000
	s_addc_u32 s23, s17, 0
	s_add_u32 s16, s16, 0x11800000
	s_addc_u32 s17, s17, 0
	global_load_dwordx4 v[128:131], v192, s[8:9] offset:0
	global_load_dwordx4 v[132:135], v192, s[8:9] offset:1024
	global_load_dwordx4 v[136:139], v192, s[8:9] offset:2048
	global_load_dwordx4 v[140:143], v192, s[8:9] offset:3072
	global_load_dwordx4 v[144:147], v193, s[8:9] offset:0
	global_load_dwordx4 v[148:151], v193, s[8:9] offset:1024
	global_load_dwordx4 v[152:155], v193, s[8:9] offset:2048
	global_load_dwordx4 v[156:159], v193, s[8:9] offset:3072
	global_load_dwordx4 v[32:35], v192, s[82:83] offset:0
	global_load_dwordx4 v[36:39], v192, s[82:83] offset:1024
	global_load_dwordx4 v[40:43], v192, s[82:83] offset:2048
	global_load_dwordx4 v[44:47], v192, s[82:83] offset:3072
	global_load_dwordx4 v[48:51], v193, s[82:83] offset:0
	global_load_dwordx4 v[52:55], v193, s[82:83] offset:1024
	global_load_dwordx4 v[56:59], v193, s[82:83] offset:2048
	global_load_dwordx4 v[60:63], v193, s[82:83] offset:3072
	global_load_dwordx4 v[160:163], v192, s[10:11] offset:0
	global_load_dwordx4 v[164:167], v192, s[10:11] offset:1024
	global_load_dwordx4 v[168:171], v192, s[10:11] offset:2048
	global_load_dwordx4 v[172:175], v192, s[10:11] offset:3072
	global_load_dwordx4 v[176:179], v193, s[10:11] offset:0
	global_load_dwordx4 v[180:183], v193, s[10:11] offset:1024
	global_load_dwordx4 v[184:187], v193, s[10:11] offset:2048
	global_load_dwordx4 v[188:191], v193, s[10:11] offset:3072
	global_load_dwordx4 v[96:99], v192, s[12:13] offset:0
	global_load_dwordx4 v[100:103], v192, s[12:13] offset:1024
	global_load_dwordx4 v[104:107], v192, s[12:13] offset:2048
	global_load_dwordx4 v[108:111], v192, s[12:13] offset:3072
	global_load_dwordx4 v[112:115], v193, s[12:13] offset:0
	global_load_dwordx4 v[116:119], v193, s[12:13] offset:1024
	global_load_dwordx4 v[120:123], v193, s[12:13] offset:2048
	global_load_dwordx4 v[124:127], v193, s[12:13] offset:3072
	s_waitcnt vmcnt(0)
	v_mul_f32_e32 v128, v128, v32
	v_mul_f32_e32 v129, v129, v33
	v_mul_f32_e32 v130, v130, v34
	v_mul_f32_e32 v131, v131, v35
	v_mul_f32_e32 v132, v132, v36
	v_mul_f32_e32 v133, v133, v37
	v_mul_f32_e32 v134, v134, v38
	v_mul_f32_e32 v135, v135, v39
	v_mul_f32_e32 v136, v136, v40
	v_mul_f32_e32 v137, v137, v41
	v_mul_f32_e32 v138, v138, v42
	v_mul_f32_e32 v139, v139, v43
	v_mul_f32_e32 v140, v140, v44
	v_mul_f32_e32 v141, v141, v45
	v_mul_f32_e32 v142, v142, v46
	v_mul_f32_e32 v143, v143, v47
	v_mul_f32_e32 v144, v144, v48
	v_mul_f32_e32 v145, v145, v49
	v_mul_f32_e32 v146, v146, v50
	v_mul_f32_e32 v147, v147, v51
	v_mul_f32_e32 v148, v148, v52
	v_mul_f32_e32 v149, v149, v53
	v_mul_f32_e32 v150, v150, v54
	v_mul_f32_e32 v151, v151, v55
	v_mul_f32_e32 v152, v152, v56
	v_mul_f32_e32 v153, v153, v57
	v_mul_f32_e32 v154, v154, v58
	v_mul_f32_e32 v155, v155, v59
	v_mul_f32_e32 v156, v156, v60
	v_mul_f32_e32 v157, v157, v61
	v_mul_f32_e32 v158, v158, v62
	v_mul_f32_e32 v159, v159, v63
	v_mul_f32_e32 v160, v160, v96
	v_mul_f32_e32 v161, v161, v97
	v_mul_f32_e32 v162, v162, v98
	v_mul_f32_e32 v163, v163, v99
	v_mul_f32_e32 v164, v164, v100
	v_mul_f32_e32 v165, v165, v101
	v_mul_f32_e32 v166, v166, v102
	v_mul_f32_e32 v167, v167, v103
	v_mul_f32_e32 v168, v168, v104
	v_mul_f32_e32 v169, v169, v105
	v_mul_f32_e32 v170, v170, v106
	v_mul_f32_e32 v171, v171, v107
	v_mul_f32_e32 v172, v172, v108
	v_mul_f32_e32 v173, v173, v109
	v_mul_f32_e32 v174, v174, v110
	v_mul_f32_e32 v175, v175, v111
	v_mul_f32_e32 v176, v176, v112
	v_mul_f32_e32 v177, v177, v113
	v_mul_f32_e32 v178, v178, v114
	v_mul_f32_e32 v179, v179, v115
	v_mul_f32_e32 v180, v180, v116
	v_mul_f32_e32 v181, v181, v117
	v_mul_f32_e32 v182, v182, v118
	v_mul_f32_e32 v183, v183, v119
	v_mul_f32_e32 v184, v184, v120
	v_mul_f32_e32 v185, v185, v121
	v_mul_f32_e32 v186, v186, v122
	v_mul_f32_e32 v187, v187, v123
	v_mul_f32_e32 v188, v188, v124
	v_mul_f32_e32 v189, v189, v125
	v_mul_f32_e32 v190, v190, v126
	v_mul_f32_e32 v191, v191, v127
	global_load_dwordx4 v[0:3], v192, s[14:15] offset:0
	global_load_dwordx4 v[4:7], v192, s[14:15] offset:1024
	global_load_dwordx4 v[8:11], v192, s[14:15] offset:2048
	global_load_dwordx4 v[12:15], v192, s[14:15] offset:3072
	global_load_dwordx4 v[16:19], v193, s[14:15] offset:0
	global_load_dwordx4 v[20:23], v193, s[14:15] offset:1024
	global_load_dwordx4 v[24:27], v193, s[14:15] offset:2048
	global_load_dwordx4 v[28:31], v193, s[14:15] offset:3072
	global_load_dwordx2 v[64:65], v194, s[16:17] offset:0
	global_load_dwordx2 v[66:67], v194, s[16:17] offset:512
	global_load_dwordx2 v[68:69], v194, s[16:17] offset:1024
	global_load_dwordx2 v[70:71], v194, s[16:17] offset:1536
	global_load_dwordx2 v[72:73], v194, s[16:17] offset:2048
	global_load_dwordx2 v[74:75], v194, s[16:17] offset:2560
; __device__ __forceinline__ float bf_lo(unsigned w) { return __uint_as_float(w << 16); }
; __device__ __forceinline__ float bf_hi(unsigned w) { return __uint_as_float(w & 0xffff0000u); }
; __global__ void __launch_bounds__(NWAVES * 64, 2) mk_fwd(Args args) {
;     ...
;             for (int q = 0; q < 2; ++q) { const int row = row0 + q; load_row_f32(args.out + (size_t)row * DM, F.lane, v[q]);
;                 const bf16_t* yr = Y + (size_t)row * DM;
; #pragma unroll
;                 for (int j = 0; j < 8; ++j) yw[q][j] = *(const u32x2*)(yr + 4 * F.lane + 256 * j); }
; #pragma unroll
;             for (int q = 0; q < 2; ++q) { const int row = row0 + q; const int r = row / SEQ;
;                 if (r != rcur) { const float* m1 = mod + (size_t)(9 + r) * 6144; rcur = r;
; #pragma unroll
;                     for (int j = 0; j < 8; ++j) { const int col = 4 * F.lane + 256 * j; PA[j] = *(const f32x4*)(m1 + 2 * DM + col) * *(const f32x4*)(post_norm + DM + col); } }
;                 float sy = 0.f;
; #pragma unroll
;                 for (int j = 0; j < 8; ++j) { const float a = bf_lo(yw[q][j].x), b = bf_hi(yw[q][j].x), c2 = bf_lo(yw[q][j].y), d = bf_hi(yw[q][j].y); sy += (a * a + b * b) + (c2 * c2 + d * d); }
	global_load_dwordx2 v[76:77], v194, s[16:17] offset:3072
	global_load_dwordx2 v[78:79], v194, s[16:17] offset:3584
	global_load_dwordx2 v[96:97], v194, s[22:23] offset:0
	global_load_dwordx2 v[98:99], v194, s[22:23] offset:512
	global_load_dwordx2 v[100:101], v194, s[22:23] offset:1024
	global_load_dwordx2 v[102:103], v194, s[22:23] offset:1536
	global_load_dwordx2 v[104:105], v194, s[22:23] offset:2048
	global_load_dwordx2 v[106:107], v194, s[22:23] offset:2560
	global_load_dwordx2 v[108:109], v194, s[22:23] offset:3072
	global_load_dwordx2 v[110:111], v194, s[22:23] offset:3584
	s_add_u32 s14, s14, 0x2000
	s_addc_u32 s15, s15, 0
	s_add_u32 s16, s16, 0x1000
	s_addc_u32 s17, s17, 0
	s_add_u32 s22, s22, 0x1000
	s_addc_u32 s23, s23, 0
	global_load_dwordx4 v[32:35], v192, s[14:15] offset:0
	global_load_dwordx4 v[36:39], v192, s[14:15] offset:1024
	global_load_dwordx4 v[40:43], v192, s[14:15] offset:2048
	global_load_dwordx4 v[44:47], v192, s[14:15] offset:3072
	global_load_dwordx4 v[48:51], v193, s[14:15] offset:0
	global_load_dwordx4 v[52:55], v193, s[14:15] offset:1024
	global_load_dwordx4 v[56:59], v193, s[14:15] offset:2048
	global_load_dwordx4 v[60:63], v193, s[14:15] offset:3072
	global_load_dwordx2 v[80:81], v194, s[16:17] offset:0
	global_load_dwordx2 v[82:83], v194, s[16:17] offset:512
	global_load_dwordx2 v[84:85], v194, s[16:17] offset:1024
	global_load_dwordx2 v[86:87], v194, s[16:17] offset:1536
	global_load_dwordx2 v[88:89], v194, s[16:17] offset:2048
	global_load_dwordx2 v[90:91], v194, s[16:17] offset:2560
	global_load_dwordx2 v[92:93], v194, s[16:17] offset:3072
	global_load_dwordx2 v[94:95], v194, s[16:17] offset:3584
	global_load_dwordx2 v[112:113], v194, s[22:23] offset:0
	global_load_dwordx2 v[114:115], v194, s[22:23] offset:512
	global_load_dwordx2 v[116:117], v194, s[22:23] offset:1024
	global_load_dwordx2 v[118:119], v194, s[22:23] offset:1536
	global_load_dwordx2 v[120:121], v194, s[22:23] offset:2048
	global_load_dwordx2 v[122:123], v194, s[22:23] offset:2560
	global_load_dwordx2 v[124:125], v194, s[22:23] offset:3072
	global_load_dwordx2 v[126:127], v194, s[22:23] offset:3584
	s_add_u32 s14, s14, 0x2000
	s_addc_u32 s15, s15, 0
	s_add_u32 s16, s16, 0x1000
	s_addc_u32 s17, s17, 0
	s_add_u32 s22, s22, 0x1000
	s_addc_u32 s23, s23, 0
	s_waitcnt vmcnt(24)
	v_lshlrev_b32_e32 v200, 16, v64
	v_and_b32_e32 v201, 0xffff0000, v64
	v_lshlrev_b32_e32 v202, 16, v65
	v_and_b32_e32 v203, 0xffff0000, v65
	v_mul_f32_e32 v208, v200, v200
	v_mul_f32_e32 v209, v201, v201
	v_fmac_f32_e32 v208, v202, v202
	v_fmac_f32_e32 v209, v203, v203
	v_lshlrev_b32_e32 v204, 16, v96
	v_and_b32_e32 v205, 0xffff0000, v96
	v_lshlrev_b32_e32 v206, 16, v97
	v_and_b32_e32 v207, 0xffff0000, v97
	v_mul_f32_e32 v210, v204, v204
	v_mul_f32_e32 v211, v205, v205
	v_fmac_f32_e32 v210, v206, v206
	v_fmac_f32_e32 v211, v207, v207
	v_lshlrev_b32_e32 v200, 16, v66
	v_and_b32_e32 v201, 0xffff0000, v66
	v_lshlrev_b32_e32 v202, 16, v67
	v_and_b32_e32 v203, 0xffff0000, v67
	v_fmac_f32_e32 v208, v200, v200
	v_fmac_f32_e32 v209, v201, v201
	v_fmac_f32_e32 v208, v202, v202
	v_fmac_f32_e32 v209, v203, v203
	v_lshlrev_b32_e32 v204, 16, v98
	v_and_b32_e32 v205, 0xffff0000, v98
	v_lshlrev_b32_e32 v206, 16, v99
	v_and_b32_e32 v207, 0xffff0000, v99
	v_fmac_f32_e32 v210, v204, v204
	v_fmac_f32_e32 v211, v205, v205
	v_fmac_f32_e32 v210, v206, v206
	v_fmac_f32_e32 v211, v207, v207
	v_lshlrev_b32_e32 v200, 16, v68
	v_and_b32_e32 v201, 0xffff0000, v68
	v_lshlrev_b32_e32 v202, 16, v69
	v_and_b32_e32 v203, 0xffff0000, v69
	v_fmac_f32_e32 v208, v200, v200
	v_fmac_f32_e32 v209, v201, v201
	v_fmac_f32_e32 v208, v202, v202
	v_fmac_f32_e32 v209, v203, v203
	v_lshlrev_b32_e32 v204, 16, v100
	v_and_b32_e32 v205, 0xffff0000, v100
	v_lshlrev_b32_e32 v206, 16, v101
	v_and_b32_e32 v207, 0xffff0000, v101
	v_fmac_f32_e32 v210, v204, v204
	v_fmac_f32_e32 v211, v205, v205
	v_fmac_f32_e32 v210, v206, v206
	v_fmac_f32_e32 v211, v207, v207
	v_lshlrev_b32_e32 v200, 16, v70
	v_and_b32_e32 v201, 0xffff0000, v70
	v_lshlrev_b32_e32 v202, 16, v71
	v_and_b32_e32 v203, 0xffff0000, v71
	v_fmac_f32_e32 v208, v200, v200
	v_fmac_f32_e32 v209, v201, v201
	v_fmac_f32_e32 v208, v202, v202
	v_fmac_f32_e32 v209, v203, v203
	v_lshlrev_b32_e32 v204, 16, v102
	v_and_b32_e32 v205, 0xffff0000, v102
	v_lshlrev_b32_e32 v206, 16, v103
	v_and_b32_e32 v207, 0xffff0000, v103
	v_fmac_f32_e32 v210, v204, v204
	v_fmac_f32_e32 v211, v205, v205
	v_fmac_f32_e32 v210, v206, v206
	v_fmac_f32_e32 v211, v207, v207
	v_lshlrev_b32_e32 v200, 16, v72
	v_and_b32_e32 v201, 0xffff0000, v72
	v_lshlrev_b32_e32 v202, 16, v73
	v_and_b32_e32 v203, 0xffff0000, v73
	v_fmac_f32_e32 v208, v200, v200
	v_fmac_f32_e32 v209, v201, v201
	v_fmac_f32_e32 v208, v202, v202
	v_fmac_f32_e32 v209, v203, v203
	v_lshlrev_b32_e32 v204, 16, v104
	v_and_b32_e32 v205, 0xffff0000, v104
	v_lshlrev_b32_e32 v206, 16, v105
	v_and_b32_e32 v207, 0xffff0000, v105
	v_fmac_f32_e32 v210, v204, v204
	v_fmac_f32_e32 v211, v205, v205
	v_fmac_f32_e32 v210, v206, v206
	v_fmac_f32_e32 v211, v207, v207
	v_lshlrev_b32_e32 v200, 16, v74
	v_and_b32_e32 v201, 0xffff0000, v74
	v_lshlrev_b32_e32 v202, 16, v75
	v_and_b32_e32 v203, 0xffff0000, v75
	v_fmac_f32_e32 v208, v200, v200
	v_fmac_f32_e32 v209, v201, v201
	v_fmac_f32_e32 v208, v202, v202
	v_fmac_f32_e32 v209, v203, v203
	v_lshlrev_b32_e32 v204, 16, v106
	v_and_b32_e32 v205, 0xffff0000, v106
	v_lshlrev_b32_e32 v206, 16, v107
	v_and_b32_e32 v207, 0xffff0000, v107
	v_fmac_f32_e32 v210, v204, v204
	v_fmac_f32_e32 v211, v205, v205
	v_fmac_f32_e32 v210, v206, v206
	v_fmac_f32_e32 v211, v207, v207
	v_lshlrev_b32_e32 v200, 16, v76
; __device__ __forceinline__ float bf_lo(unsigned w) { return __uint_as_float(w << 16); }
; __device__ __forceinline__ float bf_hi(unsigned w) { return __uint_as_float(w & 0xffff0000u); }
; __global__ void __launch_bounds__(NWAVES * 64, 2) mk_fwd(Args args) {
;     ...
;                 float sy = 0.f;
; #pragma unroll
;                 for (int j = 0; j < 8; ++j) { const float a = bf_lo(yw[q][j].x), b = bf_hi(yw[q][j].x), c2 = bf_lo(yw[q][j].y), d = bf_hi(yw[q][j].y); sy += (a * a + b * b) + (c2 * c2 + d * d); }
;                 const float rsy = __builtin_amdgcn_rsqf(wave_sum(sy) * (1.f / DM) + EPS);
; #pragma unroll
;                 for (int j = 0; j < 8; ++j) { const int col = 4 * F.lane + 256 * j;
;                     const f32x4 y4 = (f32x4){bf_lo(yw[q][j].x), bf_hi(yw[q][j].x), bf_lo(yw[q][j].y), bf_hi(yw[q][j].y)};
;                     *(f32x4*)(args.out + (size_t)row * DM + col) = v[q][j] + PA[j] * (y4 * rsy); }
	v_and_b32_e32 v201, 0xffff0000, v76
	v_lshlrev_b32_e32 v202, 16, v77
	v_and_b32_e32 v203, 0xffff0000, v77
	v_fmac_f32_e32 v208, v200, v200
	v_fmac_f32_e32 v209, v201, v201
	v_fmac_f32_e32 v208, v202, v202
	v_fmac_f32_e32 v209, v203, v203
	v_lshlrev_b32_e32 v204, 16, v108
	v_and_b32_e32 v205, 0xffff0000, v108
	v_lshlrev_b32_e32 v206, 16, v109
	v_and_b32_e32 v207, 0xffff0000, v109
	v_fmac_f32_e32 v210, v204, v204
	v_fmac_f32_e32 v211, v205, v205
	v_fmac_f32_e32 v210, v206, v206
	v_fmac_f32_e32 v211, v207, v207
	v_lshlrev_b32_e32 v200, 16, v78
	v_and_b32_e32 v201, 0xffff0000, v78
	v_lshlrev_b32_e32 v202, 16, v79
	v_and_b32_e32 v203, 0xffff0000, v79
	v_fmac_f32_e32 v208, v200, v200
	v_fmac_f32_e32 v209, v201, v201
	v_fmac_f32_e32 v208, v202, v202
	v_fmac_f32_e32 v209, v203, v203
	v_lshlrev_b32_e32 v204, 16, v110
	v_and_b32_e32 v205, 0xffff0000, v110
	v_lshlrev_b32_e32 v206, 16, v111
	v_and_b32_e32 v207, 0xffff0000, v111
	v_fmac_f32_e32 v210, v204, v204
	v_fmac_f32_e32 v211, v205, v205
	v_fmac_f32_e32 v210, v206, v206
	v_fmac_f32_e32 v211, v207, v207
	v_add_f32_e32 v208, v208, v209
	v_add_f32_e32 v210, v210, v211
	s_nop 0
	v_add_f32_dpp v212, v208, v208 quad_perm:[1,0,3,2] row_mask:0xf bank_mask:0xf
	v_add_f32_dpp v213, v210, v210 quad_perm:[1,0,3,2] row_mask:0xf bank_mask:0xf
	s_nop 0
	v_add_f32_dpp v212, v212, v212 quad_perm:[2,3,0,1] row_mask:0xf bank_mask:0xf
	v_add_f32_dpp v213, v213, v213 quad_perm:[2,3,0,1] row_mask:0xf bank_mask:0xf
	s_nop 0
	v_add_f32_dpp v212, v212, v212 row_half_mirror row_mask:0xf bank_mask:0xf
	v_add_f32_dpp v213, v213, v213 row_half_mirror row_mask:0xf bank_mask:0xf
	s_nop 0
	v_add_f32_dpp v212, v212, v212 row_mirror row_mask:0xf bank_mask:0xf
	v_add_f32_dpp v213, v213, v213 row_mirror row_mask:0xf bank_mask:0xf
	s_nop 0
	v_readlane_b32 s4, v212, 0
	v_readlane_b32 s5, v212, 16
	v_readlane_b32 s6, v212, 32
	v_readlane_b32 s7, v212, 48
	v_readlane_b32 s24, v213, 0
	v_readlane_b32 s25, v213, 16
	v_readlane_b32 s26, v213, 32
	v_readlane_b32 s27, v213, 48
	s_nop 1
	v_mov_b32_e32 v214, s4
	v_mov_b32_e32 v215, s24
	v_add_f32_e32 v214, s5, v214
	v_add_f32_e32 v215, s25, v215
	v_add_f32_e32 v214, s6, v214
	v_add_f32_e32 v215, s26, v215
	v_add_f32_e32 v214, s7, v214
	v_add_f32_e32 v215, s27, v215
	v_fmamk_f32 v214, v214, 0x3a000000, v195
	v_fmamk_f32 v215, v215, 0x3a000000, v195
	v_rsq_f32_e32 v214, v214
	v_rsq_f32_e32 v215, v215
	s_nop 0
	v_lshlrev_b32_e32 v200, 16, v64
	v_and_b32_e32 v201, 0xffff0000, v64
	v_lshlrev_b32_e32 v202, 16, v65
	v_and_b32_e32 v203, 0xffff0000, v65
	v_lshlrev_b32_e32 v204, 16, v96
	v_and_b32_e32 v205, 0xffff0000, v96
	v_lshlrev_b32_e32 v206, 16, v97
	v_and_b32_e32 v207, 0xffff0000, v97
	v_mul_f32_e32 v200, v214, v200
	v_mul_f32_e32 v201, v214, v201
	v_mul_f32_e32 v202, v214, v202
	v_mul_f32_e32 v203, v214, v203
	v_mul_f32_e32 v204, v215, v204
	v_mul_f32_e32 v205, v215, v205
	v_mul_f32_e32 v206, v215, v206
	v_mul_f32_e32 v207, v215, v207
	v_fmac_f32_e32 v0, v128, v200
	v_fmac_f32_e32 v1, v129, v201
	v_fmac_f32_e32 v2, v130, v202
	v_fmac_f32_e32 v3, v131, v203
	v_fmac_f32_e32 v0, v160, v204
	v_fmac_f32_e32 v1, v161, v205
	v_fmac_f32_e32 v2, v162, v206
	v_fmac_f32_e32 v3, v163, v207
	global_store_dwordx4 v192, v[0:3], s[18:19] offset:0 nt
	v_lshlrev_b32_e32 v200, 16, v66
	v_and_b32_e32 v201, 0xffff0000, v66
	v_lshlrev_b32_e32 v202, 16, v67
	v_and_b32_e32 v203, 0xffff0000, v67
	v_lshlrev_b32_e32 v204, 16, v98
	v_and_b32_e32 v205, 0xffff0000, v98
	v_lshlrev_b32_e32 v206, 16, v99
	v_and_b32_e32 v207, 0xffff0000, v99
	v_mul_f32_e32 v200, v214, v200
	v_mul_f32_e32 v201, v214, v201
	v_mul_f32_e32 v202, v214, v202
	v_mul_f32_e32 v203, v214, v203
	v_mul_f32_e32 v204, v215, v204
	v_mul_f32_e32 v205, v215, v205
	v_mul_f32_e32 v206, v215, v206
	v_mul_f32_e32 v207, v215, v207
	v_fmac_f32_e32 v4, v132, v200
	v_fmac_f32_e32 v5, v133, v201
	v_fmac_f32_e32 v6, v134, v202
	v_fmac_f32_e32 v7, v135, v203
	v_fmac_f32_e32 v4, v164, v204
	v_fmac_f32_e32 v5, v165, v205
	v_fmac_f32_e32 v6, v166, v206
	v_fmac_f32_e32 v7, v167, v207
	global_store_dwordx4 v192, v[4:7], s[18:19] offset:1024 nt
	v_lshlrev_b32_e32 v200, 16, v68
	v_and_b32_e32 v201, 0xffff0000, v68
	v_lshlrev_b32_e32 v202, 16, v69
	v_and_b32_e32 v203, 0xffff0000, v69
	v_lshlrev_b32_e32 v204, 16, v100
	v_and_b32_e32 v205, 0xffff0000, v100
	v_lshlrev_b32_e32 v206, 16, v101
	v_and_b32_e32 v207, 0xffff0000, v101
	v_mul_f32_e32 v200, v214, v200
	v_mul_f32_e32 v201, v214, v201
	v_mul_f32_e32 v202, v214, v202
	v_mul_f32_e32 v203, v214, v203
	v_mul_f32_e32 v204, v215, v204
	v_mul_f32_e32 v205, v215, v205
	v_mul_f32_e32 v206, v215, v206
	v_mul_f32_e32 v207, v215, v207
	v_fmac_f32_e32 v8, v136, v200
	v_fmac_f32_e32 v9, v137, v201
	v_fmac_f32_e32 v10, v138, v202
	v_fmac_f32_e32 v11, v139, v203
	v_fmac_f32_e32 v8, v168, v204
	v_fmac_f32_e32 v9, v169, v205
	v_fmac_f32_e32 v10, v170, v206
	v_fmac_f32_e32 v11, v171, v207
	global_store_dwordx4 v192, v[8:11], s[18:19] offset:2048 nt
	v_lshlrev_b32_e32 v200, 16, v70
	v_and_b32_e32 v201, 0xffff0000, v70
	v_lshlrev_b32_e32 v202, 16, v71
	v_and_b32_e32 v203, 0xffff0000, v71
	v_lshlrev_b32_e32 v204, 16, v102
	v_and_b32_e32 v205, 0xffff0000, v102
	v_lshlrev_b32_e32 v206, 16, v103
	v_and_b32_e32 v207, 0xffff0000, v103
	v_mul_f32_e32 v200, v214, v200
	v_mul_f32_e32 v201, v214, v201
	v_mul_f32_e32 v202, v214, v202
	v_mul_f32_e32 v203, v214, v203
	v_mul_f32_e32 v204, v215, v204
	v_mul_f32_e32 v205, v215, v205
	v_mul_f32_e32 v206, v215, v206
	v_mul_f32_e32 v207, v215, v207
	v_fmac_f32_e32 v12, v140, v200
	v_fmac_f32_e32 v13, v141, v201
	v_fmac_f32_e32 v14, v142, v202
	v_fmac_f32_e32 v15, v143, v203
	v_fmac_f32_e32 v12, v172, v204
; __device__ __forceinline__ float bf_lo(unsigned w) { return __uint_as_float(w << 16); }
; __device__ __forceinline__ float bf_hi(unsigned w) { return __uint_as_float(w & 0xffff0000u); }
; __global__ void __launch_bounds__(NWAVES * 64, 2) mk_fwd(Args args) {
;     ...
;                 float sy = 0.f;
; #pragma unroll
;                 for (int j = 0; j < 8; ++j) { const float a = bf_lo(yw[q][j].x), b = bf_hi(yw[q][j].x), c2 = bf_lo(yw[q][j].y), d = bf_hi(yw[q][j].y); sy += (a * a + b * b) + (c2 * c2 + d * d); }
;                 const float rsy = __builtin_amdgcn_rsqf(wave_sum(sy) * (1.f / DM) + EPS);
; #pragma unroll
;                 for (int j = 0; j < 8; ++j) { const int col = 4 * F.lane + 256 * j;
;                     const f32x4 y4 = (f32x4){bf_lo(yw[q][j].x), bf_hi(yw[q][j].x), bf_lo(yw[q][j].y), bf_hi(yw[q][j].y)};
;                     *(f32x4*)(args.out + (size_t)row * DM + col) = v[q][j] + PA[j] * (y4 * rsy); }
	v_fmac_f32_e32 v13, v173, v205
	v_fmac_f32_e32 v14, v174, v206
	v_fmac_f32_e32 v15, v175, v207
	global_store_dwordx4 v192, v[12:15], s[18:19] offset:3072 nt
	v_lshlrev_b32_e32 v200, 16, v72
	v_and_b32_e32 v201, 0xffff0000, v72
	v_lshlrev_b32_e32 v202, 16, v73
	v_and_b32_e32 v203, 0xffff0000, v73
	v_lshlrev_b32_e32 v204, 16, v104
	v_and_b32_e32 v205, 0xffff0000, v104
	v_lshlrev_b32_e32 v206, 16, v105
	v_and_b32_e32 v207, 0xffff0000, v105
	v_mul_f32_e32 v200, v214, v200
	v_mul_f32_e32 v201, v214, v201
	v_mul_f32_e32 v202, v214, v202
	v_mul_f32_e32 v203, v214, v203
	v_mul_f32_e32 v204, v215, v204
	v_mul_f32_e32 v205, v215, v205
	v_mul_f32_e32 v206, v215, v206
	v_mul_f32_e32 v207, v215, v207
	v_fmac_f32_e32 v16, v144, v200
	v_fmac_f32_e32 v17, v145, v201
	v_fmac_f32_e32 v18, v146, v202
	v_fmac_f32_e32 v19, v147, v203
	v_fmac_f32_e32 v16, v176, v204
	v_fmac_f32_e32 v17, v177, v205
	v_fmac_f32_e32 v18, v178, v206
	v_fmac_f32_e32 v19, v179, v207
	global_store_dwordx4 v193, v[16:19], s[18:19] offset:0 nt
	v_lshlrev_b32_e32 v200, 16, v74
	v_and_b32_e32 v201, 0xffff0000, v74
	v_lshlrev_b32_e32 v202, 16, v75
	v_and_b32_e32 v203, 0xffff0000, v75
	v_lshlrev_b32_e32 v204, 16, v106
	v_and_b32_e32 v205, 0xffff0000, v106
	v_lshlrev_b32_e32 v206, 16, v107
	v_and_b32_e32 v207, 0xffff0000, v107
	v_mul_f32_e32 v200, v214, v200
	v_mul_f32_e32 v201, v214, v201
	v_mul_f32_e32 v202, v214, v202
	v_mul_f32_e32 v203, v214, v203
	v_mul_f32_e32 v204, v215, v204
	v_mul_f32_e32 v205, v215, v205
	v_mul_f32_e32 v206, v215, v206
	v_mul_f32_e32 v207, v215, v207
	v_fmac_f32_e32 v20, v148, v200
	v_fmac_f32_e32 v21, v149, v201
	v_fmac_f32_e32 v22, v150, v202
	v_fmac_f32_e32 v23, v151, v203
	v_fmac_f32_e32 v20, v180, v204
	v_fmac_f32_e32 v21, v181, v205
	v_fmac_f32_e32 v22, v182, v206
	v_fmac_f32_e32 v23, v183, v207
	global_store_dwordx4 v193, v[20:23], s[18:19] offset:1024 nt
	v_lshlrev_b32_e32 v200, 16, v76
	v_and_b32_e32 v201, 0xffff0000, v76
	v_lshlrev_b32_e32 v202, 16, v77
	v_and_b32_e32 v203, 0xffff0000, v77
	v_lshlrev_b32_e32 v204, 16, v108
	v_and_b32_e32 v205, 0xffff0000, v108
	v_lshlrev_b32_e32 v206, 16, v109
	v_and_b32_e32 v207, 0xffff0000, v109
	v_mul_f32_e32 v200, v214, v200
	v_mul_f32_e32 v201, v214, v201
	v_mul_f32_e32 v202, v214, v202
	v_mul_f32_e32 v203, v214, v203
	v_mul_f32_e32 v204, v215, v204
	v_mul_f32_e32 v205, v215, v205
	v_mul_f32_e32 v206, v215, v206
	v_mul_f32_e32 v207, v215, v207
	v_fmac_f32_e32 v24, v152, v200
	v_fmac_f32_e32 v25, v153, v201
	v_fmac_f32_e32 v26, v154, v202
	v_fmac_f32_e32 v27, v155, v203
	v_fmac_f32_e32 v24, v184, v204
	v_fmac_f32_e32 v25, v185, v205
	v_fmac_f32_e32 v26, v186, v206
	v_fmac_f32_e32 v27, v187, v207
	global_store_dwordx4 v193, v[24:27], s[18:19] offset:2048 nt
	v_lshlrev_b32_e32 v200, 16, v78
	v_and_b32_e32 v201, 0xffff0000, v78
	v_lshlrev_b32_e32 v202, 16, v79
	v_and_b32_e32 v203, 0xffff0000, v79
	v_lshlrev_b32_e32 v204, 16, v110
	v_and_b32_e32 v205, 0xffff0000, v110
	v_lshlrev_b32_e32 v206, 16, v111
	v_and_b32_e32 v207, 0xffff0000, v111
	v_mul_f32_e32 v200, v214, v200
	v_mul_f32_e32 v201, v214, v201
	v_mul_f32_e32 v202, v214, v202
	v_mul_f32_e32 v203, v214, v203
	v_mul_f32_e32 v204, v215, v204
	v_mul_f32_e32 v205, v215, v205
	v_mul_f32_e32 v206, v215, v206
	v_mul_f32_e32 v207, v215, v207
	v_fmac_f32_e32 v28, v156, v200
	v_fmac_f32_e32 v29, v157, v201
	v_fmac_f32_e32 v30, v158, v202
	v_fmac_f32_e32 v31, v159, v203
	v_fmac_f32_e32 v28, v188, v204
	v_fmac_f32_e32 v29, v189, v205
	v_fmac_f32_e32 v30, v190, v206
	v_fmac_f32_e32 v31, v191, v207
	global_store_dwordx4 v193, v[28:31], s[18:19] offset:3072 nt
	s_add_u32 s18, s18, 0x2000
	s_addc_u32 s19, s19, 0
	global_load_dwordx4 v[0:3], v192, s[14:15] offset:0
	global_load_dwordx4 v[4:7], v192, s[14:15] offset:1024
	global_load_dwordx4 v[8:11], v192, s[14:15] offset:2048
	global_load_dwordx4 v[12:15], v192, s[14:15] offset:3072
	global_load_dwordx4 v[16:19], v193, s[14:15] offset:0
	global_load_dwordx4 v[20:23], v193, s[14:15] offset:1024
	global_load_dwordx4 v[24:27], v193, s[14:15] offset:2048
	global_load_dwordx4 v[28:31], v193, s[14:15] offset:3072
	global_load_dwordx2 v[64:65], v194, s[16:17] offset:0
	global_load_dwordx2 v[66:67], v194, s[16:17] offset:512
	global_load_dwordx2 v[68:69], v194, s[16:17] offset:1024
	global_load_dwordx2 v[70:71], v194, s[16:17] offset:1536
	global_load_dwordx2 v[72:73], v194, s[16:17] offset:2048
	global_load_dwordx2 v[74:75], v194, s[16:17] offset:2560
	global_load_dwordx2 v[76:77], v194, s[16:17] offset:3072
	global_load_dwordx2 v[78:79], v194, s[16:17] offset:3584
	global_load_dwordx2 v[96:97], v194, s[22:23] offset:0
	global_load_dwordx2 v[98:99], v194, s[22:23] offset:512
	global_load_dwordx2 v[100:101], v194, s[22:23] offset:1024
	global_load_dwordx2 v[102:103], v194, s[22:23] offset:1536
	global_load_dwordx2 v[104:105], v194, s[22:23] offset:2048
	global_load_dwordx2 v[106:107], v194, s[22:23] offset:2560
	global_load_dwordx2 v[108:109], v194, s[22:23] offset:3072
	global_load_dwordx2 v[110:111], v194, s[22:23] offset:3584
	s_add_u32 s14, s14, 0x2000
	s_addc_u32 s15, s15, 0
	s_add_u32 s16, s16, 0x1000
	s_addc_u32 s17, s17, 0
	s_add_u32 s22, s22, 0x1000
	s_addc_u32 s23, s23, 0
	s_waitcnt vmcnt(32)
; __device__ __forceinline__ float bf_lo(unsigned w) { return __uint_as_float(w << 16); }
; __device__ __forceinline__ float bf_hi(unsigned w) { return __uint_as_float(w & 0xffff0000u); }
; __global__ void __launch_bounds__(NWAVES * 64, 2) mk_fwd(Args args) {
;     ...
;                 float sy = 0.f;
; #pragma unroll
;                 for (int j = 0; j < 8; ++j) { const float a = bf_lo(yw[q][j].x), b = bf_hi(yw[q][j].x), c2 = bf_lo(yw[q][j].y), d = bf_hi(yw[q][j].y); sy += (a * a + b * b) + (c2 * c2 + d * d); }
;                 const float rsy = __builtin_amdgcn_rsqf(wave_sum(sy) * (1.f / DM) + EPS);
	v_lshlrev_b32_e32 v200, 16, v80
	v_and_b32_e32 v201, 0xffff0000, v80
	v_lshlrev_b32_e32 v202, 16, v81
	v_and_b32_e32 v203, 0xffff0000, v81
	v_mul_f32_e32 v208, v200, v200
	v_mul_f32_e32 v209, v201, v201
	v_fmac_f32_e32 v208, v202, v202
	v_fmac_f32_e32 v209, v203, v203
	v_lshlrev_b32_e32 v204, 16, v112
	v_and_b32_e32 v205, 0xffff0000, v112
	v_lshlrev_b32_e32 v206, 16, v113
	v_and_b32_e32 v207, 0xffff0000, v113
	v_mul_f32_e32 v210, v204, v204
	v_mul_f32_e32 v211, v205, v205
	v_fmac_f32_e32 v210, v206, v206
	v_fmac_f32_e32 v211, v207, v207
	v_lshlrev_b32_e32 v200, 16, v82
	v_and_b32_e32 v201, 0xffff0000, v82
	v_lshlrev_b32_e32 v202, 16, v83
	v_and_b32_e32 v203, 0xffff0000, v83
	v_fmac_f32_e32 v208, v200, v200
	v_fmac_f32_e32 v209, v201, v201
	v_fmac_f32_e32 v208, v202, v202
	v_fmac_f32_e32 v209, v203, v203
	v_lshlrev_b32_e32 v204, 16, v114
	v_and_b32_e32 v205, 0xffff0000, v114
	v_lshlrev_b32_e32 v206, 16, v115
	v_and_b32_e32 v207, 0xffff0000, v115
	v_fmac_f32_e32 v210, v204, v204
	v_fmac_f32_e32 v211, v205, v205
	v_fmac_f32_e32 v210, v206, v206
	v_fmac_f32_e32 v211, v207, v207
	v_lshlrev_b32_e32 v200, 16, v84
	v_and_b32_e32 v201, 0xffff0000, v84
	v_lshlrev_b32_e32 v202, 16, v85
	v_and_b32_e32 v203, 0xffff0000, v85
	v_fmac_f32_e32 v208, v200, v200
	v_fmac_f32_e32 v209, v201, v201
	v_fmac_f32_e32 v208, v202, v202
	v_fmac_f32_e32 v209, v203, v203
	v_lshlrev_b32_e32 v204, 16, v116
	v_and_b32_e32 v205, 0xffff0000, v116
	v_lshlrev_b32_e32 v206, 16, v117
	v_and_b32_e32 v207, 0xffff0000, v117
	v_fmac_f32_e32 v210, v204, v204
	v_fmac_f32_e32 v211, v205, v205
	v_fmac_f32_e32 v210, v206, v206
	v_fmac_f32_e32 v211, v207, v207
	v_lshlrev_b32_e32 v200, 16, v86
	v_and_b32_e32 v201, 0xffff0000, v86
	v_lshlrev_b32_e32 v202, 16, v87
	v_and_b32_e32 v203, 0xffff0000, v87
	v_fmac_f32_e32 v208, v200, v200
	v_fmac_f32_e32 v209, v201, v201
	v_fmac_f32_e32 v208, v202, v202
	v_fmac_f32_e32 v209, v203, v203
	v_lshlrev_b32_e32 v204, 16, v118
	v_and_b32_e32 v205, 0xffff0000, v118
	v_lshlrev_b32_e32 v206, 16, v119
	v_and_b32_e32 v207, 0xffff0000, v119
	v_fmac_f32_e32 v210, v204, v204
	v_fmac_f32_e32 v211, v205, v205
	v_fmac_f32_e32 v210, v206, v206
	v_fmac_f32_e32 v211, v207, v207
	v_lshlrev_b32_e32 v200, 16, v88
	v_and_b32_e32 v201, 0xffff0000, v88
	v_lshlrev_b32_e32 v202, 16, v89
	v_and_b32_e32 v203, 0xffff0000, v89
	v_fmac_f32_e32 v208, v200, v200
	v_fmac_f32_e32 v209, v201, v201
	v_fmac_f32_e32 v208, v202, v202
	v_fmac_f32_e32 v209, v203, v203
	v_lshlrev_b32_e32 v204, 16, v120
	v_and_b32_e32 v205, 0xffff0000, v120
	v_lshlrev_b32_e32 v206, 16, v121
	v_and_b32_e32 v207, 0xffff0000, v121
	v_fmac_f32_e32 v210, v204, v204
	v_fmac_f32_e32 v211, v205, v205
	v_fmac_f32_e32 v210, v206, v206
	v_fmac_f32_e32 v211, v207, v207
	v_lshlrev_b32_e32 v200, 16, v90
	v_and_b32_e32 v201, 0xffff0000, v90
	v_lshlrev_b32_e32 v202, 16, v91
	v_and_b32_e32 v203, 0xffff0000, v91
	v_fmac_f32_e32 v208, v200, v200
	v_fmac_f32_e32 v209, v201, v201
	v_fmac_f32_e32 v208, v202, v202
	v_fmac_f32_e32 v209, v203, v203
	v_lshlrev_b32_e32 v204, 16, v122
	v_and_b32_e32 v205, 0xffff0000, v122
	v_lshlrev_b32_e32 v206, 16, v123
	v_and_b32_e32 v207, 0xffff0000, v123
	v_fmac_f32_e32 v210, v204, v204
	v_fmac_f32_e32 v211, v205, v205
	v_fmac_f32_e32 v210, v206, v206
	v_fmac_f32_e32 v211, v207, v207
	v_lshlrev_b32_e32 v200, 16, v92
	v_and_b32_e32 v201, 0xffff0000, v92
	v_lshlrev_b32_e32 v202, 16, v93
	v_and_b32_e32 v203, 0xffff0000, v93
	v_fmac_f32_e32 v208, v200, v200
	v_fmac_f32_e32 v209, v201, v201
	v_fmac_f32_e32 v208, v202, v202
	v_fmac_f32_e32 v209, v203, v203
	v_lshlrev_b32_e32 v204, 16, v124
	v_and_b32_e32 v205, 0xffff0000, v124
	v_lshlrev_b32_e32 v206, 16, v125
	v_and_b32_e32 v207, 0xffff0000, v125
	v_fmac_f32_e32 v210, v204, v204
	v_fmac_f32_e32 v211, v205, v205
	v_fmac_f32_e32 v210, v206, v206
	v_fmac_f32_e32 v211, v207, v207
	v_lshlrev_b32_e32 v200, 16, v94
	v_and_b32_e32 v201, 0xffff0000, v94
	v_lshlrev_b32_e32 v202, 16, v95
	v_and_b32_e32 v203, 0xffff0000, v95
	v_fmac_f32_e32 v208, v200, v200
	v_fmac_f32_e32 v209, v201, v201
	v_fmac_f32_e32 v208, v202, v202
	v_fmac_f32_e32 v209, v203, v203
	v_lshlrev_b32_e32 v204, 16, v126
	v_and_b32_e32 v205, 0xffff0000, v126
	v_lshlrev_b32_e32 v206, 16, v127
	v_and_b32_e32 v207, 0xffff0000, v127
	v_fmac_f32_e32 v210, v204, v204
	v_fmac_f32_e32 v211, v205, v205
	v_fmac_f32_e32 v210, v206, v206
	v_fmac_f32_e32 v211, v207, v207
	v_add_f32_e32 v208, v208, v209
	v_add_f32_e32 v210, v210, v211
	s_nop 0
	v_add_f32_dpp v212, v208, v208 quad_perm:[1,0,3,2] row_mask:0xf bank_mask:0xf
	v_add_f32_dpp v213, v210, v210 quad_perm:[1,0,3,2] row_mask:0xf bank_mask:0xf
	s_nop 0
	v_add_f32_dpp v212, v212, v212 quad_perm:[2,3,0,1] row_mask:0xf bank_mask:0xf
	v_add_f32_dpp v213, v213, v213 quad_perm:[2,3,0,1] row_mask:0xf bank_mask:0xf
	s_nop 0
	v_add_f32_dpp v212, v212, v212 row_half_mirror row_mask:0xf bank_mask:0xf
	v_add_f32_dpp v213, v213, v213 row_half_mirror row_mask:0xf bank_mask:0xf
	s_nop 0
	v_add_f32_dpp v212, v212, v212 row_mirror row_mask:0xf bank_mask:0xf
	v_add_f32_dpp v213, v213, v213 row_mirror row_mask:0xf bank_mask:0xf
	s_nop 0
	v_readlane_b32 s4, v212, 0
	v_readlane_b32 s5, v212, 16
	v_readlane_b32 s6, v212, 32
	v_readlane_b32 s7, v212, 48
	v_readlane_b32 s24, v213, 0
	v_readlane_b32 s25, v213, 16
	v_readlane_b32 s26, v213, 32
	v_readlane_b32 s27, v213, 48
	s_nop 1
	v_mov_b32_e32 v214, s4
	v_mov_b32_e32 v215, s24
	v_add_f32_e32 v214, s5, v214
	v_add_f32_e32 v215, s25, v215
	v_add_f32_e32 v214, s6, v214
	v_add_f32_e32 v215, s26, v215
	v_add_f32_e32 v214, s7, v214
	v_add_f32_e32 v215, s27, v215
	v_fmamk_f32 v214, v214, 0x3a000000, v195
	v_fmamk_f32 v215, v215, 0x3a000000, v195
; __device__ __forceinline__ float bf_lo(unsigned w) { return __uint_as_float(w << 16); }
; __device__ __forceinline__ float bf_hi(unsigned w) { return __uint_as_float(w & 0xffff0000u); }
; __global__ void __launch_bounds__(NWAVES * 64, 2) mk_fwd(Args args) {
;     ...
;                 const float rsy = __builtin_amdgcn_rsqf(wave_sum(sy) * (1.f / DM) + EPS);
; #pragma unroll
;                 for (int j = 0; j < 8; ++j) { const int col = 4 * F.lane + 256 * j;
;                     const f32x4 y4 = (f32x4){bf_lo(yw[q][j].x), bf_hi(yw[q][j].x), bf_lo(yw[q][j].y), bf_hi(yw[q][j].y)};
;                     *(f32x4*)(args.out + (size_t)row * DM + col) = v[q][j] + PA[j] * (y4 * rsy); }
	v_rsq_f32_e32 v214, v214
	v_rsq_f32_e32 v215, v215
	s_nop 0
	v_lshlrev_b32_e32 v200, 16, v80
	v_and_b32_e32 v201, 0xffff0000, v80
	v_lshlrev_b32_e32 v202, 16, v81
	v_and_b32_e32 v203, 0xffff0000, v81
	v_lshlrev_b32_e32 v204, 16, v112
	v_and_b32_e32 v205, 0xffff0000, v112
	v_lshlrev_b32_e32 v206, 16, v113
	v_and_b32_e32 v207, 0xffff0000, v113
	v_mul_f32_e32 v200, v214, v200
	v_mul_f32_e32 v201, v214, v201
	v_mul_f32_e32 v202, v214, v202
	v_mul_f32_e32 v203, v214, v203
	v_mul_f32_e32 v204, v215, v204
	v_mul_f32_e32 v205, v215, v205
	v_mul_f32_e32 v206, v215, v206
	v_mul_f32_e32 v207, v215, v207
	v_fmac_f32_e32 v32, v128, v200
	v_fmac_f32_e32 v33, v129, v201
	v_fmac_f32_e32 v34, v130, v202
	v_fmac_f32_e32 v35, v131, v203
	v_fmac_f32_e32 v32, v160, v204
	v_fmac_f32_e32 v33, v161, v205
	v_fmac_f32_e32 v34, v162, v206
	v_fmac_f32_e32 v35, v163, v207
	global_store_dwordx4 v192, v[32:35], s[18:19] offset:0 nt
	v_lshlrev_b32_e32 v200, 16, v82
	v_and_b32_e32 v201, 0xffff0000, v82
	v_lshlrev_b32_e32 v202, 16, v83
	v_and_b32_e32 v203, 0xffff0000, v83
	v_lshlrev_b32_e32 v204, 16, v114
	v_and_b32_e32 v205, 0xffff0000, v114
	v_lshlrev_b32_e32 v206, 16, v115
	v_and_b32_e32 v207, 0xffff0000, v115
	v_mul_f32_e32 v200, v214, v200
	v_mul_f32_e32 v201, v214, v201
	v_mul_f32_e32 v202, v214, v202
	v_mul_f32_e32 v203, v214, v203
	v_mul_f32_e32 v204, v215, v204
	v_mul_f32_e32 v205, v215, v205
	v_mul_f32_e32 v206, v215, v206
	v_mul_f32_e32 v207, v215, v207
	v_fmac_f32_e32 v36, v132, v200
	v_fmac_f32_e32 v37, v133, v201
	v_fmac_f32_e32 v38, v134, v202
	v_fmac_f32_e32 v39, v135, v203
	v_fmac_f32_e32 v36, v164, v204
	v_fmac_f32_e32 v37, v165, v205
	v_fmac_f32_e32 v38, v166, v206
	v_fmac_f32_e32 v39, v167, v207
	global_store_dwordx4 v192, v[36:39], s[18:19] offset:1024 nt
	v_lshlrev_b32_e32 v200, 16, v84
	v_and_b32_e32 v201, 0xffff0000, v84
	v_lshlrev_b32_e32 v202, 16, v85
	v_and_b32_e32 v203, 0xffff0000, v85
	v_lshlrev_b32_e32 v204, 16, v116
	v_and_b32_e32 v205, 0xffff0000, v116
	v_lshlrev_b32_e32 v206, 16, v117
	v_and_b32_e32 v207, 0xffff0000, v117
	v_mul_f32_e32 v200, v214, v200
	v_mul_f32_e32 v201, v214, v201
	v_mul_f32_e32 v202, v214, v202
	v_mul_f32_e32 v203, v214, v203
	v_mul_f32_e32 v204, v215, v204
	v_mul_f32_e32 v205, v215, v205
	v_mul_f32_e32 v206, v215, v206
	v_mul_f32_e32 v207, v215, v207
	v_fmac_f32_e32 v40, v136, v200
	v_fmac_f32_e32 v41, v137, v201
	v_fmac_f32_e32 v42, v138, v202
	v_fmac_f32_e32 v43, v139, v203
	v_fmac_f32_e32 v40, v168, v204
	v_fmac_f32_e32 v41, v169, v205
	v_fmac_f32_e32 v42, v170, v206
	v_fmac_f32_e32 v43, v171, v207
	global_store_dwordx4 v192, v[40:43], s[18:19] offset:2048 nt
	v_lshlrev_b32_e32 v200, 16, v86
	v_and_b32_e32 v201, 0xffff0000, v86
	v_lshlrev_b32_e32 v202, 16, v87
	v_and_b32_e32 v203, 0xffff0000, v87
	v_lshlrev_b32_e32 v204, 16, v118
	v_and_b32_e32 v205, 0xffff0000, v118
	v_lshlrev_b32_e32 v206, 16, v119
	v_and_b32_e32 v207, 0xffff0000, v119
	v_mul_f32_e32 v200, v214, v200
	v_mul_f32_e32 v201, v214, v201
	v_mul_f32_e32 v202, v214, v202
	v_mul_f32_e32 v203, v214, v203
	v_mul_f32_e32 v204, v215, v204
	v_mul_f32_e32 v205, v215, v205
	v_mul_f32_e32 v206, v215, v206
	v_mul_f32_e32 v207, v215, v207
	v_fmac_f32_e32 v44, v140, v200
	v_fmac_f32_e32 v45, v141, v201
	v_fmac_f32_e32 v46, v142, v202
	v_fmac_f32_e32 v47, v143, v203
	v_fmac_f32_e32 v44, v172, v204
	v_fmac_f32_e32 v45, v173, v205
	v_fmac_f32_e32 v46, v174, v206
	v_fmac_f32_e32 v47, v175, v207
	global_store_dwordx4 v192, v[44:47], s[18:19] offset:3072 nt
	v_lshlrev_b32_e32 v200, 16, v88
	v_and_b32_e32 v201, 0xffff0000, v88
	v_lshlrev_b32_e32 v202, 16, v89
	v_and_b32_e32 v203, 0xffff0000, v89
	v_lshlrev_b32_e32 v204, 16, v120
	v_and_b32_e32 v205, 0xffff0000, v120
	v_lshlrev_b32_e32 v206, 16, v121
	v_and_b32_e32 v207, 0xffff0000, v121
	v_mul_f32_e32 v200, v214, v200
	v_mul_f32_e32 v201, v214, v201
	v_mul_f32_e32 v202, v214, v202
	v_mul_f32_e32 v203, v214, v203
	v_mul_f32_e32 v204, v215, v204
	v_mul_f32_e32 v205, v215, v205
	v_mul_f32_e32 v206, v215, v206
	v_mul_f32_e32 v207, v215, v207
	v_fmac_f32_e32 v48, v144, v200
	v_fmac_f32_e32 v49, v145, v201
	v_fmac_f32_e32 v50, v146, v202
	v_fmac_f32_e32 v51, v147, v203
	v_fmac_f32_e32 v48, v176, v204
	v_fmac_f32_e32 v49, v177, v205
	v_fmac_f32_e32 v50, v178, v206
	v_fmac_f32_e32 v51, v179, v207
	global_store_dwordx4 v193, v[48:51], s[18:19] offset:0 nt
	v_lshlrev_b32_e32 v200, 16, v90
	v_and_b32_e32 v201, 0xffff0000, v90
	v_lshlrev_b32_e32 v202, 16, v91
	v_and_b32_e32 v203, 0xffff0000, v91
	v_lshlrev_b32_e32 v204, 16, v122
	v_and_b32_e32 v205, 0xffff0000, v122
	v_lshlrev_b32_e32 v206, 16, v123
	v_and_b32_e32 v207, 0xffff0000, v123
	v_mul_f32_e32 v200, v214, v200
	v_mul_f32_e32 v201, v214, v201
	v_mul_f32_e32 v202, v214, v202
	v_mul_f32_e32 v203, v214, v203
	v_mul_f32_e32 v204, v215, v204
	v_mul_f32_e32 v205, v215, v205
	v_mul_f32_e32 v206, v215, v206
	v_mul_f32_e32 v207, v215, v207
	v_fmac_f32_e32 v52, v148, v200
	v_fmac_f32_e32 v53, v149, v201
	v_fmac_f32_e32 v54, v150, v202
	v_fmac_f32_e32 v55, v151, v203
	v_fmac_f32_e32 v52, v180, v204
	v_fmac_f32_e32 v53, v181, v205
	v_fmac_f32_e32 v54, v182, v206
	v_fmac_f32_e32 v55, v183, v207
	global_store_dwordx4 v193, v[52:55], s[18:19] offset:1024 nt
	v_lshlrev_b32_e32 v200, 16, v92
	v_and_b32_e32 v201, 0xffff0000, v92
	v_lshlrev_b32_e32 v202, 16, v93
	v_and_b32_e32 v203, 0xffff0000, v93
	v_lshlrev_b32_e32 v204, 16, v124
	v_and_b32_e32 v205, 0xffff0000, v124
	v_lshlrev_b32_e32 v206, 16, v125
	v_and_b32_e32 v207, 0xffff0000, v125
	v_mul_f32_e32 v200, v214, v200
	v_mul_f32_e32 v201, v214, v201
	v_mul_f32_e32 v202, v214, v202
	v_mul_f32_e32 v203, v214, v203
	v_mul_f32_e32 v204, v215, v204
; __device__ __forceinline__ float bf_lo(unsigned w) { return __uint_as_float(w << 16); }
; __device__ __forceinline__ float bf_hi(unsigned w) { return __uint_as_float(w & 0xffff0000u); }
; __global__ void __launch_bounds__(NWAVES * 64, 2) mk_fwd(Args args) {
;     ...
;                 float sy = 0.f;
; #pragma unroll
;                 for (int j = 0; j < 8; ++j) { const float a = bf_lo(yw[q][j].x), b = bf_hi(yw[q][j].x), c2 = bf_lo(yw[q][j].y), d = bf_hi(yw[q][j].y); sy += (a * a + b * b) + (c2 * c2 + d * d); }
;                 const float rsy = __builtin_amdgcn_rsqf(wave_sum(sy) * (1.f / DM) + EPS);
; #pragma unroll
;                 for (int j = 0; j < 8; ++j) { const int col = 4 * F.lane + 256 * j;
;                     const f32x4 y4 = (f32x4){bf_lo(yw[q][j].x), bf_hi(yw[q][j].x), bf_lo(yw[q][j].y), bf_hi(yw[q][j].y)};
;                     *(f32x4*)(args.out + (size_t)row * DM + col) = v[q][j] + PA[j] * (y4 * rsy); }
	v_mul_f32_e32 v205, v215, v205
	v_mul_f32_e32 v206, v215, v206
	v_mul_f32_e32 v207, v215, v207
	v_fmac_f32_e32 v56, v152, v200
	v_fmac_f32_e32 v57, v153, v201
	v_fmac_f32_e32 v58, v154, v202
	v_fmac_f32_e32 v59, v155, v203
	v_fmac_f32_e32 v56, v184, v204
	v_fmac_f32_e32 v57, v185, v205
	v_fmac_f32_e32 v58, v186, v206
	v_fmac_f32_e32 v59, v187, v207
	global_store_dwordx4 v193, v[56:59], s[18:19] offset:2048 nt
	v_lshlrev_b32_e32 v200, 16, v94
	v_and_b32_e32 v201, 0xffff0000, v94
	v_lshlrev_b32_e32 v202, 16, v95
	v_and_b32_e32 v203, 0xffff0000, v95
	v_lshlrev_b32_e32 v204, 16, v126
	v_and_b32_e32 v205, 0xffff0000, v126
	v_lshlrev_b32_e32 v206, 16, v127
	v_and_b32_e32 v207, 0xffff0000, v127
	v_mul_f32_e32 v200, v214, v200
	v_mul_f32_e32 v201, v214, v201
	v_mul_f32_e32 v202, v214, v202
	v_mul_f32_e32 v203, v214, v203
	v_mul_f32_e32 v204, v215, v204
	v_mul_f32_e32 v205, v215, v205
	v_mul_f32_e32 v206, v215, v206
	v_mul_f32_e32 v207, v215, v207
	v_fmac_f32_e32 v60, v156, v200
	v_fmac_f32_e32 v61, v157, v201
	v_fmac_f32_e32 v62, v158, v202
	v_fmac_f32_e32 v63, v159, v203
	v_fmac_f32_e32 v60, v188, v204
	v_fmac_f32_e32 v61, v189, v205
	v_fmac_f32_e32 v62, v190, v206
	v_fmac_f32_e32 v63, v191, v207
	global_store_dwordx4 v193, v[60:63], s[18:19] offset:3072 nt
	s_add_u32 s18, s18, 0x2000
	s_addc_u32 s19, s19, 0
	global_load_dwordx4 v[32:35], v192, s[14:15] offset:0
	global_load_dwordx4 v[36:39], v192, s[14:15] offset:1024
	global_load_dwordx4 v[40:43], v192, s[14:15] offset:2048
	global_load_dwordx4 v[44:47], v192, s[14:15] offset:3072
	global_load_dwordx4 v[48:51], v193, s[14:15] offset:0
	global_load_dwordx4 v[52:55], v193, s[14:15] offset:1024
	global_load_dwordx4 v[56:59], v193, s[14:15] offset:2048
	global_load_dwordx4 v[60:63], v193, s[14:15] offset:3072
	global_load_dwordx2 v[80:81], v194, s[16:17] offset:0
	global_load_dwordx2 v[82:83], v194, s[16:17] offset:512
	global_load_dwordx2 v[84:85], v194, s[16:17] offset:1024
	global_load_dwordx2 v[86:87], v194, s[16:17] offset:1536
	global_load_dwordx2 v[88:89], v194, s[16:17] offset:2048
	global_load_dwordx2 v[90:91], v194, s[16:17] offset:2560
	global_load_dwordx2 v[92:93], v194, s[16:17] offset:3072
	global_load_dwordx2 v[94:95], v194, s[16:17] offset:3584
	global_load_dwordx2 v[112:113], v194, s[22:23] offset:0
	global_load_dwordx2 v[114:115], v194, s[22:23] offset:512
	global_load_dwordx2 v[116:117], v194, s[22:23] offset:1024
	global_load_dwordx2 v[118:119], v194, s[22:23] offset:1536
	global_load_dwordx2 v[120:121], v194, s[22:23] offset:2048
	global_load_dwordx2 v[122:123], v194, s[22:23] offset:2560
	global_load_dwordx2 v[124:125], v194, s[22:23] offset:3072
	global_load_dwordx2 v[126:127], v194, s[22:23] offset:3584
	s_add_u32 s14, s14, 0x2000
	s_addc_u32 s15, s15, 0
	s_add_u32 s16, s16, 0x1000
	s_addc_u32 s17, s17, 0
	s_add_u32 s22, s22, 0x1000
	s_addc_u32 s23, s23, 0
	s_waitcnt vmcnt(32)
	v_lshlrev_b32_e32 v200, 16, v64
	v_and_b32_e32 v201, 0xffff0000, v64
	v_lshlrev_b32_e32 v202, 16, v65
	v_and_b32_e32 v203, 0xffff0000, v65
	v_mul_f32_e32 v208, v200, v200
	v_mul_f32_e32 v209, v201, v201
	v_fmac_f32_e32 v208, v202, v202
	v_fmac_f32_e32 v209, v203, v203
	v_lshlrev_b32_e32 v204, 16, v96
	v_and_b32_e32 v205, 0xffff0000, v96
	v_lshlrev_b32_e32 v206, 16, v97
	v_and_b32_e32 v207, 0xffff0000, v97
	v_mul_f32_e32 v210, v204, v204
	v_mul_f32_e32 v211, v205, v205
	v_fmac_f32_e32 v210, v206, v206
	v_fmac_f32_e32 v211, v207, v207
	v_lshlrev_b32_e32 v200, 16, v66
	v_and_b32_e32 v201, 0xffff0000, v66
	v_lshlrev_b32_e32 v202, 16, v67
	v_and_b32_e32 v203, 0xffff0000, v67
	v_fmac_f32_e32 v208, v200, v200
	v_fmac_f32_e32 v209, v201, v201
	v_fmac_f32_e32 v208, v202, v202
	v_fmac_f32_e32 v209, v203, v203
	v_lshlrev_b32_e32 v204, 16, v98
	v_and_b32_e32 v205, 0xffff0000, v98
	v_lshlrev_b32_e32 v206, 16, v99
	v_and_b32_e32 v207, 0xffff0000, v99
	v_fmac_f32_e32 v210, v204, v204
	v_fmac_f32_e32 v211, v205, v205
	v_fmac_f32_e32 v210, v206, v206
	v_fmac_f32_e32 v211, v207, v207
	v_lshlrev_b32_e32 v200, 16, v68
	v_and_b32_e32 v201, 0xffff0000, v68
	v_lshlrev_b32_e32 v202, 16, v69
	v_and_b32_e32 v203, 0xffff0000, v69
	v_fmac_f32_e32 v208, v200, v200
	v_fmac_f32_e32 v209, v201, v201
	v_fmac_f32_e32 v208, v202, v202
	v_fmac_f32_e32 v209, v203, v203
	v_lshlrev_b32_e32 v204, 16, v100
	v_and_b32_e32 v205, 0xffff0000, v100
	v_lshlrev_b32_e32 v206, 16, v101
	v_and_b32_e32 v207, 0xffff0000, v101
	v_fmac_f32_e32 v210, v204, v204
	v_fmac_f32_e32 v211, v205, v205
	v_fmac_f32_e32 v210, v206, v206
	v_fmac_f32_e32 v211, v207, v207
	v_lshlrev_b32_e32 v200, 16, v70
	v_and_b32_e32 v201, 0xffff0000, v70
	v_lshlrev_b32_e32 v202, 16, v71
	v_and_b32_e32 v203, 0xffff0000, v71
	v_fmac_f32_e32 v208, v200, v200
	v_fmac_f32_e32 v209, v201, v201
	v_fmac_f32_e32 v208, v202, v202
	v_fmac_f32_e32 v209, v203, v203
	v_lshlrev_b32_e32 v204, 16, v102
	v_and_b32_e32 v205, 0xffff0000, v102
	v_lshlrev_b32_e32 v206, 16, v103
	v_and_b32_e32 v207, 0xffff0000, v103
	v_fmac_f32_e32 v210, v204, v204
	v_fmac_f32_e32 v211, v205, v205
	v_fmac_f32_e32 v210, v206, v206
	v_fmac_f32_e32 v211, v207, v207
	v_lshlrev_b32_e32 v200, 16, v72
	v_and_b32_e32 v201, 0xffff0000, v72
	v_lshlrev_b32_e32 v202, 16, v73
	v_and_b32_e32 v203, 0xffff0000, v73
	v_fmac_f32_e32 v208, v200, v200
	v_fmac_f32_e32 v209, v201, v201
	v_fmac_f32_e32 v208, v202, v202
	v_fmac_f32_e32 v209, v203, v203
	v_lshlrev_b32_e32 v204, 16, v104
	v_and_b32_e32 v205, 0xffff0000, v104
	v_lshlrev_b32_e32 v206, 16, v105
	v_and_b32_e32 v207, 0xffff0000, v105
	v_fmac_f32_e32 v210, v204, v204
	v_fmac_f32_e32 v211, v205, v205
	v_fmac_f32_e32 v210, v206, v206
	v_fmac_f32_e32 v211, v207, v207
	v_lshlrev_b32_e32 v200, 16, v74
; __device__ __forceinline__ float bf_lo(unsigned w) { return __uint_as_float(w << 16); }
; __device__ __forceinline__ float bf_hi(unsigned w) { return __uint_as_float(w & 0xffff0000u); }
; __global__ void __launch_bounds__(NWAVES * 64, 2) mk_fwd(Args args) {
;     ...
;                 float sy = 0.f;
; #pragma unroll
;                 for (int j = 0; j < 8; ++j) { const float a = bf_lo(yw[q][j].x), b = bf_hi(yw[q][j].x), c2 = bf_lo(yw[q][j].y), d = bf_hi(yw[q][j].y); sy += (a * a + b * b) + (c2 * c2 + d * d); }
;                 const float rsy = __builtin_amdgcn_rsqf(wave_sum(sy) * (1.f / DM) + EPS);
; #pragma unroll
;                 for (int j = 0; j < 8; ++j) { const int col = 4 * F.lane + 256 * j;
;                     const f32x4 y4 = (f32x4){bf_lo(yw[q][j].x), bf_hi(yw[q][j].x), bf_lo(yw[q][j].y), bf_hi(yw[q][j].y)};
;                     *(f32x4*)(args.out + (size_t)row * DM + col) = v[q][j] + PA[j] * (y4 * rsy); }
	v_and_b32_e32 v201, 0xffff0000, v74
	v_lshlrev_b32_e32 v202, 16, v75
	v_and_b32_e32 v203, 0xffff0000, v75
	v_fmac_f32_e32 v208, v200, v200
	v_fmac_f32_e32 v209, v201, v201
	v_fmac_f32_e32 v208, v202, v202
	v_fmac_f32_e32 v209, v203, v203
	v_lshlrev_b32_e32 v204, 16, v106
	v_and_b32_e32 v205, 0xffff0000, v106
	v_lshlrev_b32_e32 v206, 16, v107
	v_and_b32_e32 v207, 0xffff0000, v107
	v_fmac_f32_e32 v210, v204, v204
	v_fmac_f32_e32 v211, v205, v205
	v_fmac_f32_e32 v210, v206, v206
	v_fmac_f32_e32 v211, v207, v207
	v_lshlrev_b32_e32 v200, 16, v76
	v_and_b32_e32 v201, 0xffff0000, v76
	v_lshlrev_b32_e32 v202, 16, v77
	v_and_b32_e32 v203, 0xffff0000, v77
	v_fmac_f32_e32 v208, v200, v200
	v_fmac_f32_e32 v209, v201, v201
	v_fmac_f32_e32 v208, v202, v202
	v_fmac_f32_e32 v209, v203, v203
	v_lshlrev_b32_e32 v204, 16, v108
	v_and_b32_e32 v205, 0xffff0000, v108
	v_lshlrev_b32_e32 v206, 16, v109
	v_and_b32_e32 v207, 0xffff0000, v109
	v_fmac_f32_e32 v210, v204, v204
	v_fmac_f32_e32 v211, v205, v205
	v_fmac_f32_e32 v210, v206, v206
	v_fmac_f32_e32 v211, v207, v207
	v_lshlrev_b32_e32 v200, 16, v78
	v_and_b32_e32 v201, 0xffff0000, v78
	v_lshlrev_b32_e32 v202, 16, v79
	v_and_b32_e32 v203, 0xffff0000, v79
	v_fmac_f32_e32 v208, v200, v200
	v_fmac_f32_e32 v209, v201, v201
	v_fmac_f32_e32 v208, v202, v202
	v_fmac_f32_e32 v209, v203, v203
	v_lshlrev_b32_e32 v204, 16, v110
	v_and_b32_e32 v205, 0xffff0000, v110
	v_lshlrev_b32_e32 v206, 16, v111
	v_and_b32_e32 v207, 0xffff0000, v111
	v_fmac_f32_e32 v210, v204, v204
	v_fmac_f32_e32 v211, v205, v205
	v_fmac_f32_e32 v210, v206, v206
	v_fmac_f32_e32 v211, v207, v207
	v_add_f32_e32 v208, v208, v209
	v_add_f32_e32 v210, v210, v211
	s_nop 0
	v_add_f32_dpp v212, v208, v208 quad_perm:[1,0,3,2] row_mask:0xf bank_mask:0xf
	v_add_f32_dpp v213, v210, v210 quad_perm:[1,0,3,2] row_mask:0xf bank_mask:0xf
	s_nop 0
	v_add_f32_dpp v212, v212, v212 quad_perm:[2,3,0,1] row_mask:0xf bank_mask:0xf
	v_add_f32_dpp v213, v213, v213 quad_perm:[2,3,0,1] row_mask:0xf bank_mask:0xf
	s_nop 0
	v_add_f32_dpp v212, v212, v212 row_half_mirror row_mask:0xf bank_mask:0xf
	v_add_f32_dpp v213, v213, v213 row_half_mirror row_mask:0xf bank_mask:0xf
	s_nop 0
	v_add_f32_dpp v212, v212, v212 row_mirror row_mask:0xf bank_mask:0xf
	v_add_f32_dpp v213, v213, v213 row_mirror row_mask:0xf bank_mask:0xf
	s_nop 0
	v_readlane_b32 s4, v212, 0
	v_readlane_b32 s5, v212, 16
	v_readlane_b32 s6, v212, 32
	v_readlane_b32 s7, v212, 48
	v_readlane_b32 s24, v213, 0
	v_readlane_b32 s25, v213, 16
	v_readlane_b32 s26, v213, 32
	v_readlane_b32 s27, v213, 48
	s_nop 1
	v_mov_b32_e32 v214, s4
	v_mov_b32_e32 v215, s24
	v_add_f32_e32 v214, s5, v214
	v_add_f32_e32 v215, s25, v215
	v_add_f32_e32 v214, s6, v214
	v_add_f32_e32 v215, s26, v215
	v_add_f32_e32 v214, s7, v214
	v_add_f32_e32 v215, s27, v215
	v_fmamk_f32 v214, v214, 0x3a000000, v195
	v_fmamk_f32 v215, v215, 0x3a000000, v195
	v_rsq_f32_e32 v214, v214
	v_rsq_f32_e32 v215, v215
	s_nop 0
	v_lshlrev_b32_e32 v200, 16, v64
	v_and_b32_e32 v201, 0xffff0000, v64
	v_lshlrev_b32_e32 v202, 16, v65
	v_and_b32_e32 v203, 0xffff0000, v65
	v_lshlrev_b32_e32 v204, 16, v96
	v_and_b32_e32 v205, 0xffff0000, v96
	v_lshlrev_b32_e32 v206, 16, v97
	v_and_b32_e32 v207, 0xffff0000, v97
	v_mul_f32_e32 v200, v214, v200
	v_mul_f32_e32 v201, v214, v201
	v_mul_f32_e32 v202, v214, v202
	v_mul_f32_e32 v203, v214, v203
	v_mul_f32_e32 v204, v215, v204
	v_mul_f32_e32 v205, v215, v205
	v_mul_f32_e32 v206, v215, v206
	v_mul_f32_e32 v207, v215, v207
	v_fmac_f32_e32 v0, v128, v200
	v_fmac_f32_e32 v1, v129, v201
	v_fmac_f32_e32 v2, v130, v202
	v_fmac_f32_e32 v3, v131, v203
	v_fmac_f32_e32 v0, v160, v204
	v_fmac_f32_e32 v1, v161, v205
	v_fmac_f32_e32 v2, v162, v206
	v_fmac_f32_e32 v3, v163, v207
	global_store_dwordx4 v192, v[0:3], s[18:19] offset:0 nt
	v_lshlrev_b32_e32 v200, 16, v66
	v_and_b32_e32 v201, 0xffff0000, v66
	v_lshlrev_b32_e32 v202, 16, v67
	v_and_b32_e32 v203, 0xffff0000, v67
	v_lshlrev_b32_e32 v204, 16, v98
	v_and_b32_e32 v205, 0xffff0000, v98
	v_lshlrev_b32_e32 v206, 16, v99
	v_and_b32_e32 v207, 0xffff0000, v99
	v_mul_f32_e32 v200, v214, v200
	v_mul_f32_e32 v201, v214, v201
	v_mul_f32_e32 v202, v214, v202
	v_mul_f32_e32 v203, v214, v203
	v_mul_f32_e32 v204, v215, v204
	v_mul_f32_e32 v205, v215, v205
	v_mul_f32_e32 v206, v215, v206
	v_mul_f32_e32 v207, v215, v207
	v_fmac_f32_e32 v4, v132, v200
	v_fmac_f32_e32 v5, v133, v201
	v_fmac_f32_e32 v6, v134, v202
	v_fmac_f32_e32 v7, v135, v203
	v_fmac_f32_e32 v4, v164, v204
	v_fmac_f32_e32 v5, v165, v205
	v_fmac_f32_e32 v6, v166, v206
	v_fmac_f32_e32 v7, v167, v207
	global_store_dwordx4 v192, v[4:7], s[18:19] offset:1024 nt
	v_lshlrev_b32_e32 v200, 16, v68
	v_and_b32_e32 v201, 0xffff0000, v68
	v_lshlrev_b32_e32 v202, 16, v69
	v_and_b32_e32 v203, 0xffff0000, v69
	v_lshlrev_b32_e32 v204, 16, v100
	v_and_b32_e32 v205, 0xffff0000, v100
	v_lshlrev_b32_e32 v206, 16, v101
	v_and_b32_e32 v207, 0xffff0000, v101
	v_mul_f32_e32 v200, v214, v200
	v_mul_f32_e32 v201, v214, v201
	v_mul_f32_e32 v202, v214, v202
	v_mul_f32_e32 v203, v214, v203
	v_mul_f32_e32 v204, v215, v204
	v_mul_f32_e32 v205, v215, v205
	v_mul_f32_e32 v206, v215, v206
	v_mul_f32_e32 v207, v215, v207
	v_fmac_f32_e32 v8, v136, v200
	v_fmac_f32_e32 v9, v137, v201
	v_fmac_f32_e32 v10, v138, v202
	v_fmac_f32_e32 v11, v139, v203
	v_fmac_f32_e32 v8, v168, v204
	v_fmac_f32_e32 v9, v169, v205
	v_fmac_f32_e32 v10, v170, v206
	v_fmac_f32_e32 v11, v171, v207
	global_store_dwordx4 v192, v[8:11], s[18:19] offset:2048 nt
	v_lshlrev_b32_e32 v200, 16, v70
	v_and_b32_e32 v201, 0xffff0000, v70
	v_lshlrev_b32_e32 v202, 16, v71
	v_and_b32_e32 v203, 0xffff0000, v71
; __device__ __forceinline__ float bf_lo(unsigned w) { return __uint_as_float(w << 16); }
; __device__ __forceinline__ float bf_hi(unsigned w) { return __uint_as_float(w & 0xffff0000u); }
; __global__ void __launch_bounds__(NWAVES * 64, 2) mk_fwd(Args args) {
;     ...
;                 float sy = 0.f;
; #pragma unroll
;                 for (int j = 0; j < 8; ++j) { const float a = bf_lo(yw[q][j].x), b = bf_hi(yw[q][j].x), c2 = bf_lo(yw[q][j].y), d = bf_hi(yw[q][j].y); sy += (a * a + b * b) + (c2 * c2 + d * d); }
;                 const float rsy = __builtin_amdgcn_rsqf(wave_sum(sy) * (1.f / DM) + EPS);
; #pragma unroll
;                 for (int j = 0; j < 8; ++j) { const int col = 4 * F.lane + 256 * j;
;                     const f32x4 y4 = (f32x4){bf_lo(yw[q][j].x), bf_hi(yw[q][j].x), bf_lo(yw[q][j].y), bf_hi(yw[q][j].y)};
;                     *(f32x4*)(args.out + (size_t)row * DM + col) = v[q][j] + PA[j] * (y4 * rsy); }
	v_lshlrev_b32_e32 v204, 16, v102
	v_and_b32_e32 v205, 0xffff0000, v102
	v_lshlrev_b32_e32 v206, 16, v103
	v_and_b32_e32 v207, 0xffff0000, v103
	v_mul_f32_e32 v200, v214, v200
	v_mul_f32_e32 v201, v214, v201
	v_mul_f32_e32 v202, v214, v202
	v_mul_f32_e32 v203, v214, v203
	v_mul_f32_e32 v204, v215, v204
	v_mul_f32_e32 v205, v215, v205
	v_mul_f32_e32 v206, v215, v206
	v_mul_f32_e32 v207, v215, v207
	v_fmac_f32_e32 v12, v140, v200
	v_fmac_f32_e32 v13, v141, v201
	v_fmac_f32_e32 v14, v142, v202
	v_fmac_f32_e32 v15, v143, v203
	v_fmac_f32_e32 v12, v172, v204
	v_fmac_f32_e32 v13, v173, v205
	v_fmac_f32_e32 v14, v174, v206
	v_fmac_f32_e32 v15, v175, v207
	global_store_dwordx4 v192, v[12:15], s[18:19] offset:3072 nt
	v_lshlrev_b32_e32 v200, 16, v72
	v_and_b32_e32 v201, 0xffff0000, v72
	v_lshlrev_b32_e32 v202, 16, v73
	v_and_b32_e32 v203, 0xffff0000, v73
	v_lshlrev_b32_e32 v204, 16, v104
	v_and_b32_e32 v205, 0xffff0000, v104
	v_lshlrev_b32_e32 v206, 16, v105
	v_and_b32_e32 v207, 0xffff0000, v105
	v_mul_f32_e32 v200, v214, v200
	v_mul_f32_e32 v201, v214, v201
	v_mul_f32_e32 v202, v214, v202
	v_mul_f32_e32 v203, v214, v203
	v_mul_f32_e32 v204, v215, v204
	v_mul_f32_e32 v205, v215, v205
	v_mul_f32_e32 v206, v215, v206
	v_mul_f32_e32 v207, v215, v207
	v_fmac_f32_e32 v16, v144, v200
	v_fmac_f32_e32 v17, v145, v201
	v_fmac_f32_e32 v18, v146, v202
	v_fmac_f32_e32 v19, v147, v203
	v_fmac_f32_e32 v16, v176, v204
	v_fmac_f32_e32 v17, v177, v205
	v_fmac_f32_e32 v18, v178, v206
	v_fmac_f32_e32 v19, v179, v207
	global_store_dwordx4 v193, v[16:19], s[18:19] offset:0 nt
	v_lshlrev_b32_e32 v200, 16, v74
	v_and_b32_e32 v201, 0xffff0000, v74
	v_lshlrev_b32_e32 v202, 16, v75
	v_and_b32_e32 v203, 0xffff0000, v75
	v_lshlrev_b32_e32 v204, 16, v106
	v_and_b32_e32 v205, 0xffff0000, v106
	v_lshlrev_b32_e32 v206, 16, v107
	v_and_b32_e32 v207, 0xffff0000, v107
	v_mul_f32_e32 v200, v214, v200
	v_mul_f32_e32 v201, v214, v201
	v_mul_f32_e32 v202, v214, v202
	v_mul_f32_e32 v203, v214, v203
	v_mul_f32_e32 v204, v215, v204
	v_mul_f32_e32 v205, v215, v205
	v_mul_f32_e32 v206, v215, v206
	v_mul_f32_e32 v207, v215, v207
	v_fmac_f32_e32 v20, v148, v200
	v_fmac_f32_e32 v21, v149, v201
	v_fmac_f32_e32 v22, v150, v202
	v_fmac_f32_e32 v23, v151, v203
	v_fmac_f32_e32 v20, v180, v204
	v_fmac_f32_e32 v21, v181, v205
	v_fmac_f32_e32 v22, v182, v206
	v_fmac_f32_e32 v23, v183, v207
	global_store_dwordx4 v193, v[20:23], s[18:19] offset:1024 nt
	v_lshlrev_b32_e32 v200, 16, v76
	v_and_b32_e32 v201, 0xffff0000, v76
	v_lshlrev_b32_e32 v202, 16, v77
	v_and_b32_e32 v203, 0xffff0000, v77
	v_lshlrev_b32_e32 v204, 16, v108
	v_and_b32_e32 v205, 0xffff0000, v108
	v_lshlrev_b32_e32 v206, 16, v109
	v_and_b32_e32 v207, 0xffff0000, v109
	v_mul_f32_e32 v200, v214, v200
	v_mul_f32_e32 v201, v214, v201
	v_mul_f32_e32 v202, v214, v202
	v_mul_f32_e32 v203, v214, v203
	v_mul_f32_e32 v204, v215, v204
	v_mul_f32_e32 v205, v215, v205
	v_mul_f32_e32 v206, v215, v206
	v_mul_f32_e32 v207, v215, v207
	v_fmac_f32_e32 v24, v152, v200
	v_fmac_f32_e32 v25, v153, v201
	v_fmac_f32_e32 v26, v154, v202
	v_fmac_f32_e32 v27, v155, v203
	v_fmac_f32_e32 v24, v184, v204
	v_fmac_f32_e32 v25, v185, v205
	v_fmac_f32_e32 v26, v186, v206
	v_fmac_f32_e32 v27, v187, v207
	global_store_dwordx4 v193, v[24:27], s[18:19] offset:2048 nt
	v_lshlrev_b32_e32 v200, 16, v78
	v_and_b32_e32 v201, 0xffff0000, v78
	v_lshlrev_b32_e32 v202, 16, v79
	v_and_b32_e32 v203, 0xffff0000, v79
	v_lshlrev_b32_e32 v204, 16, v110
	v_and_b32_e32 v205, 0xffff0000, v110
	v_lshlrev_b32_e32 v206, 16, v111
	v_and_b32_e32 v207, 0xffff0000, v111
	v_mul_f32_e32 v200, v214, v200
	v_mul_f32_e32 v201, v214, v201
	v_mul_f32_e32 v202, v214, v202
	v_mul_f32_e32 v203, v214, v203
	v_mul_f32_e32 v204, v215, v204
	v_mul_f32_e32 v205, v215, v205
	v_mul_f32_e32 v206, v215, v206
	v_mul_f32_e32 v207, v215, v207
	v_fmac_f32_e32 v28, v156, v200
	v_fmac_f32_e32 v29, v157, v201
	v_fmac_f32_e32 v30, v158, v202
	v_fmac_f32_e32 v31, v159, v203
	v_fmac_f32_e32 v28, v188, v204
	v_fmac_f32_e32 v29, v189, v205
	v_fmac_f32_e32 v30, v190, v206
	v_fmac_f32_e32 v31, v191, v207
	global_store_dwordx4 v193, v[28:31], s[18:19] offset:3072 nt
	s_add_u32 s18, s18, 0x2000
	s_addc_u32 s19, s19, 0
	global_load_dwordx4 v[0:3], v192, s[14:15] offset:0
	global_load_dwordx4 v[4:7], v192, s[14:15] offset:1024
	global_load_dwordx4 v[8:11], v192, s[14:15] offset:2048
	global_load_dwordx4 v[12:15], v192, s[14:15] offset:3072
	global_load_dwordx4 v[16:19], v193, s[14:15] offset:0
	global_load_dwordx4 v[20:23], v193, s[14:15] offset:1024
	global_load_dwordx4 v[24:27], v193, s[14:15] offset:2048
	global_load_dwordx4 v[28:31], v193, s[14:15] offset:3072
	global_load_dwordx2 v[64:65], v194, s[16:17] offset:0
	global_load_dwordx2 v[66:67], v194, s[16:17] offset:512
	global_load_dwordx2 v[68:69], v194, s[16:17] offset:1024
	global_load_dwordx2 v[70:71], v194, s[16:17] offset:1536
	global_load_dwordx2 v[72:73], v194, s[16:17] offset:2048
	global_load_dwordx2 v[74:75], v194, s[16:17] offset:2560
	global_load_dwordx2 v[76:77], v194, s[16:17] offset:3072
	global_load_dwordx2 v[78:79], v194, s[16:17] offset:3584
	global_load_dwordx2 v[96:97], v194, s[22:23] offset:0
	global_load_dwordx2 v[98:99], v194, s[22:23] offset:512
	global_load_dwordx2 v[100:101], v194, s[22:23] offset:1024
	global_load_dwordx2 v[102:103], v194, s[22:23] offset:1536
	global_load_dwordx2 v[104:105], v194, s[22:23] offset:2048
	global_load_dwordx2 v[106:107], v194, s[22:23] offset:2560
	global_load_dwordx2 v[108:109], v194, s[22:23] offset:3072
	global_load_dwordx2 v[110:111], v194, s[22:23] offset:3584
	s_add_u32 s14, s14, 0x2000
	s_addc_u32 s15, s15, 0
	s_add_u32 s16, s16, 0x1000
	s_addc_u32 s17, s17, 0
	s_add_u32 s22, s22, 0x1000
	s_addc_u32 s23, s23, 0
	s_waitcnt vmcnt(32)
; __device__ __forceinline__ float bf_lo(unsigned w) { return __uint_as_float(w << 16); }
; __device__ __forceinline__ float bf_hi(unsigned w) { return __uint_as_float(w & 0xffff0000u); }
; __global__ void __launch_bounds__(NWAVES * 64, 2) mk_fwd(Args args) {
;     ...
;                 float sy = 0.f;
; #pragma unroll
;                 for (int j = 0; j < 8; ++j) { const float a = bf_lo(yw[q][j].x), b = bf_hi(yw[q][j].x), c2 = bf_lo(yw[q][j].y), d = bf_hi(yw[q][j].y); sy += (a * a + b * b) + (c2 * c2 + d * d); }
;                 const float rsy = __builtin_amdgcn_rsqf(wave_sum(sy) * (1.f / DM) + EPS);
	v_lshlrev_b32_e32 v200, 16, v80
	v_and_b32_e32 v201, 0xffff0000, v80
	v_lshlrev_b32_e32 v202, 16, v81
	v_and_b32_e32 v203, 0xffff0000, v81
	v_mul_f32_e32 v208, v200, v200
	v_mul_f32_e32 v209, v201, v201
	v_fmac_f32_e32 v208, v202, v202
	v_fmac_f32_e32 v209, v203, v203
	v_lshlrev_b32_e32 v204, 16, v112
	v_and_b32_e32 v205, 0xffff0000, v112
	v_lshlrev_b32_e32 v206, 16, v113
	v_and_b32_e32 v207, 0xffff0000, v113
	v_mul_f32_e32 v210, v204, v204
	v_mul_f32_e32 v211, v205, v205
	v_fmac_f32_e32 v210, v206, v206
	v_fmac_f32_e32 v211, v207, v207
	v_lshlrev_b32_e32 v200, 16, v82
	v_and_b32_e32 v201, 0xffff0000, v82
	v_lshlrev_b32_e32 v202, 16, v83
	v_and_b32_e32 v203, 0xffff0000, v83
	v_fmac_f32_e32 v208, v200, v200
	v_fmac_f32_e32 v209, v201, v201
	v_fmac_f32_e32 v208, v202, v202
	v_fmac_f32_e32 v209, v203, v203
	v_lshlrev_b32_e32 v204, 16, v114
	v_and_b32_e32 v205, 0xffff0000, v114
	v_lshlrev_b32_e32 v206, 16, v115
	v_and_b32_e32 v207, 0xffff0000, v115
	v_fmac_f32_e32 v210, v204, v204
	v_fmac_f32_e32 v211, v205, v205
	v_fmac_f32_e32 v210, v206, v206
	v_fmac_f32_e32 v211, v207, v207
	v_lshlrev_b32_e32 v200, 16, v84
	v_and_b32_e32 v201, 0xffff0000, v84
	v_lshlrev_b32_e32 v202, 16, v85
	v_and_b32_e32 v203, 0xffff0000, v85
	v_fmac_f32_e32 v208, v200, v200
	v_fmac_f32_e32 v209, v201, v201
	v_fmac_f32_e32 v208, v202, v202
	v_fmac_f32_e32 v209, v203, v203
	v_lshlrev_b32_e32 v204, 16, v116
	v_and_b32_e32 v205, 0xffff0000, v116
	v_lshlrev_b32_e32 v206, 16, v117
	v_and_b32_e32 v207, 0xffff0000, v117
	v_fmac_f32_e32 v210, v204, v204
	v_fmac_f32_e32 v211, v205, v205
	v_fmac_f32_e32 v210, v206, v206
	v_fmac_f32_e32 v211, v207, v207
	v_lshlrev_b32_e32 v200, 16, v86
	v_and_b32_e32 v201, 0xffff0000, v86
	v_lshlrev_b32_e32 v202, 16, v87
	v_and_b32_e32 v203, 0xffff0000, v87
	v_fmac_f32_e32 v208, v200, v200
	v_fmac_f32_e32 v209, v201, v201
	v_fmac_f32_e32 v208, v202, v202
	v_fmac_f32_e32 v209, v203, v203
	v_lshlrev_b32_e32 v204, 16, v118
	v_and_b32_e32 v205, 0xffff0000, v118
	v_lshlrev_b32_e32 v206, 16, v119
	v_and_b32_e32 v207, 0xffff0000, v119
	v_fmac_f32_e32 v210, v204, v204
	v_fmac_f32_e32 v211, v205, v205
	v_fmac_f32_e32 v210, v206, v206
	v_fmac_f32_e32 v211, v207, v207
	v_lshlrev_b32_e32 v200, 16, v88
	v_and_b32_e32 v201, 0xffff0000, v88
	v_lshlrev_b32_e32 v202, 16, v89
	v_and_b32_e32 v203, 0xffff0000, v89
	v_fmac_f32_e32 v208, v200, v200
	v_fmac_f32_e32 v209, v201, v201
	v_fmac_f32_e32 v208, v202, v202
	v_fmac_f32_e32 v209, v203, v203
	v_lshlrev_b32_e32 v204, 16, v120
	v_and_b32_e32 v205, 0xffff0000, v120
	v_lshlrev_b32_e32 v206, 16, v121
	v_and_b32_e32 v207, 0xffff0000, v121
	v_fmac_f32_e32 v210, v204, v204
	v_fmac_f32_e32 v211, v205, v205
	v_fmac_f32_e32 v210, v206, v206
	v_fmac_f32_e32 v211, v207, v207
	v_lshlrev_b32_e32 v200, 16, v90
	v_and_b32_e32 v201, 0xffff0000, v90
	v_lshlrev_b32_e32 v202, 16, v91
	v_and_b32_e32 v203, 0xffff0000, v91
	v_fmac_f32_e32 v208, v200, v200
	v_fmac_f32_e32 v209, v201, v201
	v_fmac_f32_e32 v208, v202, v202
	v_fmac_f32_e32 v209, v203, v203
	v_lshlrev_b32_e32 v204, 16, v122
	v_and_b32_e32 v205, 0xffff0000, v122
	v_lshlrev_b32_e32 v206, 16, v123
	v_and_b32_e32 v207, 0xffff0000, v123
	v_fmac_f32_e32 v210, v204, v204
	v_fmac_f32_e32 v211, v205, v205
	v_fmac_f32_e32 v210, v206, v206
	v_fmac_f32_e32 v211, v207, v207
	v_lshlrev_b32_e32 v200, 16, v92
	v_and_b32_e32 v201, 0xffff0000, v92
	v_lshlrev_b32_e32 v202, 16, v93
	v_and_b32_e32 v203, 0xffff0000, v93
	v_fmac_f32_e32 v208, v200, v200
	v_fmac_f32_e32 v209, v201, v201
	v_fmac_f32_e32 v208, v202, v202
	v_fmac_f32_e32 v209, v203, v203
	v_lshlrev_b32_e32 v204, 16, v124
	v_and_b32_e32 v205, 0xffff0000, v124
	v_lshlrev_b32_e32 v206, 16, v125
	v_and_b32_e32 v207, 0xffff0000, v125
	v_fmac_f32_e32 v210, v204, v204
	v_fmac_f32_e32 v211, v205, v205
	v_fmac_f32_e32 v210, v206, v206
	v_fmac_f32_e32 v211, v207, v207
	v_lshlrev_b32_e32 v200, 16, v94
	v_and_b32_e32 v201, 0xffff0000, v94
	v_lshlrev_b32_e32 v202, 16, v95
	v_and_b32_e32 v203, 0xffff0000, v95
	v_fmac_f32_e32 v208, v200, v200
	v_fmac_f32_e32 v209, v201, v201
	v_fmac_f32_e32 v208, v202, v202
	v_fmac_f32_e32 v209, v203, v203
	v_lshlrev_b32_e32 v204, 16, v126
	v_and_b32_e32 v205, 0xffff0000, v126
	v_lshlrev_b32_e32 v206, 16, v127
	v_and_b32_e32 v207, 0xffff0000, v127
	v_fmac_f32_e32 v210, v204, v204
	v_fmac_f32_e32 v211, v205, v205
	v_fmac_f32_e32 v210, v206, v206
	v_fmac_f32_e32 v211, v207, v207
	v_add_f32_e32 v208, v208, v209
	v_add_f32_e32 v210, v210, v211
	s_nop 0
	v_add_f32_dpp v212, v208, v208 quad_perm:[1,0,3,2] row_mask:0xf bank_mask:0xf
	v_add_f32_dpp v213, v210, v210 quad_perm:[1,0,3,2] row_mask:0xf bank_mask:0xf
	s_nop 0
	v_add_f32_dpp v212, v212, v212 quad_perm:[2,3,0,1] row_mask:0xf bank_mask:0xf
	v_add_f32_dpp v213, v213, v213 quad_perm:[2,3,0,1] row_mask:0xf bank_mask:0xf
	s_nop 0
	v_add_f32_dpp v212, v212, v212 row_half_mirror row_mask:0xf bank_mask:0xf
	v_add_f32_dpp v213, v213, v213 row_half_mirror row_mask:0xf bank_mask:0xf
	s_nop 0
	v_add_f32_dpp v212, v212, v212 row_mirror row_mask:0xf bank_mask:0xf
	v_add_f32_dpp v213, v213, v213 row_mirror row_mask:0xf bank_mask:0xf
	s_nop 0
	v_readlane_b32 s4, v212, 0
	v_readlane_b32 s5, v212, 16
	v_readlane_b32 s6, v212, 32
	v_readlane_b32 s7, v212, 48
	v_readlane_b32 s24, v213, 0
	v_readlane_b32 s25, v213, 16
	v_readlane_b32 s26, v213, 32
	v_readlane_b32 s27, v213, 48
	s_nop 1
	v_mov_b32_e32 v214, s4
	v_mov_b32_e32 v215, s24
	v_add_f32_e32 v214, s5, v214
	v_add_f32_e32 v215, s25, v215
	v_add_f32_e32 v214, s6, v214
	v_add_f32_e32 v215, s26, v215
	v_add_f32_e32 v214, s7, v214
	v_add_f32_e32 v215, s27, v215
	v_fmamk_f32 v214, v214, 0x3a000000, v195
	v_fmamk_f32 v215, v215, 0x3a000000, v195
; __device__ __forceinline__ float bf_lo(unsigned w) { return __uint_as_float(w << 16); }
; __device__ __forceinline__ float bf_hi(unsigned w) { return __uint_as_float(w & 0xffff0000u); }
; __global__ void __launch_bounds__(NWAVES * 64, 2) mk_fwd(Args args) {
;     ...
;                 const float rsy = __builtin_amdgcn_rsqf(wave_sum(sy) * (1.f / DM) + EPS);
; #pragma unroll
;                 for (int j = 0; j < 8; ++j) { const int col = 4 * F.lane + 256 * j;
;                     const f32x4 y4 = (f32x4){bf_lo(yw[q][j].x), bf_hi(yw[q][j].x), bf_lo(yw[q][j].y), bf_hi(yw[q][j].y)};
;                     *(f32x4*)(args.out + (size_t)row * DM + col) = v[q][j] + PA[j] * (y4 * rsy); }
	v_rsq_f32_e32 v214, v214
	v_rsq_f32_e32 v215, v215
	s_nop 0
	v_lshlrev_b32_e32 v200, 16, v80
	v_and_b32_e32 v201, 0xffff0000, v80
	v_lshlrev_b32_e32 v202, 16, v81
	v_and_b32_e32 v203, 0xffff0000, v81
	v_lshlrev_b32_e32 v204, 16, v112
	v_and_b32_e32 v205, 0xffff0000, v112
	v_lshlrev_b32_e32 v206, 16, v113
	v_and_b32_e32 v207, 0xffff0000, v113
	v_mul_f32_e32 v200, v214, v200
	v_mul_f32_e32 v201, v214, v201
	v_mul_f32_e32 v202, v214, v202
	v_mul_f32_e32 v203, v214, v203
	v_mul_f32_e32 v204, v215, v204
	v_mul_f32_e32 v205, v215, v205
	v_mul_f32_e32 v206, v215, v206
	v_mul_f32_e32 v207, v215, v207
	v_fmac_f32_e32 v32, v128, v200
	v_fmac_f32_e32 v33, v129, v201
	v_fmac_f32_e32 v34, v130, v202
	v_fmac_f32_e32 v35, v131, v203
	v_fmac_f32_e32 v32, v160, v204
	v_fmac_f32_e32 v33, v161, v205
	v_fmac_f32_e32 v34, v162, v206
	v_fmac_f32_e32 v35, v163, v207
	global_store_dwordx4 v192, v[32:35], s[18:19] offset:0 nt
	v_lshlrev_b32_e32 v200, 16, v82
	v_and_b32_e32 v201, 0xffff0000, v82
	v_lshlrev_b32_e32 v202, 16, v83
	v_and_b32_e32 v203, 0xffff0000, v83
	v_lshlrev_b32_e32 v204, 16, v114
	v_and_b32_e32 v205, 0xffff0000, v114
	v_lshlrev_b32_e32 v206, 16, v115
	v_and_b32_e32 v207, 0xffff0000, v115
	v_mul_f32_e32 v200, v214, v200
	v_mul_f32_e32 v201, v214, v201
	v_mul_f32_e32 v202, v214, v202
	v_mul_f32_e32 v203, v214, v203
	v_mul_f32_e32 v204, v215, v204
	v_mul_f32_e32 v205, v215, v205
	v_mul_f32_e32 v206, v215, v206
	v_mul_f32_e32 v207, v215, v207
	v_fmac_f32_e32 v36, v132, v200
	v_fmac_f32_e32 v37, v133, v201
	v_fmac_f32_e32 v38, v134, v202
	v_fmac_f32_e32 v39, v135, v203
	v_fmac_f32_e32 v36, v164, v204
	v_fmac_f32_e32 v37, v165, v205
	v_fmac_f32_e32 v38, v166, v206
	v_fmac_f32_e32 v39, v167, v207
	global_store_dwordx4 v192, v[36:39], s[18:19] offset:1024 nt
	v_lshlrev_b32_e32 v200, 16, v84
	v_and_b32_e32 v201, 0xffff0000, v84
	v_lshlrev_b32_e32 v202, 16, v85
	v_and_b32_e32 v203, 0xffff0000, v85
	v_lshlrev_b32_e32 v204, 16, v116
	v_and_b32_e32 v205, 0xffff0000, v116
	v_lshlrev_b32_e32 v206, 16, v117
	v_and_b32_e32 v207, 0xffff0000, v117
	v_mul_f32_e32 v200, v214, v200
	v_mul_f32_e32 v201, v214, v201
	v_mul_f32_e32 v202, v214, v202
	v_mul_f32_e32 v203, v214, v203
	v_mul_f32_e32 v204, v215, v204
	v_mul_f32_e32 v205, v215, v205
	v_mul_f32_e32 v206, v215, v206
	v_mul_f32_e32 v207, v215, v207
	v_fmac_f32_e32 v40, v136, v200
	v_fmac_f32_e32 v41, v137, v201
	v_fmac_f32_e32 v42, v138, v202
	v_fmac_f32_e32 v43, v139, v203
	v_fmac_f32_e32 v40, v168, v204
	v_fmac_f32_e32 v41, v169, v205
	v_fmac_f32_e32 v42, v170, v206
	v_fmac_f32_e32 v43, v171, v207
	global_store_dwordx4 v192, v[40:43], s[18:19] offset:2048 nt
	v_lshlrev_b32_e32 v200, 16, v86
	v_and_b32_e32 v201, 0xffff0000, v86
	v_lshlrev_b32_e32 v202, 16, v87
	v_and_b32_e32 v203, 0xffff0000, v87
	v_lshlrev_b32_e32 v204, 16, v118
	v_and_b32_e32 v205, 0xffff0000, v118
	v_lshlrev_b32_e32 v206, 16, v119
	v_and_b32_e32 v207, 0xffff0000, v119
	v_mul_f32_e32 v200, v214, v200
	v_mul_f32_e32 v201, v214, v201
	v_mul_f32_e32 v202, v214, v202
	v_mul_f32_e32 v203, v214, v203
	v_mul_f32_e32 v204, v215, v204
	v_mul_f32_e32 v205, v215, v205
	v_mul_f32_e32 v206, v215, v206
	v_mul_f32_e32 v207, v215, v207
	v_fmac_f32_e32 v44, v140, v200
	v_fmac_f32_e32 v45, v141, v201
	v_fmac_f32_e32 v46, v142, v202
	v_fmac_f32_e32 v47, v143, v203
	v_fmac_f32_e32 v44, v172, v204
	v_fmac_f32_e32 v45, v173, v205
	v_fmac_f32_e32 v46, v174, v206
	v_fmac_f32_e32 v47, v175, v207
	global_store_dwordx4 v192, v[44:47], s[18:19] offset:3072 nt
	v_lshlrev_b32_e32 v200, 16, v88
	v_and_b32_e32 v201, 0xffff0000, v88
	v_lshlrev_b32_e32 v202, 16, v89
	v_and_b32_e32 v203, 0xffff0000, v89
	v_lshlrev_b32_e32 v204, 16, v120
	v_and_b32_e32 v205, 0xffff0000, v120
	v_lshlrev_b32_e32 v206, 16, v121
	v_and_b32_e32 v207, 0xffff0000, v121
	v_mul_f32_e32 v200, v214, v200
	v_mul_f32_e32 v201, v214, v201
	v_mul_f32_e32 v202, v214, v202
	v_mul_f32_e32 v203, v214, v203
	v_mul_f32_e32 v204, v215, v204
	v_mul_f32_e32 v205, v215, v205
	v_mul_f32_e32 v206, v215, v206
	v_mul_f32_e32 v207, v215, v207
	v_fmac_f32_e32 v48, v144, v200
	v_fmac_f32_e32 v49, v145, v201
	v_fmac_f32_e32 v50, v146, v202
	v_fmac_f32_e32 v51, v147, v203
	v_fmac_f32_e32 v48, v176, v204
	v_fmac_f32_e32 v49, v177, v205
	v_fmac_f32_e32 v50, v178, v206
	v_fmac_f32_e32 v51, v179, v207
	global_store_dwordx4 v193, v[48:51], s[18:19] offset:0 nt
	v_lshlrev_b32_e32 v200, 16, v90
	v_and_b32_e32 v201, 0xffff0000, v90
	v_lshlrev_b32_e32 v202, 16, v91
	v_and_b32_e32 v203, 0xffff0000, v91
	v_lshlrev_b32_e32 v204, 16, v122
	v_and_b32_e32 v205, 0xffff0000, v122
	v_lshlrev_b32_e32 v206, 16, v123
	v_and_b32_e32 v207, 0xffff0000, v123
	v_mul_f32_e32 v200, v214, v200
	v_mul_f32_e32 v201, v214, v201
	v_mul_f32_e32 v202, v214, v202
	v_mul_f32_e32 v203, v214, v203
	v_mul_f32_e32 v204, v215, v204
	v_mul_f32_e32 v205, v215, v205
	v_mul_f32_e32 v206, v215, v206
	v_mul_f32_e32 v207, v215, v207
	v_fmac_f32_e32 v52, v148, v200
	v_fmac_f32_e32 v53, v149, v201
	v_fmac_f32_e32 v54, v150, v202
	v_fmac_f32_e32 v55, v151, v203
	v_fmac_f32_e32 v52, v180, v204
	v_fmac_f32_e32 v53, v181, v205
	v_fmac_f32_e32 v54, v182, v206
	v_fmac_f32_e32 v55, v183, v207
	global_store_dwordx4 v193, v[52:55], s[18:19] offset:1024 nt
	v_lshlrev_b32_e32 v200, 16, v92
	v_and_b32_e32 v201, 0xffff0000, v92
	v_lshlrev_b32_e32 v202, 16, v93
	v_and_b32_e32 v203, 0xffff0000, v93
	v_lshlrev_b32_e32 v204, 16, v124
	v_and_b32_e32 v205, 0xffff0000, v124
	v_lshlrev_b32_e32 v206, 16, v125
	v_and_b32_e32 v207, 0xffff0000, v125
	v_mul_f32_e32 v200, v214, v200
	v_mul_f32_e32 v201, v214, v201
	v_mul_f32_e32 v202, v214, v202
	v_mul_f32_e32 v203, v214, v203
	v_mul_f32_e32 v204, v215, v204
; __device__ __forceinline__ float bf_lo(unsigned w) { return __uint_as_float(w << 16); }
; __device__ __forceinline__ float bf_hi(unsigned w) { return __uint_as_float(w & 0xffff0000u); }
; __global__ void __launch_bounds__(NWAVES * 64, 2) mk_fwd(Args args) {
;     ...
;                 float sy = 0.f;
; #pragma unroll
;                 for (int j = 0; j < 8; ++j) { const float a = bf_lo(yw[q][j].x), b = bf_hi(yw[q][j].x), c2 = bf_lo(yw[q][j].y), d = bf_hi(yw[q][j].y); sy += (a * a + b * b) + (c2 * c2 + d * d); }
;                 const float rsy = __builtin_amdgcn_rsqf(wave_sum(sy) * (1.f / DM) + EPS);
; #pragma unroll
;                 for (int j = 0; j < 8; ++j) { const int col = 4 * F.lane + 256 * j;
;                     const f32x4 y4 = (f32x4){bf_lo(yw[q][j].x), bf_hi(yw[q][j].x), bf_lo(yw[q][j].y), bf_hi(yw[q][j].y)};
;                     *(f32x4*)(args.out + (size_t)row * DM + col) = v[q][j] + PA[j] * (y4 * rsy); }
	v_mul_f32_e32 v205, v215, v205
	v_mul_f32_e32 v206, v215, v206
	v_mul_f32_e32 v207, v215, v207
	v_fmac_f32_e32 v56, v152, v200
	v_fmac_f32_e32 v57, v153, v201
	v_fmac_f32_e32 v58, v154, v202
	v_fmac_f32_e32 v59, v155, v203
	v_fmac_f32_e32 v56, v184, v204
	v_fmac_f32_e32 v57, v185, v205
	v_fmac_f32_e32 v58, v186, v206
	v_fmac_f32_e32 v59, v187, v207
	global_store_dwordx4 v193, v[56:59], s[18:19] offset:2048 nt
	v_lshlrev_b32_e32 v200, 16, v94
	v_and_b32_e32 v201, 0xffff0000, v94
	v_lshlrev_b32_e32 v202, 16, v95
	v_and_b32_e32 v203, 0xffff0000, v95
	v_lshlrev_b32_e32 v204, 16, v126
	v_and_b32_e32 v205, 0xffff0000, v126
	v_lshlrev_b32_e32 v206, 16, v127
	v_and_b32_e32 v207, 0xffff0000, v127
	v_mul_f32_e32 v200, v214, v200
	v_mul_f32_e32 v201, v214, v201
	v_mul_f32_e32 v202, v214, v202
	v_mul_f32_e32 v203, v214, v203
	v_mul_f32_e32 v204, v215, v204
	v_mul_f32_e32 v205, v215, v205
	v_mul_f32_e32 v206, v215, v206
	v_mul_f32_e32 v207, v215, v207
	v_fmac_f32_e32 v60, v156, v200
	v_fmac_f32_e32 v61, v157, v201
	v_fmac_f32_e32 v62, v158, v202
	v_fmac_f32_e32 v63, v159, v203
	v_fmac_f32_e32 v60, v188, v204
	v_fmac_f32_e32 v61, v189, v205
	v_fmac_f32_e32 v62, v190, v206
	v_fmac_f32_e32 v63, v191, v207
	global_store_dwordx4 v193, v[60:63], s[18:19] offset:3072 nt
	s_add_u32 s18, s18, 0x2000
	s_addc_u32 s19, s19, 0
	global_load_dwordx4 v[32:35], v192, s[14:15] offset:0
	global_load_dwordx4 v[36:39], v192, s[14:15] offset:1024
	global_load_dwordx4 v[40:43], v192, s[14:15] offset:2048
	global_load_dwordx4 v[44:47], v192, s[14:15] offset:3072
	global_load_dwordx4 v[48:51], v193, s[14:15] offset:0
	global_load_dwordx4 v[52:55], v193, s[14:15] offset:1024
	global_load_dwordx4 v[56:59], v193, s[14:15] offset:2048
	global_load_dwordx4 v[60:63], v193, s[14:15] offset:3072
	global_load_dwordx2 v[80:81], v194, s[16:17] offset:0
	global_load_dwordx2 v[82:83], v194, s[16:17] offset:512
	global_load_dwordx2 v[84:85], v194, s[16:17] offset:1024
	global_load_dwordx2 v[86:87], v194, s[16:17] offset:1536
	global_load_dwordx2 v[88:89], v194, s[16:17] offset:2048
	global_load_dwordx2 v[90:91], v194, s[16:17] offset:2560
	global_load_dwordx2 v[92:93], v194, s[16:17] offset:3072
	global_load_dwordx2 v[94:95], v194, s[16:17] offset:3584
	global_load_dwordx2 v[112:113], v194, s[22:23] offset:0
	global_load_dwordx2 v[114:115], v194, s[22:23] offset:512
	global_load_dwordx2 v[116:117], v194, s[22:23] offset:1024
	global_load_dwordx2 v[118:119], v194, s[22:23] offset:1536
	global_load_dwordx2 v[120:121], v194, s[22:23] offset:2048
	global_load_dwordx2 v[122:123], v194, s[22:23] offset:2560
	global_load_dwordx2 v[124:125], v194, s[22:23] offset:3072
	global_load_dwordx2 v[126:127], v194, s[22:23] offset:3584
	s_add_u32 s14, s14, 0x2000
	s_addc_u32 s15, s15, 0
	s_add_u32 s16, s16, 0x1000
	s_addc_u32 s17, s17, 0
	s_add_u32 s22, s22, 0x1000
	s_addc_u32 s23, s23, 0
	s_waitcnt vmcnt(32)
	v_lshlrev_b32_e32 v200, 16, v64
	v_and_b32_e32 v201, 0xffff0000, v64
	v_lshlrev_b32_e32 v202, 16, v65
	v_and_b32_e32 v203, 0xffff0000, v65
	v_mul_f32_e32 v208, v200, v200
	v_mul_f32_e32 v209, v201, v201
	v_fmac_f32_e32 v208, v202, v202
	v_fmac_f32_e32 v209, v203, v203
	v_lshlrev_b32_e32 v204, 16, v96
	v_and_b32_e32 v205, 0xffff0000, v96
	v_lshlrev_b32_e32 v206, 16, v97
	v_and_b32_e32 v207, 0xffff0000, v97
	v_mul_f32_e32 v210, v204, v204
	v_mul_f32_e32 v211, v205, v205
	v_fmac_f32_e32 v210, v206, v206
	v_fmac_f32_e32 v211, v207, v207
	v_lshlrev_b32_e32 v200, 16, v66
	v_and_b32_e32 v201, 0xffff0000, v66
	v_lshlrev_b32_e32 v202, 16, v67
	v_and_b32_e32 v203, 0xffff0000, v67
	v_fmac_f32_e32 v208, v200, v200
	v_fmac_f32_e32 v209, v201, v201
	v_fmac_f32_e32 v208, v202, v202
	v_fmac_f32_e32 v209, v203, v203
	v_lshlrev_b32_e32 v204, 16, v98
	v_and_b32_e32 v205, 0xffff0000, v98
	v_lshlrev_b32_e32 v206, 16, v99
	v_and_b32_e32 v207, 0xffff0000, v99
	v_fmac_f32_e32 v210, v204, v204
	v_fmac_f32_e32 v211, v205, v205
	v_fmac_f32_e32 v210, v206, v206
	v_fmac_f32_e32 v211, v207, v207
	v_lshlrev_b32_e32 v200, 16, v68
	v_and_b32_e32 v201, 0xffff0000, v68
	v_lshlrev_b32_e32 v202, 16, v69
	v_and_b32_e32 v203, 0xffff0000, v69
	v_fmac_f32_e32 v208, v200, v200
	v_fmac_f32_e32 v209, v201, v201
	v_fmac_f32_e32 v208, v202, v202
	v_fmac_f32_e32 v209, v203, v203
	v_lshlrev_b32_e32 v204, 16, v100
	v_and_b32_e32 v205, 0xffff0000, v100
	v_lshlrev_b32_e32 v206, 16, v101
	v_and_b32_e32 v207, 0xffff0000, v101
	v_fmac_f32_e32 v210, v204, v204
	v_fmac_f32_e32 v211, v205, v205
	v_fmac_f32_e32 v210, v206, v206
	v_fmac_f32_e32 v211, v207, v207
	v_lshlrev_b32_e32 v200, 16, v70
	v_and_b32_e32 v201, 0xffff0000, v70
	v_lshlrev_b32_e32 v202, 16, v71
	v_and_b32_e32 v203, 0xffff0000, v71
	v_fmac_f32_e32 v208, v200, v200
	v_fmac_f32_e32 v209, v201, v201
	v_fmac_f32_e32 v208, v202, v202
	v_fmac_f32_e32 v209, v203, v203
	v_lshlrev_b32_e32 v204, 16, v102
	v_and_b32_e32 v205, 0xffff0000, v102
	v_lshlrev_b32_e32 v206, 16, v103
	v_and_b32_e32 v207, 0xffff0000, v103
	v_fmac_f32_e32 v210, v204, v204
	v_fmac_f32_e32 v211, v205, v205
	v_fmac_f32_e32 v210, v206, v206
	v_fmac_f32_e32 v211, v207, v207
	v_lshlrev_b32_e32 v200, 16, v72
	v_and_b32_e32 v201, 0xffff0000, v72
	v_lshlrev_b32_e32 v202, 16, v73
	v_and_b32_e32 v203, 0xffff0000, v73
	v_fmac_f32_e32 v208, v200, v200
	v_fmac_f32_e32 v209, v201, v201
	v_fmac_f32_e32 v208, v202, v202
	v_fmac_f32_e32 v209, v203, v203
	v_lshlrev_b32_e32 v204, 16, v104
	v_and_b32_e32 v205, 0xffff0000, v104
	v_lshlrev_b32_e32 v206, 16, v105
	v_and_b32_e32 v207, 0xffff0000, v105
	v_fmac_f32_e32 v210, v204, v204
	v_fmac_f32_e32 v211, v205, v205
	v_fmac_f32_e32 v210, v206, v206
	v_fmac_f32_e32 v211, v207, v207
	v_lshlrev_b32_e32 v200, 16, v74
; __device__ __forceinline__ float bf_lo(unsigned w) { return __uint_as_float(w << 16); }
; __device__ __forceinline__ float bf_hi(unsigned w) { return __uint_as_float(w & 0xffff0000u); }
; __global__ void __launch_bounds__(NWAVES * 64, 2) mk_fwd(Args args) {
;     ...
;                 float sy = 0.f;
; #pragma unroll
;                 for (int j = 0; j < 8; ++j) { const float a = bf_lo(yw[q][j].x), b = bf_hi(yw[q][j].x), c2 = bf_lo(yw[q][j].y), d = bf_hi(yw[q][j].y); sy += (a * a + b * b) + (c2 * c2 + d * d); }
;                 const float rsy = __builtin_amdgcn_rsqf(wave_sum(sy) * (1.f / DM) + EPS);
; #pragma unroll
;                 for (int j = 0; j < 8; ++j) { const int col = 4 * F.lane + 256 * j;
;                     const f32x4 y4 = (f32x4){bf_lo(yw[q][j].x), bf_hi(yw[q][j].x), bf_lo(yw[q][j].y), bf_hi(yw[q][j].y)};
;                     *(f32x4*)(args.out + (size_t)row * DM + col) = v[q][j] + PA[j] * (y4 * rsy); }
	v_and_b32_e32 v201, 0xffff0000, v74
	v_lshlrev_b32_e32 v202, 16, v75
	v_and_b32_e32 v203, 0xffff0000, v75
	v_fmac_f32_e32 v208, v200, v200
	v_fmac_f32_e32 v209, v201, v201
	v_fmac_f32_e32 v208, v202, v202
	v_fmac_f32_e32 v209, v203, v203
	v_lshlrev_b32_e32 v204, 16, v106
	v_and_b32_e32 v205, 0xffff0000, v106
	v_lshlrev_b32_e32 v206, 16, v107
	v_and_b32_e32 v207, 0xffff0000, v107
	v_fmac_f32_e32 v210, v204, v204
	v_fmac_f32_e32 v211, v205, v205
	v_fmac_f32_e32 v210, v206, v206
	v_fmac_f32_e32 v211, v207, v207
	v_lshlrev_b32_e32 v200, 16, v76
	v_and_b32_e32 v201, 0xffff0000, v76
	v_lshlrev_b32_e32 v202, 16, v77
	v_and_b32_e32 v203, 0xffff0000, v77
	v_fmac_f32_e32 v208, v200, v200
	v_fmac_f32_e32 v209, v201, v201
	v_fmac_f32_e32 v208, v202, v202
	v_fmac_f32_e32 v209, v203, v203
	v_lshlrev_b32_e32 v204, 16, v108
	v_and_b32_e32 v205, 0xffff0000, v108
	v_lshlrev_b32_e32 v206, 16, v109
	v_and_b32_e32 v207, 0xffff0000, v109
	v_fmac_f32_e32 v210, v204, v204
	v_fmac_f32_e32 v211, v205, v205
	v_fmac_f32_e32 v210, v206, v206
	v_fmac_f32_e32 v211, v207, v207
	v_lshlrev_b32_e32 v200, 16, v78
	v_and_b32_e32 v201, 0xffff0000, v78
	v_lshlrev_b32_e32 v202, 16, v79
	v_and_b32_e32 v203, 0xffff0000, v79
	v_fmac_f32_e32 v208, v200, v200
	v_fmac_f32_e32 v209, v201, v201
	v_fmac_f32_e32 v208, v202, v202
	v_fmac_f32_e32 v209, v203, v203
	v_lshlrev_b32_e32 v204, 16, v110
	v_and_b32_e32 v205, 0xffff0000, v110
	v_lshlrev_b32_e32 v206, 16, v111
	v_and_b32_e32 v207, 0xffff0000, v111
	v_fmac_f32_e32 v210, v204, v204
	v_fmac_f32_e32 v211, v205, v205
	v_fmac_f32_e32 v210, v206, v206
	v_fmac_f32_e32 v211, v207, v207
	v_add_f32_e32 v208, v208, v209
	v_add_f32_e32 v210, v210, v211
	s_nop 0
	v_add_f32_dpp v212, v208, v208 quad_perm:[1,0,3,2] row_mask:0xf bank_mask:0xf
	v_add_f32_dpp v213, v210, v210 quad_perm:[1,0,3,2] row_mask:0xf bank_mask:0xf
	s_nop 0
	v_add_f32_dpp v212, v212, v212 quad_perm:[2,3,0,1] row_mask:0xf bank_mask:0xf
	v_add_f32_dpp v213, v213, v213 quad_perm:[2,3,0,1] row_mask:0xf bank_mask:0xf
	s_nop 0
	v_add_f32_dpp v212, v212, v212 row_half_mirror row_mask:0xf bank_mask:0xf
	v_add_f32_dpp v213, v213, v213 row_half_mirror row_mask:0xf bank_mask:0xf
	s_nop 0
	v_add_f32_dpp v212, v212, v212 row_mirror row_mask:0xf bank_mask:0xf
	v_add_f32_dpp v213, v213, v213 row_mirror row_mask:0xf bank_mask:0xf
	s_nop 0
	v_readlane_b32 s4, v212, 0
	v_readlane_b32 s5, v212, 16
	v_readlane_b32 s6, v212, 32
	v_readlane_b32 s7, v212, 48
	v_readlane_b32 s24, v213, 0
	v_readlane_b32 s25, v213, 16
	v_readlane_b32 s26, v213, 32
	v_readlane_b32 s27, v213, 48
	s_nop 1
	v_mov_b32_e32 v214, s4
	v_mov_b32_e32 v215, s24
	v_add_f32_e32 v214, s5, v214
	v_add_f32_e32 v215, s25, v215
	v_add_f32_e32 v214, s6, v214
	v_add_f32_e32 v215, s26, v215
	v_add_f32_e32 v214, s7, v214
	v_add_f32_e32 v215, s27, v215
	v_fmamk_f32 v214, v214, 0x3a000000, v195
	v_fmamk_f32 v215, v215, 0x3a000000, v195
	v_rsq_f32_e32 v214, v214
	v_rsq_f32_e32 v215, v215
	s_nop 0
	v_lshlrev_b32_e32 v200, 16, v64
	v_and_b32_e32 v201, 0xffff0000, v64
	v_lshlrev_b32_e32 v202, 16, v65
	v_and_b32_e32 v203, 0xffff0000, v65
	v_lshlrev_b32_e32 v204, 16, v96
	v_and_b32_e32 v205, 0xffff0000, v96
	v_lshlrev_b32_e32 v206, 16, v97
	v_and_b32_e32 v207, 0xffff0000, v97
	v_mul_f32_e32 v200, v214, v200
	v_mul_f32_e32 v201, v214, v201
	v_mul_f32_e32 v202, v214, v202
	v_mul_f32_e32 v203, v214, v203
	v_mul_f32_e32 v204, v215, v204
	v_mul_f32_e32 v205, v215, v205
	v_mul_f32_e32 v206, v215, v206
	v_mul_f32_e32 v207, v215, v207
	v_fmac_f32_e32 v0, v128, v200
	v_fmac_f32_e32 v1, v129, v201
	v_fmac_f32_e32 v2, v130, v202
	v_fmac_f32_e32 v3, v131, v203
	v_fmac_f32_e32 v0, v160, v204
	v_fmac_f32_e32 v1, v161, v205
	v_fmac_f32_e32 v2, v162, v206
	v_fmac_f32_e32 v3, v163, v207
	global_store_dwordx4 v192, v[0:3], s[18:19] offset:0 nt
	v_lshlrev_b32_e32 v200, 16, v66
	v_and_b32_e32 v201, 0xffff0000, v66
	v_lshlrev_b32_e32 v202, 16, v67
	v_and_b32_e32 v203, 0xffff0000, v67
	v_lshlrev_b32_e32 v204, 16, v98
	v_and_b32_e32 v205, 0xffff0000, v98
	v_lshlrev_b32_e32 v206, 16, v99
	v_and_b32_e32 v207, 0xffff0000, v99
	v_mul_f32_e32 v200, v214, v200
	v_mul_f32_e32 v201, v214, v201
	v_mul_f32_e32 v202, v214, v202
	v_mul_f32_e32 v203, v214, v203
	v_mul_f32_e32 v204, v215, v204
	v_mul_f32_e32 v205, v215, v205
	v_mul_f32_e32 v206, v215, v206
	v_mul_f32_e32 v207, v215, v207
	v_fmac_f32_e32 v4, v132, v200
	v_fmac_f32_e32 v5, v133, v201
	v_fmac_f32_e32 v6, v134, v202
	v_fmac_f32_e32 v7, v135, v203
	v_fmac_f32_e32 v4, v164, v204
	v_fmac_f32_e32 v5, v165, v205
	v_fmac_f32_e32 v6, v166, v206
	v_fmac_f32_e32 v7, v167, v207
	global_store_dwordx4 v192, v[4:7], s[18:19] offset:1024 nt
	v_lshlrev_b32_e32 v200, 16, v68
	v_and_b32_e32 v201, 0xffff0000, v68
	v_lshlrev_b32_e32 v202, 16, v69
	v_and_b32_e32 v203, 0xffff0000, v69
	v_lshlrev_b32_e32 v204, 16, v100
	v_and_b32_e32 v205, 0xffff0000, v100
	v_lshlrev_b32_e32 v206, 16, v101
	v_and_b32_e32 v207, 0xffff0000, v101
	v_mul_f32_e32 v200, v214, v200
	v_mul_f32_e32 v201, v214, v201
	v_mul_f32_e32 v202, v214, v202
	v_mul_f32_e32 v203, v214, v203
	v_mul_f32_e32 v204, v215, v204
	v_mul_f32_e32 v205, v215, v205
	v_mul_f32_e32 v206, v215, v206
	v_mul_f32_e32 v207, v215, v207
	v_fmac_f32_e32 v8, v136, v200
	v_fmac_f32_e32 v9, v137, v201
	v_fmac_f32_e32 v10, v138, v202
	v_fmac_f32_e32 v11, v139, v203
	v_fmac_f32_e32 v8, v168, v204
	v_fmac_f32_e32 v9, v169, v205
	v_fmac_f32_e32 v10, v170, v206
	v_fmac_f32_e32 v11, v171, v207
	global_store_dwordx4 v192, v[8:11], s[18:19] offset:2048 nt
	v_lshlrev_b32_e32 v200, 16, v70
	v_and_b32_e32 v201, 0xffff0000, v70
	v_lshlrev_b32_e32 v202, 16, v71
	v_and_b32_e32 v203, 0xffff0000, v71
; __device__ __forceinline__ float bf_lo(unsigned w) { return __uint_as_float(w << 16); }
; __device__ __forceinline__ float bf_hi(unsigned w) { return __uint_as_float(w & 0xffff0000u); }
; __global__ void __launch_bounds__(NWAVES * 64, 2) mk_fwd(Args args) {
;     ...
;                 float sy = 0.f;
; #pragma unroll
;                 for (int j = 0; j < 8; ++j) { const float a = bf_lo(yw[q][j].x), b = bf_hi(yw[q][j].x), c2 = bf_lo(yw[q][j].y), d = bf_hi(yw[q][j].y); sy += (a * a + b * b) + (c2 * c2 + d * d); }
;                 const float rsy = __builtin_amdgcn_rsqf(wave_sum(sy) * (1.f / DM) + EPS);
; #pragma unroll
;                 for (int j = 0; j < 8; ++j) { const int col = 4 * F.lane + 256 * j;
;                     const f32x4 y4 = (f32x4){bf_lo(yw[q][j].x), bf_hi(yw[q][j].x), bf_lo(yw[q][j].y), bf_hi(yw[q][j].y)};
;                     *(f32x4*)(args.out + (size_t)row * DM + col) = v[q][j] + PA[j] * (y4 * rsy); }
	v_lshlrev_b32_e32 v204, 16, v102
	v_and_b32_e32 v205, 0xffff0000, v102
	v_lshlrev_b32_e32 v206, 16, v103
	v_and_b32_e32 v207, 0xffff0000, v103
	v_mul_f32_e32 v200, v214, v200
	v_mul_f32_e32 v201, v214, v201
	v_mul_f32_e32 v202, v214, v202
	v_mul_f32_e32 v203, v214, v203
	v_mul_f32_e32 v204, v215, v204
	v_mul_f32_e32 v205, v215, v205
	v_mul_f32_e32 v206, v215, v206
	v_mul_f32_e32 v207, v215, v207
	v_fmac_f32_e32 v12, v140, v200
	v_fmac_f32_e32 v13, v141, v201
	v_fmac_f32_e32 v14, v142, v202
	v_fmac_f32_e32 v15, v143, v203
	v_fmac_f32_e32 v12, v172, v204
	v_fmac_f32_e32 v13, v173, v205
	v_fmac_f32_e32 v14, v174, v206
	v_fmac_f32_e32 v15, v175, v207
	global_store_dwordx4 v192, v[12:15], s[18:19] offset:3072 nt
	v_lshlrev_b32_e32 v200, 16, v72
	v_and_b32_e32 v201, 0xffff0000, v72
	v_lshlrev_b32_e32 v202, 16, v73
	v_and_b32_e32 v203, 0xffff0000, v73
	v_lshlrev_b32_e32 v204, 16, v104
	v_and_b32_e32 v205, 0xffff0000, v104
	v_lshlrev_b32_e32 v206, 16, v105
	v_and_b32_e32 v207, 0xffff0000, v105
	v_mul_f32_e32 v200, v214, v200
	v_mul_f32_e32 v201, v214, v201
	v_mul_f32_e32 v202, v214, v202
	v_mul_f32_e32 v203, v214, v203
	v_mul_f32_e32 v204, v215, v204
	v_mul_f32_e32 v205, v215, v205
	v_mul_f32_e32 v206, v215, v206
	v_mul_f32_e32 v207, v215, v207
	v_fmac_f32_e32 v16, v144, v200
	v_fmac_f32_e32 v17, v145, v201
	v_fmac_f32_e32 v18, v146, v202
	v_fmac_f32_e32 v19, v147, v203
	v_fmac_f32_e32 v16, v176, v204
	v_fmac_f32_e32 v17, v177, v205
	v_fmac_f32_e32 v18, v178, v206
	v_fmac_f32_e32 v19, v179, v207
	global_store_dwordx4 v193, v[16:19], s[18:19] offset:0 nt
	v_lshlrev_b32_e32 v200, 16, v74
	v_and_b32_e32 v201, 0xffff0000, v74
	v_lshlrev_b32_e32 v202, 16, v75
	v_and_b32_e32 v203, 0xffff0000, v75
	v_lshlrev_b32_e32 v204, 16, v106
	v_and_b32_e32 v205, 0xffff0000, v106
	v_lshlrev_b32_e32 v206, 16, v107
	v_and_b32_e32 v207, 0xffff0000, v107
	v_mul_f32_e32 v200, v214, v200
	v_mul_f32_e32 v201, v214, v201
	v_mul_f32_e32 v202, v214, v202
	v_mul_f32_e32 v203, v214, v203
	v_mul_f32_e32 v204, v215, v204
	v_mul_f32_e32 v205, v215, v205
	v_mul_f32_e32 v206, v215, v206
	v_mul_f32_e32 v207, v215, v207
	v_fmac_f32_e32 v20, v148, v200
	v_fmac_f32_e32 v21, v149, v201
	v_fmac_f32_e32 v22, v150, v202
	v_fmac_f32_e32 v23, v151, v203
	v_fmac_f32_e32 v20, v180, v204
	v_fmac_f32_e32 v21, v181, v205
	v_fmac_f32_e32 v22, v182, v206
	v_fmac_f32_e32 v23, v183, v207
	global_store_dwordx4 v193, v[20:23], s[18:19] offset:1024 nt
	v_lshlrev_b32_e32 v200, 16, v76
	v_and_b32_e32 v201, 0xffff0000, v76
	v_lshlrev_b32_e32 v202, 16, v77
	v_and_b32_e32 v203, 0xffff0000, v77
	v_lshlrev_b32_e32 v204, 16, v108
	v_and_b32_e32 v205, 0xffff0000, v108
	v_lshlrev_b32_e32 v206, 16, v109
	v_and_b32_e32 v207, 0xffff0000, v109
	v_mul_f32_e32 v200, v214, v200
	v_mul_f32_e32 v201, v214, v201
	v_mul_f32_e32 v202, v214, v202
	v_mul_f32_e32 v203, v214, v203
	v_mul_f32_e32 v204, v215, v204
	v_mul_f32_e32 v205, v215, v205
	v_mul_f32_e32 v206, v215, v206
	v_mul_f32_e32 v207, v215, v207
	v_fmac_f32_e32 v24, v152, v200
	v_fmac_f32_e32 v25, v153, v201
	v_fmac_f32_e32 v26, v154, v202
	v_fmac_f32_e32 v27, v155, v203
	v_fmac_f32_e32 v24, v184, v204
	v_fmac_f32_e32 v25, v185, v205
	v_fmac_f32_e32 v26, v186, v206
	v_fmac_f32_e32 v27, v187, v207
	global_store_dwordx4 v193, v[24:27], s[18:19] offset:2048 nt
	v_lshlrev_b32_e32 v200, 16, v78
	v_and_b32_e32 v201, 0xffff0000, v78
	v_lshlrev_b32_e32 v202, 16, v79
	v_and_b32_e32 v203, 0xffff0000, v79
	v_lshlrev_b32_e32 v204, 16, v110
	v_and_b32_e32 v205, 0xffff0000, v110
	v_lshlrev_b32_e32 v206, 16, v111
	v_and_b32_e32 v207, 0xffff0000, v111
	v_mul_f32_e32 v200, v214, v200
	v_mul_f32_e32 v201, v214, v201
	v_mul_f32_e32 v202, v214, v202
	v_mul_f32_e32 v203, v214, v203
	v_mul_f32_e32 v204, v215, v204
	v_mul_f32_e32 v205, v215, v205
	v_mul_f32_e32 v206, v215, v206
	v_mul_f32_e32 v207, v215, v207
	v_fmac_f32_e32 v28, v156, v200
	v_fmac_f32_e32 v29, v157, v201
	v_fmac_f32_e32 v30, v158, v202
	v_fmac_f32_e32 v31, v159, v203
	v_fmac_f32_e32 v28, v188, v204
	v_fmac_f32_e32 v29, v189, v205
	v_fmac_f32_e32 v30, v190, v206
	v_fmac_f32_e32 v31, v191, v207
	global_store_dwordx4 v193, v[28:31], s[18:19] offset:3072 nt
	s_add_u32 s18, s18, 0x2000
	s_addc_u32 s19, s19, 0
	global_load_dwordx4 v[0:3], v192, s[14:15] offset:0
	global_load_dwordx4 v[4:7], v192, s[14:15] offset:1024
	global_load_dwordx4 v[8:11], v192, s[14:15] offset:2048
	global_load_dwordx4 v[12:15], v192, s[14:15] offset:3072
	global_load_dwordx4 v[16:19], v193, s[14:15] offset:0
	global_load_dwordx4 v[20:23], v193, s[14:15] offset:1024
	global_load_dwordx4 v[24:27], v193, s[14:15] offset:2048
	global_load_dwordx4 v[28:31], v193, s[14:15] offset:3072
	global_load_dwordx2 v[64:65], v194, s[16:17] offset:0
	global_load_dwordx2 v[66:67], v194, s[16:17] offset:512
	global_load_dwordx2 v[68:69], v194, s[16:17] offset:1024
	global_load_dwordx2 v[70:71], v194, s[16:17] offset:1536
	global_load_dwordx2 v[72:73], v194, s[16:17] offset:2048
	global_load_dwordx2 v[74:75], v194, s[16:17] offset:2560
	global_load_dwordx2 v[76:77], v194, s[16:17] offset:3072
	global_load_dwordx2 v[78:79], v194, s[16:17] offset:3584
	global_load_dwordx2 v[96:97], v194, s[22:23] offset:0
	global_load_dwordx2 v[98:99], v194, s[22:23] offset:512
	global_load_dwordx2 v[100:101], v194, s[22:23] offset:1024
	global_load_dwordx2 v[102:103], v194, s[22:23] offset:1536
	global_load_dwordx2 v[104:105], v194, s[22:23] offset:2048
	global_load_dwordx2 v[106:107], v194, s[22:23] offset:2560
	global_load_dwordx2 v[108:109], v194, s[22:23] offset:3072
	global_load_dwordx2 v[110:111], v194, s[22:23] offset:3584
	s_add_u32 s14, s14, 0x2000
	s_addc_u32 s15, s15, 0
	s_add_u32 s16, s16, 0x1000
	s_addc_u32 s17, s17, 0
	s_add_u32 s22, s22, 0x1000
	s_addc_u32 s23, s23, 0
	s_waitcnt vmcnt(32)
; __device__ __forceinline__ float bf_lo(unsigned w) { return __uint_as_float(w << 16); }
; __device__ __forceinline__ float bf_hi(unsigned w) { return __uint_as_float(w & 0xffff0000u); }
; __global__ void __launch_bounds__(NWAVES * 64, 2) mk_fwd(Args args) {
;     ...
;                 float sy = 0.f;
; #pragma unroll
;                 for (int j = 0; j < 8; ++j) { const float a = bf_lo(yw[q][j].x), b = bf_hi(yw[q][j].x), c2 = bf_lo(yw[q][j].y), d = bf_hi(yw[q][j].y); sy += (a * a + b * b) + (c2 * c2 + d * d); }
;                 const float rsy = __builtin_amdgcn_rsqf(wave_sum(sy) * (1.f / DM) + EPS);
	v_lshlrev_b32_e32 v200, 16, v80
	v_and_b32_e32 v201, 0xffff0000, v80
	v_lshlrev_b32_e32 v202, 16, v81
	v_and_b32_e32 v203, 0xffff0000, v81
	v_mul_f32_e32 v208, v200, v200
	v_mul_f32_e32 v209, v201, v201
	v_fmac_f32_e32 v208, v202, v202
	v_fmac_f32_e32 v209, v203, v203
	v_lshlrev_b32_e32 v204, 16, v112
	v_and_b32_e32 v205, 0xffff0000, v112
	v_lshlrev_b32_e32 v206, 16, v113
	v_and_b32_e32 v207, 0xffff0000, v113
	v_mul_f32_e32 v210, v204, v204
	v_mul_f32_e32 v211, v205, v205
	v_fmac_f32_e32 v210, v206, v206
	v_fmac_f32_e32 v211, v207, v207
	v_lshlrev_b32_e32 v200, 16, v82
	v_and_b32_e32 v201, 0xffff0000, v82
	v_lshlrev_b32_e32 v202, 16, v83
	v_and_b32_e32 v203, 0xffff0000, v83
	v_fmac_f32_e32 v208, v200, v200
	v_fmac_f32_e32 v209, v201, v201
	v_fmac_f32_e32 v208, v202, v202
	v_fmac_f32_e32 v209, v203, v203
	v_lshlrev_b32_e32 v204, 16, v114
	v_and_b32_e32 v205, 0xffff0000, v114
	v_lshlrev_b32_e32 v206, 16, v115
	v_and_b32_e32 v207, 0xffff0000, v115
	v_fmac_f32_e32 v210, v204, v204
	v_fmac_f32_e32 v211, v205, v205
	v_fmac_f32_e32 v210, v206, v206
	v_fmac_f32_e32 v211, v207, v207
	v_lshlrev_b32_e32 v200, 16, v84
	v_and_b32_e32 v201, 0xffff0000, v84
	v_lshlrev_b32_e32 v202, 16, v85
	v_and_b32_e32 v203, 0xffff0000, v85
	v_fmac_f32_e32 v208, v200, v200
	v_fmac_f32_e32 v209, v201, v201
	v_fmac_f32_e32 v208, v202, v202
	v_fmac_f32_e32 v209, v203, v203
	v_lshlrev_b32_e32 v204, 16, v116
	v_and_b32_e32 v205, 0xffff0000, v116
	v_lshlrev_b32_e32 v206, 16, v117
	v_and_b32_e32 v207, 0xffff0000, v117
	v_fmac_f32_e32 v210, v204, v204
	v_fmac_f32_e32 v211, v205, v205
	v_fmac_f32_e32 v210, v206, v206
	v_fmac_f32_e32 v211, v207, v207
	v_lshlrev_b32_e32 v200, 16, v86
	v_and_b32_e32 v201, 0xffff0000, v86
	v_lshlrev_b32_e32 v202, 16, v87
	v_and_b32_e32 v203, 0xffff0000, v87
	v_fmac_f32_e32 v208, v200, v200
	v_fmac_f32_e32 v209, v201, v201
	v_fmac_f32_e32 v208, v202, v202
	v_fmac_f32_e32 v209, v203, v203
	v_lshlrev_b32_e32 v204, 16, v118
	v_and_b32_e32 v205, 0xffff0000, v118
	v_lshlrev_b32_e32 v206, 16, v119
	v_and_b32_e32 v207, 0xffff0000, v119
	v_fmac_f32_e32 v210, v204, v204
	v_fmac_f32_e32 v211, v205, v205
	v_fmac_f32_e32 v210, v206, v206
	v_fmac_f32_e32 v211, v207, v207
	v_lshlrev_b32_e32 v200, 16, v88
	v_and_b32_e32 v201, 0xffff0000, v88
	v_lshlrev_b32_e32 v202, 16, v89
	v_and_b32_e32 v203, 0xffff0000, v89
	v_fmac_f32_e32 v208, v200, v200
	v_fmac_f32_e32 v209, v201, v201
	v_fmac_f32_e32 v208, v202, v202
	v_fmac_f32_e32 v209, v203, v203
	v_lshlrev_b32_e32 v204, 16, v120
	v_and_b32_e32 v205, 0xffff0000, v120
	v_lshlrev_b32_e32 v206, 16, v121
	v_and_b32_e32 v207, 0xffff0000, v121
	v_fmac_f32_e32 v210, v204, v204
	v_fmac_f32_e32 v211, v205, v205
	v_fmac_f32_e32 v210, v206, v206
	v_fmac_f32_e32 v211, v207, v207
	v_lshlrev_b32_e32 v200, 16, v90
	v_and_b32_e32 v201, 0xffff0000, v90
	v_lshlrev_b32_e32 v202, 16, v91
	v_and_b32_e32 v203, 0xffff0000, v91
	v_fmac_f32_e32 v208, v200, v200
	v_fmac_f32_e32 v209, v201, v201
	v_fmac_f32_e32 v208, v202, v202
	v_fmac_f32_e32 v209, v203, v203
	v_lshlrev_b32_e32 v204, 16, v122
	v_and_b32_e32 v205, 0xffff0000, v122
	v_lshlrev_b32_e32 v206, 16, v123
	v_and_b32_e32 v207, 0xffff0000, v123
	v_fmac_f32_e32 v210, v204, v204
	v_fmac_f32_e32 v211, v205, v205
	v_fmac_f32_e32 v210, v206, v206
	v_fmac_f32_e32 v211, v207, v207
	v_lshlrev_b32_e32 v200, 16, v92
	v_and_b32_e32 v201, 0xffff0000, v92
	v_lshlrev_b32_e32 v202, 16, v93
	v_and_b32_e32 v203, 0xffff0000, v93
	v_fmac_f32_e32 v208, v200, v200
	v_fmac_f32_e32 v209, v201, v201
	v_fmac_f32_e32 v208, v202, v202
	v_fmac_f32_e32 v209, v203, v203
	v_lshlrev_b32_e32 v204, 16, v124
	v_and_b32_e32 v205, 0xffff0000, v124
	v_lshlrev_b32_e32 v206, 16, v125
	v_and_b32_e32 v207, 0xffff0000, v125
	v_fmac_f32_e32 v210, v204, v204
	v_fmac_f32_e32 v211, v205, v205
	v_fmac_f32_e32 v210, v206, v206
	v_fmac_f32_e32 v211, v207, v207
	v_lshlrev_b32_e32 v200, 16, v94
	v_and_b32_e32 v201, 0xffff0000, v94
	v_lshlrev_b32_e32 v202, 16, v95
	v_and_b32_e32 v203, 0xffff0000, v95
	v_fmac_f32_e32 v208, v200, v200
	v_fmac_f32_e32 v209, v201, v201
	v_fmac_f32_e32 v208, v202, v202
	v_fmac_f32_e32 v209, v203, v203
	v_lshlrev_b32_e32 v204, 16, v126
	v_and_b32_e32 v205, 0xffff0000, v126
	v_lshlrev_b32_e32 v206, 16, v127
	v_and_b32_e32 v207, 0xffff0000, v127
	v_fmac_f32_e32 v210, v204, v204
	v_fmac_f32_e32 v211, v205, v205
	v_fmac_f32_e32 v210, v206, v206
	v_fmac_f32_e32 v211, v207, v207
	v_add_f32_e32 v208, v208, v209
	v_add_f32_e32 v210, v210, v211
	s_nop 0
	v_add_f32_dpp v212, v208, v208 quad_perm:[1,0,3,2] row_mask:0xf bank_mask:0xf
	v_add_f32_dpp v213, v210, v210 quad_perm:[1,0,3,2] row_mask:0xf bank_mask:0xf
	s_nop 0
	v_add_f32_dpp v212, v212, v212 quad_perm:[2,3,0,1] row_mask:0xf bank_mask:0xf
	v_add_f32_dpp v213, v213, v213 quad_perm:[2,3,0,1] row_mask:0xf bank_mask:0xf
	s_nop 0
	v_add_f32_dpp v212, v212, v212 row_half_mirror row_mask:0xf bank_mask:0xf
	v_add_f32_dpp v213, v213, v213 row_half_mirror row_mask:0xf bank_mask:0xf
	s_nop 0
	v_add_f32_dpp v212, v212, v212 row_mirror row_mask:0xf bank_mask:0xf
	v_add_f32_dpp v213, v213, v213 row_mirror row_mask:0xf bank_mask:0xf
	s_nop 0
	v_readlane_b32 s4, v212, 0
	v_readlane_b32 s5, v212, 16
	v_readlane_b32 s6, v212, 32
	v_readlane_b32 s7, v212, 48
	v_readlane_b32 s24, v213, 0
	v_readlane_b32 s25, v213, 16
	v_readlane_b32 s26, v213, 32
	v_readlane_b32 s27, v213, 48
	s_nop 1
	v_mov_b32_e32 v214, s4
	v_mov_b32_e32 v215, s24
	v_add_f32_e32 v214, s5, v214
	v_add_f32_e32 v215, s25, v215
	v_add_f32_e32 v214, s6, v214
	v_add_f32_e32 v215, s26, v215
	v_add_f32_e32 v214, s7, v214
	v_add_f32_e32 v215, s27, v215
	v_fmamk_f32 v214, v214, 0x3a000000, v195
	v_fmamk_f32 v215, v215, 0x3a000000, v195
; __device__ __forceinline__ float bf_lo(unsigned w) { return __uint_as_float(w << 16); }
; __device__ __forceinline__ float bf_hi(unsigned w) { return __uint_as_float(w & 0xffff0000u); }
; __global__ void __launch_bounds__(NWAVES * 64, 2) mk_fwd(Args args) {
;     ...
;                 const float rsy = __builtin_amdgcn_rsqf(wave_sum(sy) * (1.f / DM) + EPS);
; #pragma unroll
;                 for (int j = 0; j < 8; ++j) { const int col = 4 * F.lane + 256 * j;
;                     const f32x4 y4 = (f32x4){bf_lo(yw[q][j].x), bf_hi(yw[q][j].x), bf_lo(yw[q][j].y), bf_hi(yw[q][j].y)};
;                     *(f32x4*)(args.out + (size_t)row * DM + col) = v[q][j] + PA[j] * (y4 * rsy); }
	v_rsq_f32_e32 v214, v214
	v_rsq_f32_e32 v215, v215
	s_nop 0
	v_lshlrev_b32_e32 v200, 16, v80
	v_and_b32_e32 v201, 0xffff0000, v80
	v_lshlrev_b32_e32 v202, 16, v81
	v_and_b32_e32 v203, 0xffff0000, v81
	v_lshlrev_b32_e32 v204, 16, v112
	v_and_b32_e32 v205, 0xffff0000, v112
	v_lshlrev_b32_e32 v206, 16, v113
	v_and_b32_e32 v207, 0xffff0000, v113
	v_mul_f32_e32 v200, v214, v200
	v_mul_f32_e32 v201, v214, v201
	v_mul_f32_e32 v202, v214, v202
	v_mul_f32_e32 v203, v214, v203
	v_mul_f32_e32 v204, v215, v204
	v_mul_f32_e32 v205, v215, v205
	v_mul_f32_e32 v206, v215, v206
	v_mul_f32_e32 v207, v215, v207
	v_fmac_f32_e32 v32, v128, v200
	v_fmac_f32_e32 v33, v129, v201
	v_fmac_f32_e32 v34, v130, v202
	v_fmac_f32_e32 v35, v131, v203
	v_fmac_f32_e32 v32, v160, v204
	v_fmac_f32_e32 v33, v161, v205
	v_fmac_f32_e32 v34, v162, v206
	v_fmac_f32_e32 v35, v163, v207
	global_store_dwordx4 v192, v[32:35], s[18:19] offset:0 nt
	v_lshlrev_b32_e32 v200, 16, v82
	v_and_b32_e32 v201, 0xffff0000, v82
	v_lshlrev_b32_e32 v202, 16, v83
	v_and_b32_e32 v203, 0xffff0000, v83
	v_lshlrev_b32_e32 v204, 16, v114
	v_and_b32_e32 v205, 0xffff0000, v114
	v_lshlrev_b32_e32 v206, 16, v115
	v_and_b32_e32 v207, 0xffff0000, v115
	v_mul_f32_e32 v200, v214, v200
	v_mul_f32_e32 v201, v214, v201
	v_mul_f32_e32 v202, v214, v202
	v_mul_f32_e32 v203, v214, v203
	v_mul_f32_e32 v204, v215, v204
	v_mul_f32_e32 v205, v215, v205
	v_mul_f32_e32 v206, v215, v206
	v_mul_f32_e32 v207, v215, v207
	v_fmac_f32_e32 v36, v132, v200
	v_fmac_f32_e32 v37, v133, v201
	v_fmac_f32_e32 v38, v134, v202
	v_fmac_f32_e32 v39, v135, v203
	v_fmac_f32_e32 v36, v164, v204
	v_fmac_f32_e32 v37, v165, v205
	v_fmac_f32_e32 v38, v166, v206
	v_fmac_f32_e32 v39, v167, v207
	global_store_dwordx4 v192, v[36:39], s[18:19] offset:1024 nt
	v_lshlrev_b32_e32 v200, 16, v84
	v_and_b32_e32 v201, 0xffff0000, v84
	v_lshlrev_b32_e32 v202, 16, v85
	v_and_b32_e32 v203, 0xffff0000, v85
	v_lshlrev_b32_e32 v204, 16, v116
	v_and_b32_e32 v205, 0xffff0000, v116
	v_lshlrev_b32_e32 v206, 16, v117
	v_and_b32_e32 v207, 0xffff0000, v117
	v_mul_f32_e32 v200, v214, v200
	v_mul_f32_e32 v201, v214, v201
	v_mul_f32_e32 v202, v214, v202
	v_mul_f32_e32 v203, v214, v203
	v_mul_f32_e32 v204, v215, v204
	v_mul_f32_e32 v205, v215, v205
	v_mul_f32_e32 v206, v215, v206
	v_mul_f32_e32 v207, v215, v207
	v_fmac_f32_e32 v40, v136, v200
	v_fmac_f32_e32 v41, v137, v201
	v_fmac_f32_e32 v42, v138, v202
	v_fmac_f32_e32 v43, v139, v203
	v_fmac_f32_e32 v40, v168, v204
	v_fmac_f32_e32 v41, v169, v205
	v_fmac_f32_e32 v42, v170, v206
	v_fmac_f32_e32 v43, v171, v207
	global_store_dwordx4 v192, v[40:43], s[18:19] offset:2048 nt
	v_lshlrev_b32_e32 v200, 16, v86
	v_and_b32_e32 v201, 0xffff0000, v86
	v_lshlrev_b32_e32 v202, 16, v87
	v_and_b32_e32 v203, 0xffff0000, v87
	v_lshlrev_b32_e32 v204, 16, v118
	v_and_b32_e32 v205, 0xffff0000, v118
	v_lshlrev_b32_e32 v206, 16, v119
	v_and_b32_e32 v207, 0xffff0000, v119
	v_mul_f32_e32 v200, v214, v200
	v_mul_f32_e32 v201, v214, v201
	v_mul_f32_e32 v202, v214, v202
	v_mul_f32_e32 v203, v214, v203
	v_mul_f32_e32 v204, v215, v204
	v_mul_f32_e32 v205, v215, v205
	v_mul_f32_e32 v206, v215, v206
	v_mul_f32_e32 v207, v215, v207
	v_fmac_f32_e32 v44, v140, v200
	v_fmac_f32_e32 v45, v141, v201
	v_fmac_f32_e32 v46, v142, v202
	v_fmac_f32_e32 v47, v143, v203
	v_fmac_f32_e32 v44, v172, v204
	v_fmac_f32_e32 v45, v173, v205
	v_fmac_f32_e32 v46, v174, v206
	v_fmac_f32_e32 v47, v175, v207
	global_store_dwordx4 v192, v[44:47], s[18:19] offset:3072 nt
	v_lshlrev_b32_e32 v200, 16, v88
	v_and_b32_e32 v201, 0xffff0000, v88
	v_lshlrev_b32_e32 v202, 16, v89
	v_and_b32_e32 v203, 0xffff0000, v89
	v_lshlrev_b32_e32 v204, 16, v120
	v_and_b32_e32 v205, 0xffff0000, v120
	v_lshlrev_b32_e32 v206, 16, v121
	v_and_b32_e32 v207, 0xffff0000, v121
	v_mul_f32_e32 v200, v214, v200
	v_mul_f32_e32 v201, v214, v201
	v_mul_f32_e32 v202, v214, v202
	v_mul_f32_e32 v203, v214, v203
	v_mul_f32_e32 v204, v215, v204
	v_mul_f32_e32 v205, v215, v205
	v_mul_f32_e32 v206, v215, v206
	v_mul_f32_e32 v207, v215, v207
	v_fmac_f32_e32 v48, v144, v200
	v_fmac_f32_e32 v49, v145, v201
	v_fmac_f32_e32 v50, v146, v202
	v_fmac_f32_e32 v51, v147, v203
	v_fmac_f32_e32 v48, v176, v204
	v_fmac_f32_e32 v49, v177, v205
	v_fmac_f32_e32 v50, v178, v206
	v_fmac_f32_e32 v51, v179, v207
	global_store_dwordx4 v193, v[48:51], s[18:19] offset:0 nt
	v_lshlrev_b32_e32 v200, 16, v90
	v_and_b32_e32 v201, 0xffff0000, v90
	v_lshlrev_b32_e32 v202, 16, v91
	v_and_b32_e32 v203, 0xffff0000, v91
	v_lshlrev_b32_e32 v204, 16, v122
	v_and_b32_e32 v205, 0xffff0000, v122
	v_lshlrev_b32_e32 v206, 16, v123
	v_and_b32_e32 v207, 0xffff0000, v123
	v_mul_f32_e32 v200, v214, v200
	v_mul_f32_e32 v201, v214, v201
	v_mul_f32_e32 v202, v214, v202
	v_mul_f32_e32 v203, v214, v203
	v_mul_f32_e32 v204, v215, v204
	v_mul_f32_e32 v205, v215, v205
	v_mul_f32_e32 v206, v215, v206
	v_mul_f32_e32 v207, v215, v207
	v_fmac_f32_e32 v52, v148, v200
	v_fmac_f32_e32 v53, v149, v201
	v_fmac_f32_e32 v54, v150, v202
	v_fmac_f32_e32 v55, v151, v203
	v_fmac_f32_e32 v52, v180, v204
	v_fmac_f32_e32 v53, v181, v205
	v_fmac_f32_e32 v54, v182, v206
	v_fmac_f32_e32 v55, v183, v207
	global_store_dwordx4 v193, v[52:55], s[18:19] offset:1024 nt
	v_lshlrev_b32_e32 v200, 16, v92
	v_and_b32_e32 v201, 0xffff0000, v92
	v_lshlrev_b32_e32 v202, 16, v93
	v_and_b32_e32 v203, 0xffff0000, v93
	v_lshlrev_b32_e32 v204, 16, v124
	v_and_b32_e32 v205, 0xffff0000, v124
	v_lshlrev_b32_e32 v206, 16, v125
	v_and_b32_e32 v207, 0xffff0000, v125
	v_mul_f32_e32 v200, v214, v200
	v_mul_f32_e32 v201, v214, v201
	v_mul_f32_e32 v202, v214, v202
	v_mul_f32_e32 v203, v214, v203
	v_mul_f32_e32 v204, v215, v204
; __device__ __forceinline__ float bf_lo(unsigned w) { return __uint_as_float(w << 16); }
; __device__ __forceinline__ float bf_hi(unsigned w) { return __uint_as_float(w & 0xffff0000u); }
; __global__ void __launch_bounds__(NWAVES * 64, 2) mk_fwd(Args args) {
;     ...
;                 float sy = 0.f;
; #pragma unroll
;                 for (int j = 0; j < 8; ++j) { const float a = bf_lo(yw[q][j].x), b = bf_hi(yw[q][j].x), c2 = bf_lo(yw[q][j].y), d = bf_hi(yw[q][j].y); sy += (a * a + b * b) + (c2 * c2 + d * d); }
;                 const float rsy = __builtin_amdgcn_rsqf(wave_sum(sy) * (1.f / DM) + EPS);
; #pragma unroll
;                 for (int j = 0; j < 8; ++j) { const int col = 4 * F.lane + 256 * j;
;                     const f32x4 y4 = (f32x4){bf_lo(yw[q][j].x), bf_hi(yw[q][j].x), bf_lo(yw[q][j].y), bf_hi(yw[q][j].y)};
;                     *(f32x4*)(args.out + (size_t)row * DM + col) = v[q][j] + PA[j] * (y4 * rsy); }
	v_mul_f32_e32 v205, v215, v205
	v_mul_f32_e32 v206, v215, v206
	v_mul_f32_e32 v207, v215, v207
	v_fmac_f32_e32 v56, v152, v200
	v_fmac_f32_e32 v57, v153, v201
	v_fmac_f32_e32 v58, v154, v202
	v_fmac_f32_e32 v59, v155, v203
	v_fmac_f32_e32 v56, v184, v204
	v_fmac_f32_e32 v57, v185, v205
	v_fmac_f32_e32 v58, v186, v206
	v_fmac_f32_e32 v59, v187, v207
	global_store_dwordx4 v193, v[56:59], s[18:19] offset:2048 nt
	v_lshlrev_b32_e32 v200, 16, v94
	v_and_b32_e32 v201, 0xffff0000, v94
	v_lshlrev_b32_e32 v202, 16, v95
	v_and_b32_e32 v203, 0xffff0000, v95
	v_lshlrev_b32_e32 v204, 16, v126
	v_and_b32_e32 v205, 0xffff0000, v126
	v_lshlrev_b32_e32 v206, 16, v127
	v_and_b32_e32 v207, 0xffff0000, v127
	v_mul_f32_e32 v200, v214, v200
	v_mul_f32_e32 v201, v214, v201
	v_mul_f32_e32 v202, v214, v202
	v_mul_f32_e32 v203, v214, v203
	v_mul_f32_e32 v204, v215, v204
	v_mul_f32_e32 v205, v215, v205
	v_mul_f32_e32 v206, v215, v206
	v_mul_f32_e32 v207, v215, v207
	v_fmac_f32_e32 v60, v156, v200
	v_fmac_f32_e32 v61, v157, v201
	v_fmac_f32_e32 v62, v158, v202
	v_fmac_f32_e32 v63, v159, v203
	v_fmac_f32_e32 v60, v188, v204
	v_fmac_f32_e32 v61, v189, v205
	v_fmac_f32_e32 v62, v190, v206
	v_fmac_f32_e32 v63, v191, v207
	global_store_dwordx4 v193, v[60:63], s[18:19] offset:3072 nt
	s_add_u32 s18, s18, 0x2000
	s_addc_u32 s19, s19, 0
	global_load_dwordx4 v[32:35], v192, s[14:15] offset:0
	global_load_dwordx4 v[36:39], v192, s[14:15] offset:1024
	global_load_dwordx4 v[40:43], v192, s[14:15] offset:2048
	global_load_dwordx4 v[44:47], v192, s[14:15] offset:3072
	global_load_dwordx4 v[48:51], v193, s[14:15] offset:0
	global_load_dwordx4 v[52:55], v193, s[14:15] offset:1024
	global_load_dwordx4 v[56:59], v193, s[14:15] offset:2048
	global_load_dwordx4 v[60:63], v193, s[14:15] offset:3072
	global_load_dwordx2 v[80:81], v194, s[16:17] offset:0
	global_load_dwordx2 v[82:83], v194, s[16:17] offset:512
	global_load_dwordx2 v[84:85], v194, s[16:17] offset:1024
	global_load_dwordx2 v[86:87], v194, s[16:17] offset:1536
	global_load_dwordx2 v[88:89], v194, s[16:17] offset:2048
	global_load_dwordx2 v[90:91], v194, s[16:17] offset:2560
	global_load_dwordx2 v[92:93], v194, s[16:17] offset:3072
	global_load_dwordx2 v[94:95], v194, s[16:17] offset:3584
	global_load_dwordx2 v[112:113], v194, s[22:23] offset:0
	global_load_dwordx2 v[114:115], v194, s[22:23] offset:512
	global_load_dwordx2 v[116:117], v194, s[22:23] offset:1024
	global_load_dwordx2 v[118:119], v194, s[22:23] offset:1536
	global_load_dwordx2 v[120:121], v194, s[22:23] offset:2048
	global_load_dwordx2 v[122:123], v194, s[22:23] offset:2560
	global_load_dwordx2 v[124:125], v194, s[22:23] offset:3072
	global_load_dwordx2 v[126:127], v194, s[22:23] offset:3584
	s_add_u32 s14, s14, 0x2000
	s_addc_u32 s15, s15, 0
	s_add_u32 s16, s16, 0x1000
	s_addc_u32 s17, s17, 0
	s_add_u32 s22, s22, 0x1000
	s_addc_u32 s23, s23, 0
	s_waitcnt vmcnt(32)
	v_lshlrev_b32_e32 v200, 16, v64
	v_and_b32_e32 v201, 0xffff0000, v64
	v_lshlrev_b32_e32 v202, 16, v65
	v_and_b32_e32 v203, 0xffff0000, v65
	v_mul_f32_e32 v208, v200, v200
	v_mul_f32_e32 v209, v201, v201
	v_fmac_f32_e32 v208, v202, v202
	v_fmac_f32_e32 v209, v203, v203
	v_lshlrev_b32_e32 v204, 16, v96
	v_and_b32_e32 v205, 0xffff0000, v96
	v_lshlrev_b32_e32 v206, 16, v97
	v_and_b32_e32 v207, 0xffff0000, v97
	v_mul_f32_e32 v210, v204, v204
	v_mul_f32_e32 v211, v205, v205
	v_fmac_f32_e32 v210, v206, v206
	v_fmac_f32_e32 v211, v207, v207
	v_lshlrev_b32_e32 v200, 16, v66
	v_and_b32_e32 v201, 0xffff0000, v66
	v_lshlrev_b32_e32 v202, 16, v67
	v_and_b32_e32 v203, 0xffff0000, v67
	v_fmac_f32_e32 v208, v200, v200
	v_fmac_f32_e32 v209, v201, v201
	v_fmac_f32_e32 v208, v202, v202
	v_fmac_f32_e32 v209, v203, v203
	v_lshlrev_b32_e32 v204, 16, v98
	v_and_b32_e32 v205, 0xffff0000, v98
	v_lshlrev_b32_e32 v206, 16, v99
	v_and_b32_e32 v207, 0xffff0000, v99
	v_fmac_f32_e32 v210, v204, v204
	v_fmac_f32_e32 v211, v205, v205
	v_fmac_f32_e32 v210, v206, v206
	v_fmac_f32_e32 v211, v207, v207
	v_lshlrev_b32_e32 v200, 16, v68
	v_and_b32_e32 v201, 0xffff0000, v68
	v_lshlrev_b32_e32 v202, 16, v69
	v_and_b32_e32 v203, 0xffff0000, v69
	v_fmac_f32_e32 v208, v200, v200
	v_fmac_f32_e32 v209, v201, v201
	v_fmac_f32_e32 v208, v202, v202
	v_fmac_f32_e32 v209, v203, v203
	v_lshlrev_b32_e32 v204, 16, v100
	v_and_b32_e32 v205, 0xffff0000, v100
	v_lshlrev_b32_e32 v206, 16, v101
	v_and_b32_e32 v207, 0xffff0000, v101
	v_fmac_f32_e32 v210, v204, v204
	v_fmac_f32_e32 v211, v205, v205
	v_fmac_f32_e32 v210, v206, v206
	v_fmac_f32_e32 v211, v207, v207
	v_lshlrev_b32_e32 v200, 16, v70
	v_and_b32_e32 v201, 0xffff0000, v70
	v_lshlrev_b32_e32 v202, 16, v71
	v_and_b32_e32 v203, 0xffff0000, v71
	v_fmac_f32_e32 v208, v200, v200
	v_fmac_f32_e32 v209, v201, v201
	v_fmac_f32_e32 v208, v202, v202
	v_fmac_f32_e32 v209, v203, v203
	v_lshlrev_b32_e32 v204, 16, v102
	v_and_b32_e32 v205, 0xffff0000, v102
	v_lshlrev_b32_e32 v206, 16, v103
	v_and_b32_e32 v207, 0xffff0000, v103
	v_fmac_f32_e32 v210, v204, v204
	v_fmac_f32_e32 v211, v205, v205
	v_fmac_f32_e32 v210, v206, v206
	v_fmac_f32_e32 v211, v207, v207
	v_lshlrev_b32_e32 v200, 16, v72
	v_and_b32_e32 v201, 0xffff0000, v72
	v_lshlrev_b32_e32 v202, 16, v73
	v_and_b32_e32 v203, 0xffff0000, v73
	v_fmac_f32_e32 v208, v200, v200
	v_fmac_f32_e32 v209, v201, v201
	v_fmac_f32_e32 v208, v202, v202
	v_fmac_f32_e32 v209, v203, v203
	v_lshlrev_b32_e32 v204, 16, v104
	v_and_b32_e32 v205, 0xffff0000, v104
	v_lshlrev_b32_e32 v206, 16, v105
	v_and_b32_e32 v207, 0xffff0000, v105
	v_fmac_f32_e32 v210, v204, v204
	v_fmac_f32_e32 v211, v205, v205
	v_fmac_f32_e32 v210, v206, v206
	v_fmac_f32_e32 v211, v207, v207
	v_lshlrev_b32_e32 v200, 16, v74
; __device__ __forceinline__ float bf_lo(unsigned w) { return __uint_as_float(w << 16); }
; __device__ __forceinline__ float bf_hi(unsigned w) { return __uint_as_float(w & 0xffff0000u); }
; __global__ void __launch_bounds__(NWAVES * 64, 2) mk_fwd(Args args) {
;     ...
;                 float sy = 0.f;
; #pragma unroll
;                 for (int j = 0; j < 8; ++j) { const float a = bf_lo(yw[q][j].x), b = bf_hi(yw[q][j].x), c2 = bf_lo(yw[q][j].y), d = bf_hi(yw[q][j].y); sy += (a * a + b * b) + (c2 * c2 + d * d); }
;                 const float rsy = __builtin_amdgcn_rsqf(wave_sum(sy) * (1.f / DM) + EPS);
; #pragma unroll
;                 for (int j = 0; j < 8; ++j) { const int col = 4 * F.lane + 256 * j;
;                     const f32x4 y4 = (f32x4){bf_lo(yw[q][j].x), bf_hi(yw[q][j].x), bf_lo(yw[q][j].y), bf_hi(yw[q][j].y)};
;                     *(f32x4*)(args.out + (size_t)row * DM + col) = v[q][j] + PA[j] * (y4 * rsy); }
	v_and_b32_e32 v201, 0xffff0000, v74
	v_lshlrev_b32_e32 v202, 16, v75
	v_and_b32_e32 v203, 0xffff0000, v75
	v_fmac_f32_e32 v208, v200, v200
	v_fmac_f32_e32 v209, v201, v201
	v_fmac_f32_e32 v208, v202, v202
	v_fmac_f32_e32 v209, v203, v203
	v_lshlrev_b32_e32 v204, 16, v106
	v_and_b32_e32 v205, 0xffff0000, v106
	v_lshlrev_b32_e32 v206, 16, v107
	v_and_b32_e32 v207, 0xffff0000, v107
	v_fmac_f32_e32 v210, v204, v204
	v_fmac_f32_e32 v211, v205, v205
	v_fmac_f32_e32 v210, v206, v206
	v_fmac_f32_e32 v211, v207, v207
	v_lshlrev_b32_e32 v200, 16, v76
	v_and_b32_e32 v201, 0xffff0000, v76
	v_lshlrev_b32_e32 v202, 16, v77
	v_and_b32_e32 v203, 0xffff0000, v77
	v_fmac_f32_e32 v208, v200, v200
	v_fmac_f32_e32 v209, v201, v201
	v_fmac_f32_e32 v208, v202, v202
	v_fmac_f32_e32 v209, v203, v203
	v_lshlrev_b32_e32 v204, 16, v108
	v_and_b32_e32 v205, 0xffff0000, v108
	v_lshlrev_b32_e32 v206, 16, v109
	v_and_b32_e32 v207, 0xffff0000, v109
	v_fmac_f32_e32 v210, v204, v204
	v_fmac_f32_e32 v211, v205, v205
	v_fmac_f32_e32 v210, v206, v206
	v_fmac_f32_e32 v211, v207, v207
	v_lshlrev_b32_e32 v200, 16, v78
	v_and_b32_e32 v201, 0xffff0000, v78
	v_lshlrev_b32_e32 v202, 16, v79
	v_and_b32_e32 v203, 0xffff0000, v79
	v_fmac_f32_e32 v208, v200, v200
	v_fmac_f32_e32 v209, v201, v201
	v_fmac_f32_e32 v208, v202, v202
	v_fmac_f32_e32 v209, v203, v203
	v_lshlrev_b32_e32 v204, 16, v110
	v_and_b32_e32 v205, 0xffff0000, v110
	v_lshlrev_b32_e32 v206, 16, v111
	v_and_b32_e32 v207, 0xffff0000, v111
	v_fmac_f32_e32 v210, v204, v204
	v_fmac_f32_e32 v211, v205, v205
	v_fmac_f32_e32 v210, v206, v206
	v_fmac_f32_e32 v211, v207, v207
	v_add_f32_e32 v208, v208, v209
	v_add_f32_e32 v210, v210, v211
	s_nop 0
	v_add_f32_dpp v212, v208, v208 quad_perm:[1,0,3,2] row_mask:0xf bank_mask:0xf
	v_add_f32_dpp v213, v210, v210 quad_perm:[1,0,3,2] row_mask:0xf bank_mask:0xf
	s_nop 0
	v_add_f32_dpp v212, v212, v212 quad_perm:[2,3,0,1] row_mask:0xf bank_mask:0xf
	v_add_f32_dpp v213, v213, v213 quad_perm:[2,3,0,1] row_mask:0xf bank_mask:0xf
	s_nop 0
	v_add_f32_dpp v212, v212, v212 row_half_mirror row_mask:0xf bank_mask:0xf
	v_add_f32_dpp v213, v213, v213 row_half_mirror row_mask:0xf bank_mask:0xf
	s_nop 0
	v_add_f32_dpp v212, v212, v212 row_mirror row_mask:0xf bank_mask:0xf
	v_add_f32_dpp v213, v213, v213 row_mirror row_mask:0xf bank_mask:0xf
	s_nop 0
	v_readlane_b32 s4, v212, 0
	v_readlane_b32 s5, v212, 16
	v_readlane_b32 s6, v212, 32
	v_readlane_b32 s7, v212, 48
	v_readlane_b32 s24, v213, 0
	v_readlane_b32 s25, v213, 16
	v_readlane_b32 s26, v213, 32
	v_readlane_b32 s27, v213, 48
	s_nop 1
	v_mov_b32_e32 v214, s4
	v_mov_b32_e32 v215, s24
	v_add_f32_e32 v214, s5, v214
	v_add_f32_e32 v215, s25, v215
	v_add_f32_e32 v214, s6, v214
	v_add_f32_e32 v215, s26, v215
	v_add_f32_e32 v214, s7, v214
	v_add_f32_e32 v215, s27, v215
	v_fmamk_f32 v214, v214, 0x3a000000, v195
	v_fmamk_f32 v215, v215, 0x3a000000, v195
	v_rsq_f32_e32 v214, v214
	v_rsq_f32_e32 v215, v215
	s_nop 0
	v_lshlrev_b32_e32 v200, 16, v64
	v_and_b32_e32 v201, 0xffff0000, v64
	v_lshlrev_b32_e32 v202, 16, v65
	v_and_b32_e32 v203, 0xffff0000, v65
	v_lshlrev_b32_e32 v204, 16, v96
	v_and_b32_e32 v205, 0xffff0000, v96
	v_lshlrev_b32_e32 v206, 16, v97
	v_and_b32_e32 v207, 0xffff0000, v97
	v_mul_f32_e32 v200, v214, v200
	v_mul_f32_e32 v201, v214, v201
	v_mul_f32_e32 v202, v214, v202
	v_mul_f32_e32 v203, v214, v203
	v_mul_f32_e32 v204, v215, v204
	v_mul_f32_e32 v205, v215, v205
	v_mul_f32_e32 v206, v215, v206
	v_mul_f32_e32 v207, v215, v207
	v_fmac_f32_e32 v0, v128, v200
	v_fmac_f32_e32 v1, v129, v201
	v_fmac_f32_e32 v2, v130, v202
	v_fmac_f32_e32 v3, v131, v203
	v_fmac_f32_e32 v0, v160, v204
	v_fmac_f32_e32 v1, v161, v205
	v_fmac_f32_e32 v2, v162, v206
	v_fmac_f32_e32 v3, v163, v207
	global_store_dwordx4 v192, v[0:3], s[18:19] offset:0 nt
	v_lshlrev_b32_e32 v200, 16, v66
	v_and_b32_e32 v201, 0xffff0000, v66
	v_lshlrev_b32_e32 v202, 16, v67
	v_and_b32_e32 v203, 0xffff0000, v67
	v_lshlrev_b32_e32 v204, 16, v98
	v_and_b32_e32 v205, 0xffff0000, v98
	v_lshlrev_b32_e32 v206, 16, v99
	v_and_b32_e32 v207, 0xffff0000, v99
	v_mul_f32_e32 v200, v214, v200
	v_mul_f32_e32 v201, v214, v201
	v_mul_f32_e32 v202, v214, v202
	v_mul_f32_e32 v203, v214, v203
	v_mul_f32_e32 v204, v215, v204
	v_mul_f32_e32 v205, v215, v205
	v_mul_f32_e32 v206, v215, v206
	v_mul_f32_e32 v207, v215, v207
	v_fmac_f32_e32 v4, v132, v200
	v_fmac_f32_e32 v5, v133, v201
	v_fmac_f32_e32 v6, v134, v202
	v_fmac_f32_e32 v7, v135, v203
	v_fmac_f32_e32 v4, v164, v204
	v_fmac_f32_e32 v5, v165, v205
	v_fmac_f32_e32 v6, v166, v206
	v_fmac_f32_e32 v7, v167, v207
	global_store_dwordx4 v192, v[4:7], s[18:19] offset:1024 nt
	v_lshlrev_b32_e32 v200, 16, v68
	v_and_b32_e32 v201, 0xffff0000, v68
	v_lshlrev_b32_e32 v202, 16, v69
	v_and_b32_e32 v203, 0xffff0000, v69
	v_lshlrev_b32_e32 v204, 16, v100
	v_and_b32_e32 v205, 0xffff0000, v100
	v_lshlrev_b32_e32 v206, 16, v101
	v_and_b32_e32 v207, 0xffff0000, v101
	v_mul_f32_e32 v200, v214, v200
	v_mul_f32_e32 v201, v214, v201
	v_mul_f32_e32 v202, v214, v202
	v_mul_f32_e32 v203, v214, v203
	v_mul_f32_e32 v204, v215, v204
	v_mul_f32_e32 v205, v215, v205
	v_mul_f32_e32 v206, v215, v206
	v_mul_f32_e32 v207, v215, v207
	v_fmac_f32_e32 v8, v136, v200
	v_fmac_f32_e32 v9, v137, v201
	v_fmac_f32_e32 v10, v138, v202
	v_fmac_f32_e32 v11, v139, v203
	v_fmac_f32_e32 v8, v168, v204
	v_fmac_f32_e32 v9, v169, v205
	v_fmac_f32_e32 v10, v170, v206
	v_fmac_f32_e32 v11, v171, v207
	global_store_dwordx4 v192, v[8:11], s[18:19] offset:2048 nt
	v_lshlrev_b32_e32 v200, 16, v70
	v_and_b32_e32 v201, 0xffff0000, v70
	v_lshlrev_b32_e32 v202, 16, v71
	v_and_b32_e32 v203, 0xffff0000, v71
; __device__ __forceinline__ float bf_lo(unsigned w) { return __uint_as_float(w << 16); }
; __device__ __forceinline__ float bf_hi(unsigned w) { return __uint_as_float(w & 0xffff0000u); }
; __global__ void __launch_bounds__(NWAVES * 64, 2) mk_fwd(Args args) {
;     ...
;                 float sy = 0.f;
; #pragma unroll
;                 for (int j = 0; j < 8; ++j) { const float a = bf_lo(yw[q][j].x), b = bf_hi(yw[q][j].x), c2 = bf_lo(yw[q][j].y), d = bf_hi(yw[q][j].y); sy += (a * a + b * b) + (c2 * c2 + d * d); }
;                 const float rsy = __builtin_amdgcn_rsqf(wave_sum(sy) * (1.f / DM) + EPS);
; #pragma unroll
;                 for (int j = 0; j < 8; ++j) { const int col = 4 * F.lane + 256 * j;
;                     const f32x4 y4 = (f32x4){bf_lo(yw[q][j].x), bf_hi(yw[q][j].x), bf_lo(yw[q][j].y), bf_hi(yw[q][j].y)};
;                     *(f32x4*)(args.out + (size_t)row * DM + col) = v[q][j] + PA[j] * (y4 * rsy); }
	v_lshlrev_b32_e32 v204, 16, v102
	v_and_b32_e32 v205, 0xffff0000, v102
	v_lshlrev_b32_e32 v206, 16, v103
	v_and_b32_e32 v207, 0xffff0000, v103
	v_mul_f32_e32 v200, v214, v200
	v_mul_f32_e32 v201, v214, v201
	v_mul_f32_e32 v202, v214, v202
	v_mul_f32_e32 v203, v214, v203
	v_mul_f32_e32 v204, v215, v204
	v_mul_f32_e32 v205, v215, v205
	v_mul_f32_e32 v206, v215, v206
	v_mul_f32_e32 v207, v215, v207
	v_fmac_f32_e32 v12, v140, v200
	v_fmac_f32_e32 v13, v141, v201
	v_fmac_f32_e32 v14, v142, v202
	v_fmac_f32_e32 v15, v143, v203
	v_fmac_f32_e32 v12, v172, v204
	v_fmac_f32_e32 v13, v173, v205
	v_fmac_f32_e32 v14, v174, v206
	v_fmac_f32_e32 v15, v175, v207
	global_store_dwordx4 v192, v[12:15], s[18:19] offset:3072 nt
	v_lshlrev_b32_e32 v200, 16, v72
	v_and_b32_e32 v201, 0xffff0000, v72
	v_lshlrev_b32_e32 v202, 16, v73
	v_and_b32_e32 v203, 0xffff0000, v73
	v_lshlrev_b32_e32 v204, 16, v104
	v_and_b32_e32 v205, 0xffff0000, v104
	v_lshlrev_b32_e32 v206, 16, v105
	v_and_b32_e32 v207, 0xffff0000, v105
	v_mul_f32_e32 v200, v214, v200
	v_mul_f32_e32 v201, v214, v201
	v_mul_f32_e32 v202, v214, v202
	v_mul_f32_e32 v203, v214, v203
	v_mul_f32_e32 v204, v215, v204
	v_mul_f32_e32 v205, v215, v205
	v_mul_f32_e32 v206, v215, v206
	v_mul_f32_e32 v207, v215, v207
	v_fmac_f32_e32 v16, v144, v200
	v_fmac_f32_e32 v17, v145, v201
	v_fmac_f32_e32 v18, v146, v202
	v_fmac_f32_e32 v19, v147, v203
	v_fmac_f32_e32 v16, v176, v204
	v_fmac_f32_e32 v17, v177, v205
	v_fmac_f32_e32 v18, v178, v206
	v_fmac_f32_e32 v19, v179, v207
	global_store_dwordx4 v193, v[16:19], s[18:19] offset:0 nt
	v_lshlrev_b32_e32 v200, 16, v74
	v_and_b32_e32 v201, 0xffff0000, v74
	v_lshlrev_b32_e32 v202, 16, v75
	v_and_b32_e32 v203, 0xffff0000, v75
	v_lshlrev_b32_e32 v204, 16, v106
	v_and_b32_e32 v205, 0xffff0000, v106
	v_lshlrev_b32_e32 v206, 16, v107
	v_and_b32_e32 v207, 0xffff0000, v107
	v_mul_f32_e32 v200, v214, v200
	v_mul_f32_e32 v201, v214, v201
	v_mul_f32_e32 v202, v214, v202
	v_mul_f32_e32 v203, v214, v203
	v_mul_f32_e32 v204, v215, v204
	v_mul_f32_e32 v205, v215, v205
	v_mul_f32_e32 v206, v215, v206
	v_mul_f32_e32 v207, v215, v207
	v_fmac_f32_e32 v20, v148, v200
	v_fmac_f32_e32 v21, v149, v201
	v_fmac_f32_e32 v22, v150, v202
	v_fmac_f32_e32 v23, v151, v203
	v_fmac_f32_e32 v20, v180, v204
	v_fmac_f32_e32 v21, v181, v205
	v_fmac_f32_e32 v22, v182, v206
	v_fmac_f32_e32 v23, v183, v207
	global_store_dwordx4 v193, v[20:23], s[18:19] offset:1024 nt
	v_lshlrev_b32_e32 v200, 16, v76
	v_and_b32_e32 v201, 0xffff0000, v76
	v_lshlrev_b32_e32 v202, 16, v77
	v_and_b32_e32 v203, 0xffff0000, v77
	v_lshlrev_b32_e32 v204, 16, v108
	v_and_b32_e32 v205, 0xffff0000, v108
	v_lshlrev_b32_e32 v206, 16, v109
	v_and_b32_e32 v207, 0xffff0000, v109
	v_mul_f32_e32 v200, v214, v200
	v_mul_f32_e32 v201, v214, v201
	v_mul_f32_e32 v202, v214, v202
	v_mul_f32_e32 v203, v214, v203
	v_mul_f32_e32 v204, v215, v204
	v_mul_f32_e32 v205, v215, v205
	v_mul_f32_e32 v206, v215, v206
	v_mul_f32_e32 v207, v215, v207
	v_fmac_f32_e32 v24, v152, v200
	v_fmac_f32_e32 v25, v153, v201
	v_fmac_f32_e32 v26, v154, v202
	v_fmac_f32_e32 v27, v155, v203
	v_fmac_f32_e32 v24, v184, v204
	v_fmac_f32_e32 v25, v185, v205
	v_fmac_f32_e32 v26, v186, v206
	v_fmac_f32_e32 v27, v187, v207
	global_store_dwordx4 v193, v[24:27], s[18:19] offset:2048 nt
	v_lshlrev_b32_e32 v200, 16, v78
	v_and_b32_e32 v201, 0xffff0000, v78
	v_lshlrev_b32_e32 v202, 16, v79
	v_and_b32_e32 v203, 0xffff0000, v79
	v_lshlrev_b32_e32 v204, 16, v110
	v_and_b32_e32 v205, 0xffff0000, v110
	v_lshlrev_b32_e32 v206, 16, v111
	v_and_b32_e32 v207, 0xffff0000, v111
	v_mul_f32_e32 v200, v214, v200
	v_mul_f32_e32 v201, v214, v201
	v_mul_f32_e32 v202, v214, v202
	v_mul_f32_e32 v203, v214, v203
	v_mul_f32_e32 v204, v215, v204
	v_mul_f32_e32 v205, v215, v205
	v_mul_f32_e32 v206, v215, v206
	v_mul_f32_e32 v207, v215, v207
	v_fmac_f32_e32 v28, v156, v200
	v_fmac_f32_e32 v29, v157, v201
	v_fmac_f32_e32 v30, v158, v202
	v_fmac_f32_e32 v31, v159, v203
	v_fmac_f32_e32 v28, v188, v204
	v_fmac_f32_e32 v29, v189, v205
	v_fmac_f32_e32 v30, v190, v206
	v_fmac_f32_e32 v31, v191, v207
	global_store_dwordx4 v193, v[28:31], s[18:19] offset:3072 nt
	s_add_u32 s18, s18, 0x2000
	s_addc_u32 s19, s19, 0
	s_waitcnt vmcnt(8)
	v_lshlrev_b32_e32 v200, 16, v80
	v_and_b32_e32 v201, 0xffff0000, v80
	v_lshlrev_b32_e32 v202, 16, v81
	v_and_b32_e32 v203, 0xffff0000, v81
	v_mul_f32_e32 v208, v200, v200
	v_mul_f32_e32 v209, v201, v201
	v_fmac_f32_e32 v208, v202, v202
	v_fmac_f32_e32 v209, v203, v203
	v_lshlrev_b32_e32 v204, 16, v112
	v_and_b32_e32 v205, 0xffff0000, v112
	v_lshlrev_b32_e32 v206, 16, v113
	v_and_b32_e32 v207, 0xffff0000, v113
	v_mul_f32_e32 v210, v204, v204
	v_mul_f32_e32 v211, v205, v205
	v_fmac_f32_e32 v210, v206, v206
	v_fmac_f32_e32 v211, v207, v207
	v_lshlrev_b32_e32 v200, 16, v82
	v_and_b32_e32 v201, 0xffff0000, v82
	v_lshlrev_b32_e32 v202, 16, v83
	v_and_b32_e32 v203, 0xffff0000, v83
	v_fmac_f32_e32 v208, v200, v200
	v_fmac_f32_e32 v209, v201, v201
	v_fmac_f32_e32 v208, v202, v202
	v_fmac_f32_e32 v209, v203, v203
	v_lshlrev_b32_e32 v204, 16, v114
	v_and_b32_e32 v205, 0xffff0000, v114
	v_lshlrev_b32_e32 v206, 16, v115
	v_and_b32_e32 v207, 0xffff0000, v115
	v_fmac_f32_e32 v210, v204, v204
	v_fmac_f32_e32 v211, v205, v205
	v_fmac_f32_e32 v210, v206, v206
	v_fmac_f32_e32 v211, v207, v207
	v_lshlrev_b32_e32 v200, 16, v84
	v_and_b32_e32 v201, 0xffff0000, v84
	v_lshlrev_b32_e32 v202, 16, v85
	v_and_b32_e32 v203, 0xffff0000, v85
	v_fmac_f32_e32 v208, v200, v200
	v_fmac_f32_e32 v209, v201, v201
	v_fmac_f32_e32 v208, v202, v202
	v_fmac_f32_e32 v209, v203, v203
	v_lshlrev_b32_e32 v204, 16, v116
	v_and_b32_e32 v205, 0xffff0000, v116
; __device__ __forceinline__ float bf_lo(unsigned w) { return __uint_as_float(w << 16); }
; __device__ __forceinline__ float bf_hi(unsigned w) { return __uint_as_float(w & 0xffff0000u); }
; __global__ void __launch_bounds__(NWAVES * 64, 2) mk_fwd(Args args) {
;     ...
;                 for (int j = 0; j < 8; ++j) { const float a = bf_lo(yw[q][j].x), b = bf_hi(yw[q][j].x), c2 = bf_lo(yw[q][j].y), d = bf_hi(yw[q][j].y); sy += (a * a + b * b) + (c2 * c2 + d * d); }
;                 const float rsy = __builtin_amdgcn_rsqf(wave_sum(sy) * (1.f / DM) + EPS);
; #pragma unroll
;                 for (int j = 0; j < 8; ++j) { const int col = 4 * F.lane + 256 * j;
;                     const f32x4 y4 = (f32x4){bf_lo(yw[q][j].x), bf_hi(yw[q][j].x), bf_lo(yw[q][j].y), bf_hi(yw[q][j].y)};
;                     *(f32x4*)(args.out + (size_t)row * DM + col) = v[q][j] + PA[j] * (y4 * rsy); }
	v_lshlrev_b32_e32 v206, 16, v117
	v_and_b32_e32 v207, 0xffff0000, v117
	v_fmac_f32_e32 v210, v204, v204
	v_fmac_f32_e32 v211, v205, v205
	v_fmac_f32_e32 v210, v206, v206
	v_fmac_f32_e32 v211, v207, v207
	v_lshlrev_b32_e32 v200, 16, v86
	v_and_b32_e32 v201, 0xffff0000, v86
	v_lshlrev_b32_e32 v202, 16, v87
	v_and_b32_e32 v203, 0xffff0000, v87
	v_fmac_f32_e32 v208, v200, v200
	v_fmac_f32_e32 v209, v201, v201
	v_fmac_f32_e32 v208, v202, v202
	v_fmac_f32_e32 v209, v203, v203
	v_lshlrev_b32_e32 v204, 16, v118
	v_and_b32_e32 v205, 0xffff0000, v118
	v_lshlrev_b32_e32 v206, 16, v119
	v_and_b32_e32 v207, 0xffff0000, v119
	v_fmac_f32_e32 v210, v204, v204
	v_fmac_f32_e32 v211, v205, v205
	v_fmac_f32_e32 v210, v206, v206
	v_fmac_f32_e32 v211, v207, v207
	v_lshlrev_b32_e32 v200, 16, v88
	v_and_b32_e32 v201, 0xffff0000, v88
	v_lshlrev_b32_e32 v202, 16, v89
	v_and_b32_e32 v203, 0xffff0000, v89
	v_fmac_f32_e32 v208, v200, v200
	v_fmac_f32_e32 v209, v201, v201
	v_fmac_f32_e32 v208, v202, v202
	v_fmac_f32_e32 v209, v203, v203
	v_lshlrev_b32_e32 v204, 16, v120
	v_and_b32_e32 v205, 0xffff0000, v120
	v_lshlrev_b32_e32 v206, 16, v121
	v_and_b32_e32 v207, 0xffff0000, v121
	v_fmac_f32_e32 v210, v204, v204
	v_fmac_f32_e32 v211, v205, v205
	v_fmac_f32_e32 v210, v206, v206
	v_fmac_f32_e32 v211, v207, v207
	v_lshlrev_b32_e32 v200, 16, v90
	v_and_b32_e32 v201, 0xffff0000, v90
	v_lshlrev_b32_e32 v202, 16, v91
	v_and_b32_e32 v203, 0xffff0000, v91
	v_fmac_f32_e32 v208, v200, v200
	v_fmac_f32_e32 v209, v201, v201
	v_fmac_f32_e32 v208, v202, v202
	v_fmac_f32_e32 v209, v203, v203
	v_lshlrev_b32_e32 v204, 16, v122
	v_and_b32_e32 v205, 0xffff0000, v122
	v_lshlrev_b32_e32 v206, 16, v123
	v_and_b32_e32 v207, 0xffff0000, v123
	v_fmac_f32_e32 v210, v204, v204
	v_fmac_f32_e32 v211, v205, v205
	v_fmac_f32_e32 v210, v206, v206
	v_fmac_f32_e32 v211, v207, v207
	v_lshlrev_b32_e32 v200, 16, v92
	v_and_b32_e32 v201, 0xffff0000, v92
	v_lshlrev_b32_e32 v202, 16, v93
	v_and_b32_e32 v203, 0xffff0000, v93
	v_fmac_f32_e32 v208, v200, v200
	v_fmac_f32_e32 v209, v201, v201
	v_fmac_f32_e32 v208, v202, v202
	v_fmac_f32_e32 v209, v203, v203
	v_lshlrev_b32_e32 v204, 16, v124
	v_and_b32_e32 v205, 0xffff0000, v124
	v_lshlrev_b32_e32 v206, 16, v125
	v_and_b32_e32 v207, 0xffff0000, v125
	v_fmac_f32_e32 v210, v204, v204
	v_fmac_f32_e32 v211, v205, v205
	v_fmac_f32_e32 v210, v206, v206
	v_fmac_f32_e32 v211, v207, v207
	v_lshlrev_b32_e32 v200, 16, v94
	v_and_b32_e32 v201, 0xffff0000, v94
	v_lshlrev_b32_e32 v202, 16, v95
	v_and_b32_e32 v203, 0xffff0000, v95
	v_fmac_f32_e32 v208, v200, v200
	v_fmac_f32_e32 v209, v201, v201
	v_fmac_f32_e32 v208, v202, v202
	v_fmac_f32_e32 v209, v203, v203
	v_lshlrev_b32_e32 v204, 16, v126
	v_and_b32_e32 v205, 0xffff0000, v126
	v_lshlrev_b32_e32 v206, 16, v127
	v_and_b32_e32 v207, 0xffff0000, v127
	v_fmac_f32_e32 v210, v204, v204
	v_fmac_f32_e32 v211, v205, v205
	v_fmac_f32_e32 v210, v206, v206
	v_fmac_f32_e32 v211, v207, v207
	v_add_f32_e32 v208, v208, v209
	v_add_f32_e32 v210, v210, v211
	s_nop 0
	v_add_f32_dpp v212, v208, v208 quad_perm:[1,0,3,2] row_mask:0xf bank_mask:0xf
	v_add_f32_dpp v213, v210, v210 quad_perm:[1,0,3,2] row_mask:0xf bank_mask:0xf
	s_nop 0
	v_add_f32_dpp v212, v212, v212 quad_perm:[2,3,0,1] row_mask:0xf bank_mask:0xf
	v_add_f32_dpp v213, v213, v213 quad_perm:[2,3,0,1] row_mask:0xf bank_mask:0xf
	s_nop 0
	v_add_f32_dpp v212, v212, v212 row_half_mirror row_mask:0xf bank_mask:0xf
	v_add_f32_dpp v213, v213, v213 row_half_mirror row_mask:0xf bank_mask:0xf
	s_nop 0
	v_add_f32_dpp v212, v212, v212 row_mirror row_mask:0xf bank_mask:0xf
	v_add_f32_dpp v213, v213, v213 row_mirror row_mask:0xf bank_mask:0xf
	s_nop 0
	v_readlane_b32 s4, v212, 0
	v_readlane_b32 s5, v212, 16
	v_readlane_b32 s6, v212, 32
	v_readlane_b32 s7, v212, 48
	v_readlane_b32 s24, v213, 0
	v_readlane_b32 s25, v213, 16
	v_readlane_b32 s26, v213, 32
	v_readlane_b32 s27, v213, 48
	s_nop 1
	v_mov_b32_e32 v214, s4
	v_mov_b32_e32 v215, s24
	v_add_f32_e32 v214, s5, v214
	v_add_f32_e32 v215, s25, v215
	v_add_f32_e32 v214, s6, v214
	v_add_f32_e32 v215, s26, v215
	v_add_f32_e32 v214, s7, v214
	v_add_f32_e32 v215, s27, v215
	v_fmamk_f32 v214, v214, 0x3a000000, v195
	v_fmamk_f32 v215, v215, 0x3a000000, v195
	v_rsq_f32_e32 v214, v214
	v_rsq_f32_e32 v215, v215
	s_nop 0
	v_lshlrev_b32_e32 v200, 16, v80
	v_and_b32_e32 v201, 0xffff0000, v80
	v_lshlrev_b32_e32 v202, 16, v81
	v_and_b32_e32 v203, 0xffff0000, v81
	v_lshlrev_b32_e32 v204, 16, v112
	v_and_b32_e32 v205, 0xffff0000, v112
	v_lshlrev_b32_e32 v206, 16, v113
	v_and_b32_e32 v207, 0xffff0000, v113
	v_mul_f32_e32 v200, v214, v200
	v_mul_f32_e32 v201, v214, v201
	v_mul_f32_e32 v202, v214, v202
	v_mul_f32_e32 v203, v214, v203
	v_mul_f32_e32 v204, v215, v204
	v_mul_f32_e32 v205, v215, v205
	v_mul_f32_e32 v206, v215, v206
	v_mul_f32_e32 v207, v215, v207
	v_fmac_f32_e32 v32, v128, v200
	v_fmac_f32_e32 v33, v129, v201
	v_fmac_f32_e32 v34, v130, v202
	v_fmac_f32_e32 v35, v131, v203
	v_fmac_f32_e32 v32, v160, v204
	v_fmac_f32_e32 v33, v161, v205
	v_fmac_f32_e32 v34, v162, v206
	v_fmac_f32_e32 v35, v163, v207
	global_store_dwordx4 v192, v[32:35], s[18:19] offset:0 nt
	v_lshlrev_b32_e32 v200, 16, v82
	v_and_b32_e32 v201, 0xffff0000, v82
	v_lshlrev_b32_e32 v202, 16, v83
	v_and_b32_e32 v203, 0xffff0000, v83
	v_lshlrev_b32_e32 v204, 16, v114
	v_and_b32_e32 v205, 0xffff0000, v114
	v_lshlrev_b32_e32 v206, 16, v115
	v_and_b32_e32 v207, 0xffff0000, v115
	v_mul_f32_e32 v200, v214, v200
	v_mul_f32_e32 v201, v214, v201
	v_mul_f32_e32 v202, v214, v202
	v_mul_f32_e32 v203, v214, v203
	v_mul_f32_e32 v204, v215, v204
	v_mul_f32_e32 v205, v215, v205
; __device__ __forceinline__ float bf_lo(unsigned w) { return __uint_as_float(w << 16); }
; __device__ __forceinline__ float bf_hi(unsigned w) { return __uint_as_float(w & 0xffff0000u); }
; __global__ void __launch_bounds__(NWAVES * 64, 2) mk_fwd(Args args) {
;     ...
;                 for (int j = 0; j < 8; ++j) { const int col = 4 * F.lane + 256 * j;
;                     const f32x4 y4 = (f32x4){bf_lo(yw[q][j].x), bf_hi(yw[q][j].x), bf_lo(yw[q][j].y), bf_hi(yw[q][j].y)};
;                     *(f32x4*)(args.out + (size_t)row * DM + col) = v[q][j] + PA[j] * (y4 * rsy); }
	v_mul_f32_e32 v206, v215, v206
	v_mul_f32_e32 v207, v215, v207
	v_fmac_f32_e32 v36, v132, v200
	v_fmac_f32_e32 v37, v133, v201
	v_fmac_f32_e32 v38, v134, v202
	v_fmac_f32_e32 v39, v135, v203
	v_fmac_f32_e32 v36, v164, v204
	v_fmac_f32_e32 v37, v165, v205
	v_fmac_f32_e32 v38, v166, v206
	v_fmac_f32_e32 v39, v167, v207
	global_store_dwordx4 v192, v[36:39], s[18:19] offset:1024 nt
	v_lshlrev_b32_e32 v200, 16, v84
	v_and_b32_e32 v201, 0xffff0000, v84
	v_lshlrev_b32_e32 v202, 16, v85
	v_and_b32_e32 v203, 0xffff0000, v85
	v_lshlrev_b32_e32 v204, 16, v116
	v_and_b32_e32 v205, 0xffff0000, v116
	v_lshlrev_b32_e32 v206, 16, v117
	v_and_b32_e32 v207, 0xffff0000, v117
	v_mul_f32_e32 v200, v214, v200
	v_mul_f32_e32 v201, v214, v201
	v_mul_f32_e32 v202, v214, v202
	v_mul_f32_e32 v203, v214, v203
	v_mul_f32_e32 v204, v215, v204
	v_mul_f32_e32 v205, v215, v205
	v_mul_f32_e32 v206, v215, v206
	v_mul_f32_e32 v207, v215, v207
	v_fmac_f32_e32 v40, v136, v200
	v_fmac_f32_e32 v41, v137, v201
	v_fmac_f32_e32 v42, v138, v202
	v_fmac_f32_e32 v43, v139, v203
	v_fmac_f32_e32 v40, v168, v204
	v_fmac_f32_e32 v41, v169, v205
	v_fmac_f32_e32 v42, v170, v206
	v_fmac_f32_e32 v43, v171, v207
	global_store_dwordx4 v192, v[40:43], s[18:19] offset:2048 nt
	v_lshlrev_b32_e32 v200, 16, v86
	v_and_b32_e32 v201, 0xffff0000, v86
	v_lshlrev_b32_e32 v202, 16, v87
	v_and_b32_e32 v203, 0xffff0000, v87
	v_lshlrev_b32_e32 v204, 16, v118
	v_and_b32_e32 v205, 0xffff0000, v118
	v_lshlrev_b32_e32 v206, 16, v119
	v_and_b32_e32 v207, 0xffff0000, v119
	v_mul_f32_e32 v200, v214, v200
	v_mul_f32_e32 v201, v214, v201
	v_mul_f32_e32 v202, v214, v202
	v_mul_f32_e32 v203, v214, v203
	v_mul_f32_e32 v204, v215, v204
	v_mul_f32_e32 v205, v215, v205
	v_mul_f32_e32 v206, v215, v206
	v_mul_f32_e32 v207, v215, v207
	v_fmac_f32_e32 v44, v140, v200
	v_fmac_f32_e32 v45, v141, v201
	v_fmac_f32_e32 v46, v142, v202
	v_fmac_f32_e32 v47, v143, v203
	v_fmac_f32_e32 v44, v172, v204
	v_fmac_f32_e32 v45, v173, v205
	v_fmac_f32_e32 v46, v174, v206
	v_fmac_f32_e32 v47, v175, v207
	global_store_dwordx4 v192, v[44:47], s[18:19] offset:3072 nt
	v_lshlrev_b32_e32 v200, 16, v88
	v_and_b32_e32 v201, 0xffff0000, v88
	v_lshlrev_b32_e32 v202, 16, v89
	v_and_b32_e32 v203, 0xffff0000, v89
	v_lshlrev_b32_e32 v204, 16, v120
	v_and_b32_e32 v205, 0xffff0000, v120
	v_lshlrev_b32_e32 v206, 16, v121
	v_and_b32_e32 v207, 0xffff0000, v121
	v_mul_f32_e32 v200, v214, v200
	v_mul_f32_e32 v201, v214, v201
	v_mul_f32_e32 v202, v214, v202
	v_mul_f32_e32 v203, v214, v203
	v_mul_f32_e32 v204, v215, v204
	v_mul_f32_e32 v205, v215, v205
	v_mul_f32_e32 v206, v215, v206
	v_mul_f32_e32 v207, v215, v207
	v_fmac_f32_e32 v48, v144, v200
	v_fmac_f32_e32 v49, v145, v201
	v_fmac_f32_e32 v50, v146, v202
	v_fmac_f32_e32 v51, v147, v203
	v_fmac_f32_e32 v48, v176, v204
	v_fmac_f32_e32 v49, v177, v205
	v_fmac_f32_e32 v50, v178, v206
	v_fmac_f32_e32 v51, v179, v207
	global_store_dwordx4 v193, v[48:51], s[18:19] offset:0 nt
	v_lshlrev_b32_e32 v200, 16, v90
	v_and_b32_e32 v201, 0xffff0000, v90
	v_lshlrev_b32_e32 v202, 16, v91
	v_and_b32_e32 v203, 0xffff0000, v91
	v_lshlrev_b32_e32 v204, 16, v122
	v_and_b32_e32 v205, 0xffff0000, v122
	v_lshlrev_b32_e32 v206, 16, v123
	v_and_b32_e32 v207, 0xffff0000, v123
	v_mul_f32_e32 v200, v214, v200
	v_mul_f32_e32 v201, v214, v201
	v_mul_f32_e32 v202, v214, v202
	v_mul_f32_e32 v203, v214, v203
	v_mul_f32_e32 v204, v215, v204
	v_mul_f32_e32 v205, v215, v205
	v_mul_f32_e32 v206, v215, v206
	v_mul_f32_e32 v207, v215, v207
	v_fmac_f32_e32 v52, v148, v200
	v_fmac_f32_e32 v53, v149, v201
	v_fmac_f32_e32 v54, v150, v202
	v_fmac_f32_e32 v55, v151, v203
	v_fmac_f32_e32 v52, v180, v204
	v_fmac_f32_e32 v53, v181, v205
	v_fmac_f32_e32 v54, v182, v206
	v_fmac_f32_e32 v55, v183, v207
	global_store_dwordx4 v193, v[52:55], s[18:19] offset:1024 nt
	v_lshlrev_b32_e32 v200, 16, v92
	v_and_b32_e32 v201, 0xffff0000, v92
	v_lshlrev_b32_e32 v202, 16, v93
	v_and_b32_e32 v203, 0xffff0000, v93
	v_lshlrev_b32_e32 v204, 16, v124
	v_and_b32_e32 v205, 0xffff0000, v124
	v_lshlrev_b32_e32 v206, 16, v125
	v_and_b32_e32 v207, 0xffff0000, v125
	v_mul_f32_e32 v200, v214, v200
	v_mul_f32_e32 v201, v214, v201
	v_mul_f32_e32 v202, v214, v202
	v_mul_f32_e32 v203, v214, v203
	v_mul_f32_e32 v204, v215, v204
	v_mul_f32_e32 v205, v215, v205
	v_mul_f32_e32 v206, v215, v206
	v_mul_f32_e32 v207, v215, v207
	v_fmac_f32_e32 v56, v152, v200
	v_fmac_f32_e32 v57, v153, v201
	v_fmac_f32_e32 v58, v154, v202
	v_fmac_f32_e32 v59, v155, v203
	v_fmac_f32_e32 v56, v184, v204
	v_fmac_f32_e32 v57, v185, v205
	v_fmac_f32_e32 v58, v186, v206
	v_fmac_f32_e32 v59, v187, v207
	global_store_dwordx4 v193, v[56:59], s[18:19] offset:2048 nt
	v_lshlrev_b32_e32 v200, 16, v94
	v_and_b32_e32 v201, 0xffff0000, v94
	v_lshlrev_b32_e32 v202, 16, v95
	v_and_b32_e32 v203, 0xffff0000, v95
	v_lshlrev_b32_e32 v204, 16, v126
	v_and_b32_e32 v205, 0xffff0000, v126
	v_lshlrev_b32_e32 v206, 16, v127
	v_and_b32_e32 v207, 0xffff0000, v127
	v_mul_f32_e32 v200, v214, v200
	v_mul_f32_e32 v201, v214, v201
	v_mul_f32_e32 v202, v214, v202
	v_mul_f32_e32 v203, v214, v203
	v_mul_f32_e32 v204, v215, v204
	v_mul_f32_e32 v205, v215, v205
	v_mul_f32_e32 v206, v215, v206
	v_mul_f32_e32 v207, v215, v207
	v_fmac_f32_e32 v60, v156, v200
	v_fmac_f32_e32 v61, v157, v201
	v_fmac_f32_e32 v62, v158, v202
	v_fmac_f32_e32 v63, v159, v203
	v_fmac_f32_e32 v60, v188, v204
	v_fmac_f32_e32 v61, v189, v205
	v_fmac_f32_e32 v62, v190, v206
	v_fmac_f32_e32 v63, v191, v207
	global_store_dwordx4 v193, v[60:63], s[18:19] offset:3072 nt
	s_add_u32 s18, s18, 0x2000
	s_addc_u32 s19, s19, 0
	s_branch .LBB0_1296
